# setprio moved outside the MFMA segments (raise before the pre-MMA barrier, lower after the post-MMA barrier) on top of previous
# speedup vs baseline: 1.0171x; 1.0029x over previous
; #define PG8_WAIT_V(n) asm volatile("s_waitcnt vmcnt(" #n ")" ::: "memory")
; template <class Epi, bool ALIGN_EPI, bool SP2, class Hook>
; __device__ __forceinline__ void gemm_phase(LAS unsigned char* lds, const Gemm g, const StaticOrder& S, const Epi& E, Acc& acc, const bool fresh, const Hook& H, const int wave_id) {
;     ...
;         if constexpr (SP2 && Epi::NSTORE > 0) {
;             const Src a1 = cA + kstep, a2 = cA + 2 * kstep, b2 = cB + 2 * kstep, a3 = a2 + kstep, b3 = b2 + kstep;
;             if constexpr (Epi::NSTORE == 16) PG8_TRIP_SP2(PG8_WAIT_V(24)); else PG8_TRIP_SP2(PG8_WAIT_V(16));
;             t0 = 2;
.LBB0_382:
	ds_read_b128 v[2:5], v150
	ds_read_b128 v[6:9], v150 offset:1024
	ds_read_b128 v[10:13], v150 offset:2048
	ds_read_b128 v[14:17], v150 offset:3072
	ds_read_b128 v[18:21], v151
	ds_read_b128 v[22:25], v151 offset:1024
	ds_read_b128 v[26:29], v151 offset:2048
	ds_read_b128 v[30:33], v151 offset:3072
	s_or_b32 s9, s68, 0x100
	s_or_b32 s8, s68, 0x180
	s_or_b32 s10, s69, 0x100
	s_or_b32 s11, s68, 0x40080
	s_mov_b32 m0, s45
	ds_read_b128 v[34:37], v149
	ds_read_b128 v[38:41], v149 offset:1024
	ds_read_b128 v[42:45], v149 offset:2048
	ds_read_b128 v[46:49], v149 offset:3072
	ds_read_b128 v[50:53], v149 offset:4096
	ds_read_b128 v[54:57], v149 offset:5120
	ds_read_b128 v[58:61], v149 offset:6144
	ds_read_b128 v[62:65], v149 offset:7168
	buffer_load_dwordx4 v144, s[0:3], s11 offen lds
	s_mov_b32 m0, s46
	s_nop 0
	buffer_load_dwordx4 v146, s[0:3], s11 offen lds
	s_waitcnt vmcnt(24)
	s_waitcnt lgkmcnt(0)
	s_setprio 1
	s_barrier
	v_mfma_f32_16x16x32_bf16 v[86:89], v[10:13], v[50:53], 0
	v_mfma_f32_16x16x32_bf16 v[92:95], v[14:17], v[54:57], v[86:89]
	v_mfma_f32_16x16x32_bf16 v[86:89], v[2:5], v[58:61], 0
	v_mfma_f32_16x16x32_bf16 v[66:69], v[2:5], v[34:37], 0
	v_mfma_f32_16x16x32_bf16 v[70:73], v[10:13], v[34:37], 0
	v_mfma_f32_16x16x32_bf16 v[74:77], v[2:5], v[42:45], 0
	v_mfma_f32_16x16x32_bf16 v[78:81], v[10:13], v[42:45], 0
	v_mfma_f32_16x16x32_bf16 v[82:85], v[2:5], v[50:53], 0
	v_mfma_f32_16x16x32_bf16 v[96:99], v[6:9], v[62:65], v[86:89]
	v_mfma_f32_16x16x32_bf16 v[86:89], v[10:13], v[58:61], 0
	v_mfma_f32_16x16x32_bf16 v[66:69], v[6:9], v[38:41], v[66:69]
	v_mfma_f32_16x16x32_bf16 v[70:73], v[14:17], v[38:41], v[70:73]
	v_mfma_f32_16x16x32_bf16 v[74:77], v[6:9], v[46:49], v[74:77]
	v_mfma_f32_16x16x32_bf16 v[78:81], v[14:17], v[46:49], v[78:81]
	v_mfma_f32_16x16x32_bf16 v[82:85], v[6:9], v[54:57], v[82:85]
	v_mfma_f32_16x16x32_bf16 v[104:107], v[14:17], v[62:65], v[86:89]
	v_mfma_f32_16x16x32_bf16 v[86:89], v[18:21], v[34:37], 0
	v_mfma_f32_16x16x32_bf16 v[34:37], v[26:29], v[34:37], 0
	v_mfma_f32_16x16x32_bf16 v[116:119], v[30:33], v[38:41], v[34:37]
	v_mfma_f32_16x16x32_bf16 v[34:37], v[18:21], v[42:45], 0
	v_mfma_f32_16x16x32_bf16 v[132:135], v[22:25], v[46:49], v[34:37]
	v_mfma_f32_16x16x32_bf16 v[34:37], v[26:29], v[42:45], 0
	v_mfma_f32_16x16x32_bf16 v[108:111], v[22:25], v[38:41], v[86:89]
	v_mfma_f32_16x16x32_bf16 v[40:43], v[30:33], v[46:49], v[34:37]
	v_mfma_f32_16x16x32_bf16 v[34:37], v[18:21], v[50:53], 0
	v_mfma_f32_16x16x32_bf16 v[44:47], v[22:25], v[54:57], v[34:37]
	v_mfma_f32_16x16x32_bf16 v[34:37], v[26:29], v[50:53], 0
	v_mfma_f32_16x16x32_bf16 v[48:51], v[30:33], v[54:57], v[34:37]
	v_mfma_f32_16x16x32_bf16 v[34:37], v[18:21], v[58:61], 0
	v_mfma_f32_16x16x32_bf16 v[52:55], v[22:25], v[62:65], v[34:37]
	v_mfma_f32_16x16x32_bf16 v[34:37], v[26:29], v[58:61], 0
	v_mfma_f32_16x16x32_bf16 v[60:63], v[30:33], v[62:65], v[34:37]
	s_barrier
	s_setprio 0
	s_mov_b32 m0, s92
	s_nop 3
	ds_read_b128 v[34:37], v149 offset:16384
	ds_read_b128 v[56:59], v149 offset:17408
	ds_read_b128 v[86:89], v149 offset:18432
	ds_read_b128 v[100:103], v149 offset:19456
	ds_read_b128 v[112:115], v149 offset:20480
	ds_read_b128 v[120:123], v149 offset:21504
	ds_read_b128 v[124:127], v149 offset:22528
	ds_read_b128 v[128:131], v149 offset:23552
	buffer_load_dwordx4 v145, s[4:7], s10 offen lds
	s_mov_b32 m0, s93
	s_nop 0
	buffer_load_dwordx4 v147, s[4:7], s10 offen lds
	s_or_b32 s10, s69, 0x40100
	s_mov_b32 m0, s94
	s_nop 0
	buffer_load_dwordx4 v145, s[4:7], s10 offen lds
	s_mov_b32 m0, s95
	s_nop 0
	buffer_load_dwordx4 v147, s[4:7], s10 offen lds
	s_mov_b32 m0, s44
	s_nop 0
	buffer_load_dwordx4 v144, s[0:3], s9 offen lds
	s_mov_b32 m0, s36
	s_nop 0
	buffer_load_dwordx4 v146, s[0:3], s9 offen lds
	s_waitcnt vmcnt(24)
	s_waitcnt lgkmcnt(0)
	s_setprio 1
	s_barrier
	v_mfma_f32_16x16x32_bf16 v[136:139], v[2:5], v[34:37], 0
	v_mfma_f32_16x16x32_bf16 v[154:157], v[2:5], v[86:89], 0
	v_mfma_f32_16x16x32_bf16 v[162:165], v[2:5], v[112:115], 0
	v_mfma_f32_16x16x32_bf16 v[2:5], v[2:5], v[124:127], 0
	v_mfma_f32_16x16x32_bf16 v[136:139], v[6:9], v[56:59], v[136:139]
	v_mfma_f32_16x16x32_bf16 v[140:143], v[10:13], v[34:37], 0
	v_mfma_f32_16x16x32_bf16 v[154:157], v[6:9], v[100:103], v[154:157]
	v_mfma_f32_16x16x32_bf16 v[158:161], v[10:13], v[86:89], 0
	v_mfma_f32_16x16x32_bf16 v[162:165], v[6:9], v[120:123], v[162:165]
	v_mfma_f32_16x16x32_bf16 v[166:169], v[10:13], v[112:115], 0
	v_mfma_f32_16x16x32_bf16 v[2:5], v[6:9], v[128:131], v[2:5]
	v_mfma_f32_16x16x32_bf16 v[6:9], v[10:13], v[124:127], 0
	v_mfma_f32_16x16x32_bf16 v[140:143], v[14:17], v[56:59], v[140:143]
	v_mfma_f32_16x16x32_bf16 v[158:161], v[14:17], v[100:103], v[158:161]
	v_mfma_f32_16x16x32_bf16 v[166:169], v[14:17], v[120:123], v[166:169]
	v_mfma_f32_16x16x32_bf16 v[170:173], v[14:17], v[128:131], v[6:9]
	v_mfma_f32_16x16x32_bf16 v[6:9], v[18:21], v[34:37], 0
	v_mfma_f32_16x16x32_bf16 v[174:177], v[22:25], v[56:59], v[6:9]
	v_mfma_f32_16x16x32_bf16 v[6:9], v[26:29], v[34:37], 0
	v_mfma_f32_16x16x32_bf16 v[178:181], v[30:33], v[56:59], v[6:9]
	v_mfma_f32_16x16x32_bf16 v[6:9], v[18:21], v[86:89], 0
	v_mfma_f32_16x16x32_bf16 v[182:185], v[22:25], v[100:103], v[6:9]
	v_mfma_f32_16x16x32_bf16 v[6:9], v[26:29], v[86:89], 0
	v_mfma_f32_16x16x32_bf16 v[186:189], v[30:33], v[100:103], v[6:9]
	v_mfma_f32_16x16x32_bf16 v[6:9], v[18:21], v[112:115], 0
	v_mfma_f32_16x16x32_bf16 v[190:193], v[22:25], v[120:123], v[6:9]
	v_mfma_f32_16x16x32_bf16 v[6:9], v[26:29], v[112:115], 0
	v_mfma_f32_16x16x32_bf16 v[212:215], v[30:33], v[120:123], v[6:9]
	v_mfma_f32_16x16x32_bf16 v[6:9], v[18:21], v[124:127], 0
	v_mfma_f32_16x16x32_bf16 v[20:23], v[22:25], v[128:131], v[6:9]
	v_mfma_f32_16x16x32_bf16 v[6:9], v[26:29], v[124:127], 0
	v_mfma_f32_16x16x32_bf16 v[216:219], v[30:33], v[128:131], v[6:9]
	s_barrier
; #define PG8_WAIT_V(n) asm volatile("s_waitcnt vmcnt(" #n ")" ::: "memory")
; template <class Epi, bool ALIGN_EPI, bool SP2, class Hook>
; __device__ __forceinline__ void gemm_phase(LAS unsigned char* lds, const Gemm g, const StaticOrder& S, const Epi& E, Acc& acc, const bool fresh, const Hook& H, const int wave_id) {
;     ...
;         if constexpr (SP2 && Epi::NSTORE > 0) {
;             const Src a1 = cA + kstep, a2 = cA + 2 * kstep, b2 = cB + 2 * kstep, a3 = a2 + kstep, b3 = b2 + kstep;
;             if constexpr (Epi::NSTORE == 16) PG8_TRIP_SP2(PG8_WAIT_V(24)); else PG8_TRIP_SP2(PG8_WAIT_V(16));
;             t0 = 2;
	s_setprio 0
	s_nop 4
	ds_read_b128 v[6:9], v152
	ds_read_b128 v[24:27], v152 offset:1024
	ds_read_b128 v[228:231], v152 offset:2048
	ds_read_b128 v[232:235], v152 offset:3072
	ds_read_b128 v[236:239], v153
	ds_read_b128 v[240:243], v153 offset:1024
	ds_read_b128 v[244:247], v153 offset:2048
	ds_read_b128 v[150:153], v153 offset:3072
	s_or_b32 s9, s68, 0x40100
	s_mov_b32 m0, s37
	ds_read_b128 v[10:13], v149 offset:32768
	ds_read_b128 v[14:17], v149 offset:33792
	ds_read_b128 v[32:35], v149 offset:34816
	ds_read_b128 v[194:197], v149 offset:35840
	ds_read_b128 v[208:211], v149 offset:36864
	ds_read_b128 v[200:203], v149 offset:37888
	ds_read_b128 v[204:207], v149 offset:38912
	ds_read_b128 v[220:223], v149 offset:39936
	buffer_load_dwordx4 v144, s[0:3], s9 offen lds
	s_mov_b32 m0, s38
	s_nop 0
	buffer_load_dwordx4 v146, s[0:3], s9 offen lds
	s_waitcnt vmcnt(8)
	s_waitcnt lgkmcnt(0)
	s_setprio 1
	s_barrier
	v_mfma_f32_16x16x32_bf16 v[28:31], v[6:9], v[10:13], v[66:69]
	v_mfma_f32_16x16x32_bf16 v[120:123], v[24:27], v[14:17], v[28:31]
	v_mfma_f32_16x16x32_bf16 v[28:31], v[228:231], v[10:13], v[70:73]
	v_mfma_f32_16x16x32_bf16 v[112:115], v[232:235], v[14:17], v[28:31]
	v_mfma_f32_16x16x32_bf16 v[28:31], v[6:9], v[32:35], v[74:77]
	v_mfma_f32_16x16x32_bf16 v[100:103], v[24:27], v[194:197], v[28:31]
	v_mfma_f32_16x16x32_bf16 v[28:31], v[228:231], v[32:35], v[78:81]
	v_mfma_f32_16x16x32_bf16 v[88:91], v[232:235], v[194:197], v[28:31]
	v_mfma_f32_16x16x32_bf16 v[28:31], v[6:9], v[208:211], v[82:85]
	v_mfma_f32_16x16x32_bf16 v[68:71], v[24:27], v[200:203], v[28:31]
	v_mfma_f32_16x16x32_bf16 v[28:31], v[228:231], v[208:211], v[92:95]
	v_mfma_f32_16x16x32_bf16 v[56:59], v[232:235], v[200:203], v[28:31]
	v_mfma_f32_16x16x32_bf16 v[28:31], v[6:9], v[204:207], v[96:99]
	v_mfma_f32_16x16x32_bf16 v[36:39], v[24:27], v[220:223], v[28:31]
	v_mfma_f32_16x16x32_bf16 v[28:31], v[228:231], v[204:207], v[104:107]
	v_mfma_f32_16x16x32_bf16 v[28:31], v[232:235], v[220:223], v[28:31]
	v_mfma_f32_16x16x32_bf16 v[64:67], v[236:239], v[10:13], v[108:111]
	v_mfma_f32_16x16x32_bf16 v[10:13], v[244:247], v[10:13], v[116:119]
	v_mfma_f32_16x16x32_bf16 v[124:127], v[150:153], v[14:17], v[10:13]
	v_mfma_f32_16x16x32_bf16 v[10:13], v[236:239], v[32:35], v[132:135]
	v_mfma_f32_16x16x32_bf16 v[116:119], v[240:243], v[194:197], v[10:13]
	v_mfma_f32_16x16x32_bf16 v[10:13], v[244:247], v[32:35], v[40:43]
	v_mfma_f32_16x16x32_bf16 v[108:111], v[150:153], v[194:197], v[10:13]
	v_mfma_f32_16x16x32_bf16 v[10:13], v[236:239], v[208:211], v[44:47]
	v_mfma_f32_16x16x32_bf16 v[92:95], v[240:243], v[200:203], v[10:13]
	v_mfma_f32_16x16x32_bf16 v[10:13], v[244:247], v[208:211], v[48:51]
	v_mfma_f32_16x16x32_bf16 v[80:83], v[150:153], v[200:203], v[10:13]
	v_mfma_f32_16x16x32_bf16 v[10:13], v[236:239], v[204:207], v[52:55]
	v_mfma_f32_16x16x32_bf16 v[128:131], v[240:243], v[14:17], v[64:67]
	v_mfma_f32_16x16x32_bf16 v[64:67], v[240:243], v[220:223], v[10:13]
	v_mfma_f32_16x16x32_bf16 v[10:13], v[244:247], v[204:207], v[60:63]
	v_mfma_f32_16x16x32_bf16 v[48:51], v[150:153], v[220:223], v[10:13]
	s_barrier
	s_setprio 0
	s_mov_b32 m0, s39
	s_or_b32 s9, s69, 0x180
	ds_read_b128 v[44:47], v149 offset:49152
	ds_read_b128 v[52:55], v149 offset:50176
	ds_read_b128 v[76:79], v149 offset:51200
	ds_read_b128 v[132:135], v149 offset:52224
	ds_read_b128 v[194:197], v149 offset:53248
	ds_read_b128 v[200:203], v149 offset:54272
	ds_read_b128 v[204:207], v149 offset:55296
	ds_read_b128 v[208:211], v149 offset:56320
	buffer_load_dwordx4 v145, s[4:7], s9 offen lds
	s_mov_b32 m0, s40
	s_nop 0
	buffer_load_dwordx4 v147, s[4:7], s9 offen lds
	s_or_b32 s9, s69, 0x40180
	s_mov_b32 m0, s43
	s_nop 0
	buffer_load_dwordx4 v145, s[4:7], s9 offen lds
	s_mov_b32 m0, s42
	s_nop 0
	buffer_load_dwordx4 v147, s[4:7], s9 offen lds
	s_mov_b32 m0, s41
	s_nop 0
	buffer_load_dwordx4 v144, s[0:3], s8 offen lds
	s_mov_b32 m0, s33
	s_nop 0
	buffer_load_dwordx4 v146, s[0:3], s8 offen lds
	s_waitcnt vmcnt(8)
	s_waitcnt lgkmcnt(0)
	s_setprio 1
	s_barrier
	v_mfma_f32_16x16x32_bf16 v[10:13], v[6:9], v[44:47], v[136:139]
	v_mfma_f32_16x16x32_bf16 v[72:75], v[24:27], v[52:55], v[10:13]
	v_mfma_f32_16x16x32_bf16 v[10:13], v[228:231], v[44:47], v[140:143]
	v_mfma_f32_16x16x32_bf16 v[60:63], v[232:235], v[52:55], v[10:13]
	v_mfma_f32_16x16x32_bf16 v[10:13], v[6:9], v[76:79], v[154:157]
	v_mfma_f32_16x16x32_bf16 v[40:43], v[24:27], v[132:135], v[10:13]
	v_mfma_f32_16x16x32_bf16 v[10:13], v[228:231], v[76:79], v[158:161]
	v_mfma_f32_16x16x32_bf16 v[32:35], v[232:235], v[132:135], v[10:13]
	v_mfma_f32_16x16x32_bf16 v[10:13], v[6:9], v[194:197], v[162:165]
	v_mfma_f32_16x16x32_bf16 v[16:19], v[24:27], v[200:203], v[10:13]
	v_mfma_f32_16x16x32_bf16 v[10:13], v[228:231], v[194:197], v[166:169]
	v_mfma_f32_16x16x32_bf16 v[2:5], v[6:9], v[204:207], v[2:5]
	v_mfma_f32_16x16x32_bf16 v[12:15], v[232:235], v[200:203], v[10:13]
	v_mfma_f32_16x16x32_bf16 v[8:11], v[24:27], v[208:211], v[2:5]
	v_mfma_f32_16x16x32_bf16 v[2:5], v[228:231], v[204:207], v[170:173]
	v_mfma_f32_16x16x32_bf16 v[4:7], v[232:235], v[208:211], v[2:5]
	v_mfma_f32_16x16x32_bf16 v[24:27], v[236:239], v[44:47], v[174:177]
	v_mfma_f32_16x16x32_bf16 v[96:99], v[240:243], v[52:55], v[24:27]
	v_mfma_f32_16x16x32_bf16 v[24:27], v[244:247], v[44:47], v[178:181]
	v_mfma_f32_16x16x32_bf16 v[104:107], v[150:153], v[52:55], v[24:27]
	v_mfma_f32_16x16x32_bf16 v[24:27], v[236:239], v[76:79], v[182:185]
	v_mfma_f32_16x16x32_bf16 v[84:87], v[240:243], v[132:135], v[24:27]
	v_mfma_f32_16x16x32_bf16 v[24:27], v[244:247], v[76:79], v[186:189]
	v_mfma_f32_16x16x32_bf16 v[76:79], v[150:153], v[132:135], v[24:27]
	v_mfma_f32_16x16x32_bf16 v[24:27], v[236:239], v[194:197], v[190:193]
	v_mfma_f32_16x16x32_bf16 v[52:55], v[240:243], v[200:203], v[24:27]
	v_mfma_f32_16x16x32_bf16 v[24:27], v[244:247], v[194:197], v[212:215]
	v_mfma_f32_16x16x32_bf16 v[20:23], v[236:239], v[204:207], v[20:23]
	v_mfma_f32_16x16x32_bf16 v[44:47], v[150:153], v[200:203], v[24:27]
	v_mfma_f32_16x16x32_bf16 v[24:27], v[240:243], v[208:211], v[20:23]
	v_mfma_f32_16x16x32_bf16 v[20:23], v[244:247], v[204:207], v[216:219]
	v_mfma_f32_16x16x32_bf16 v[20:23], v[150:153], v[208:211], v[20:23]
	s_barrier
	s_setprio 0
	s_mov_b64 s[8:9], 0
	v_mov_b64_e32 v[234:235], v[198:199]
	v_mov_b64_e32 v[236:237], v[226:227]
	v_mov_b32_e32 v198, v0
	v_mov_b32_e32 v226, v225
	v_mov_b64_e32 v[244:245], 0x100
	v_mov_b64_e32 v[246:247], 0xff

; #define PG8_WAIT_V(n) asm volatile("s_waitcnt vmcnt(" #n ")" ::: "memory")
; template <class Epi, bool ALIGN_EPI, bool SP2, class Hook>
; __device__ __forceinline__ void gemm_phase(LAS unsigned char* lds, const Gemm g, const StaticOrder& S, const Epi& E, Acc& acc, const bool fresh, const Hook& H, const int wave_id) {
;     ...
;         for (int t = t0; t < nt; t += 2) {
;             const bool last = (t == nt - 2);
;             const Src a1 = cA + (size_t)(t + 1) * kstep;
;             const Src a2 = last ? nA : cA + (size_t)(t + 2) * kstep, b2 = last ? nB : cB + (size_t)(t + 2) * kstep;
;             const Src a3 = a2 + kstep, b3 = b2 + kstep;
;             if (last && has_next) H(nxt);
;             if constexpr (SP2) {
;             PG8_TRIP_SP2(PG8_WAIT_V(8));
.LBB0_391:
	v_add_u32_e32 v150, 0x10000, v148
	v_add_u32_e32 v151, 0x14000, v148
	ds_read_b128 v[132:135], v150
	ds_read_b128 v[136:139], v150 offset:1024
	ds_read_b128 v[140:143], v150 offset:2048
	ds_read_b128 v[152:155], v150 offset:3072
	ds_read_b128 v[156:159], v151
	ds_read_b128 v[160:163], v151 offset:1024
	ds_read_b128 v[164:167], v151 offset:2048
	ds_read_b128 v[168:171], v151 offset:3072
	s_add_i32 s12, s56, 0xfffc0080
	s_cmp_eq_u32 s29, 12
	s_cselect_b32 s60, s68, s12
	s_cselect_b32 s13, s5, s77
	s_cselect_b32 s12, s4, s76
	s_cselect_b32 s15, s7, s55
	s_cselect_b32 s14, s6, s54
	s_cselect_b32 s58, s69, s57
	s_cselect_b32 s16, s0, s8
	s_cselect_b32 s17, s1, s9
	s_cselect_b32 s18, s2, s10
	s_cselect_b32 s19, s3, s11
	s_or_b32 s59, s60, 0x80
	s_mov_b32 m0, s45
	ds_read_b128 v[172:175], v149
	ds_read_b128 v[176:179], v149 offset:1024
	ds_read_b128 v[180:183], v149 offset:2048
	ds_read_b128 v[184:187], v149 offset:3072
	ds_read_b128 v[188:191], v149 offset:4096
	ds_read_b128 v[212:215], v149 offset:5120
	ds_read_b128 v[216:219], v149 offset:6144
	ds_read_b128 v[228:231], v149 offset:7168
	buffer_load_dwordx4 v144, s[8:11], s56 offen lds
	s_mov_b32 m0, s46
	s_nop 0
	buffer_load_dwordx4 v146, s[8:11], s56 offen lds
	s_waitcnt vmcnt(8)
	s_waitcnt lgkmcnt(0)
	s_setprio 1
	s_barrier
	v_mfma_f32_16x16x32_bf16 v[120:123], v[132:135], v[172:175], v[120:123]
	v_mfma_f32_16x16x32_bf16 v[112:115], v[140:143], v[172:175], v[112:115]
	v_mfma_f32_16x16x32_bf16 v[100:103], v[132:135], v[180:183], v[100:103]
	v_mfma_f32_16x16x32_bf16 v[88:91], v[140:143], v[180:183], v[88:91]
	v_mfma_f32_16x16x32_bf16 v[68:71], v[132:135], v[188:191], v[68:71]
	v_mfma_f32_16x16x32_bf16 v[56:59], v[140:143], v[188:191], v[56:59]
	v_mfma_f32_16x16x32_bf16 v[36:39], v[132:135], v[216:219], v[36:39]
	v_mfma_f32_16x16x32_bf16 v[28:31], v[140:143], v[216:219], v[28:31]
	v_mfma_f32_16x16x32_bf16 v[120:123], v[136:139], v[176:179], v[120:123]
	v_mfma_f32_16x16x32_bf16 v[112:115], v[152:155], v[176:179], v[112:115]
	v_mfma_f32_16x16x32_bf16 v[100:103], v[136:139], v[184:187], v[100:103]
	v_mfma_f32_16x16x32_bf16 v[88:91], v[152:155], v[184:187], v[88:91]
	v_mfma_f32_16x16x32_bf16 v[68:71], v[136:139], v[212:215], v[68:71]
	v_mfma_f32_16x16x32_bf16 v[56:59], v[152:155], v[212:215], v[56:59]
	v_mfma_f32_16x16x32_bf16 v[36:39], v[136:139], v[228:231], v[36:39]
	v_mfma_f32_16x16x32_bf16 v[28:31], v[152:155], v[228:231], v[28:31]
	v_mfma_f32_16x16x32_bf16 v[128:131], v[156:159], v[172:175], v[128:131]
	v_mfma_f32_16x16x32_bf16 v[124:127], v[164:167], v[172:175], v[124:127]
	v_mfma_f32_16x16x32_bf16 v[116:119], v[156:159], v[180:183], v[116:119]
	v_mfma_f32_16x16x32_bf16 v[108:111], v[164:167], v[180:183], v[108:111]
	v_mfma_f32_16x16x32_bf16 v[92:95], v[156:159], v[188:191], v[92:95]
	v_mfma_f32_16x16x32_bf16 v[80:83], v[164:167], v[188:191], v[80:83]
	v_mfma_f32_16x16x32_bf16 v[64:67], v[156:159], v[216:219], v[64:67]
	v_mfma_f32_16x16x32_bf16 v[48:51], v[164:167], v[216:219], v[48:51]
	v_mfma_f32_16x16x32_bf16 v[128:131], v[160:163], v[176:179], v[128:131]
	v_mfma_f32_16x16x32_bf16 v[124:127], v[168:171], v[176:179], v[124:127]
	v_mfma_f32_16x16x32_bf16 v[116:119], v[160:163], v[184:187], v[116:119]
	v_mfma_f32_16x16x32_bf16 v[108:111], v[168:171], v[184:187], v[108:111]
	v_mfma_f32_16x16x32_bf16 v[92:95], v[160:163], v[212:215], v[92:95]
	v_mfma_f32_16x16x32_bf16 v[80:83], v[168:171], v[212:215], v[80:83]
	v_mfma_f32_16x16x32_bf16 v[64:67], v[160:163], v[228:231], v[64:67]
	v_mfma_f32_16x16x32_bf16 v[48:51], v[168:171], v[228:231], v[48:51]
	s_barrier
	s_setprio 0
	s_mov_b32 m0, s92
	ds_read_b128 v[172:175], v149 offset:16384
	ds_read_b128 v[176:179], v149 offset:17408
	ds_read_b128 v[180:183], v149 offset:18432
	ds_read_b128 v[184:187], v149 offset:19456
	ds_read_b128 v[188:191], v149 offset:20480
	ds_read_b128 v[212:215], v149 offset:21504
	ds_read_b128 v[216:219], v149 offset:22528
	ds_read_b128 v[228:231], v149 offset:23552
	buffer_load_dwordx4 v145, s[12:15], s58 offen lds
	s_mov_b32 m0, s93
	s_add_i32 s61, s58, 0x40000
	buffer_load_dwordx4 v147, s[12:15], s58 offen lds
	s_mov_b32 m0, s94
	s_nop 0
	buffer_load_dwordx4 v145, s[12:15], s61 offen lds
	s_mov_b32 m0, s95
	s_nop 0
	buffer_load_dwordx4 v147, s[12:15], s61 offen lds
	s_mov_b32 m0, s44
	s_nop 0
	buffer_load_dwordx4 v144, s[16:19], s60 offen lds
	s_mov_b32 m0, s36
	s_nop 0
	buffer_load_dwordx4 v146, s[16:19], s60 offen lds
	s_waitcnt vmcnt(8)
	s_waitcnt lgkmcnt(0)
	s_setprio 1
	s_barrier
	v_mfma_f32_16x16x32_bf16 v[72:75], v[132:135], v[172:175], v[72:75]
	v_mfma_f32_16x16x32_bf16 v[60:63], v[140:143], v[172:175], v[60:63]
	v_mfma_f32_16x16x32_bf16 v[40:43], v[132:135], v[180:183], v[40:43]
	v_mfma_f32_16x16x32_bf16 v[32:35], v[140:143], v[180:183], v[32:35]
	v_mfma_f32_16x16x32_bf16 v[16:19], v[132:135], v[188:191], v[16:19]
	v_mfma_f32_16x16x32_bf16 v[12:15], v[140:143], v[188:191], v[12:15]
	v_mfma_f32_16x16x32_bf16 v[8:11], v[132:135], v[216:219], v[8:11]
	v_mfma_f32_16x16x32_bf16 v[2:5], v[140:143], v[216:219], v[4:7]
	v_mfma_f32_16x16x32_bf16 v[72:75], v[136:139], v[176:179], v[72:75]
	v_mfma_f32_16x16x32_bf16 v[60:63], v[152:155], v[176:179], v[60:63]
	v_mfma_f32_16x16x32_bf16 v[40:43], v[136:139], v[184:187], v[40:43]
	v_mfma_f32_16x16x32_bf16 v[32:35], v[152:155], v[184:187], v[32:35]
	v_mfma_f32_16x16x32_bf16 v[16:19], v[136:139], v[212:215], v[16:19]
	v_mfma_f32_16x16x32_bf16 v[12:15], v[152:155], v[212:215], v[12:15]
	v_mfma_f32_16x16x32_bf16 v[8:11], v[136:139], v[228:231], v[8:11]
	v_mfma_f32_16x16x32_bf16 v[2:5], v[152:155], v[228:231], v[2:5]
	v_mfma_f32_16x16x32_bf16 v[96:99], v[156:159], v[172:175], v[96:99]
	v_mfma_f32_16x16x32_bf16 v[104:107], v[164:167], v[172:175], v[104:107]
	v_mfma_f32_16x16x32_bf16 v[84:87], v[156:159], v[180:183], v[84:87]
	v_mfma_f32_16x16x32_bf16 v[76:79], v[164:167], v[180:183], v[76:79]
	v_mfma_f32_16x16x32_bf16 v[52:55], v[156:159], v[188:191], v[52:55]
	v_mfma_f32_16x16x32_bf16 v[44:47], v[164:167], v[188:191], v[44:47]
	v_mfma_f32_16x16x32_bf16 v[24:27], v[156:159], v[216:219], v[24:27]
	v_mfma_f32_16x16x32_bf16 v[20:23], v[164:167], v[216:219], v[20:23]
	v_mfma_f32_16x16x32_bf16 v[96:99], v[160:163], v[176:179], v[96:99]
	v_mfma_f32_16x16x32_bf16 v[104:107], v[168:171], v[176:179], v[104:107]
	v_mfma_f32_16x16x32_bf16 v[84:87], v[160:163], v[184:187], v[84:87]
	v_mfma_f32_16x16x32_bf16 v[76:79], v[168:171], v[184:187], v[76:79]
	v_mfma_f32_16x16x32_bf16 v[52:55], v[160:163], v[212:215], v[52:55]
	v_mfma_f32_16x16x32_bf16 v[44:47], v[168:171], v[212:215], v[44:47]
	v_mfma_f32_16x16x32_bf16 v[24:27], v[160:163], v[228:231], v[24:27]
	v_mfma_f32_16x16x32_bf16 v[20:23], v[168:171], v[228:231], v[20:23]
	s_barrier
; #define PG8_WAIT_V(n) asm volatile("s_waitcnt vmcnt(" #n ")" ::: "memory")
; template <class Epi, bool ALIGN_EPI, bool SP2, class Hook>
; __device__ __forceinline__ void gemm_phase(LAS unsigned char* lds, const Gemm g, const StaticOrder& S, const Epi& E, Acc& acc, const bool fresh, const Hook& H, const int wave_id) {
;     ...
;         for (int t = t0; t < nt; t += 2) {
;             const bool last = (t == nt - 2);
;             const Src a1 = cA + (size_t)(t + 1) * kstep;
;             const Src a2 = last ? nA : cA + (size_t)(t + 2) * kstep, b2 = last ? nB : cB + (size_t)(t + 2) * kstep;
;             const Src a3 = a2 + kstep, b3 = b2 + kstep;
;             if (last && has_next) H(nxt);
;             if constexpr (SP2) {
;             PG8_TRIP_SP2(PG8_WAIT_V(8));
	s_setprio 0
	v_add_u32_e32 v152, 0x18000, v148
	v_add_u32_e32 v153, 0x1c000, v148
	ds_read_b128 v[132:135], v152
	ds_read_b128 v[136:139], v152 offset:1024
	ds_read_b128 v[140:143], v152 offset:2048
	ds_read_b128 v[154:157], v152 offset:3072
	ds_read_b128 v[158:161], v153
	ds_read_b128 v[162:165], v153 offset:1024
	ds_read_b128 v[166:169], v153 offset:2048
	ds_read_b128 v[170:173], v153 offset:3072
	s_add_i32 s60, s60, 0x40000
	s_mov_b32 m0, s37
	ds_read_b128 v[174:177], v149 offset:32768
	ds_read_b128 v[178:181], v149 offset:33792
	ds_read_b128 v[182:185], v149 offset:34816
	ds_read_b128 v[186:189], v149 offset:35840
	ds_read_b128 v[190:193], v149 offset:36864
	ds_read_b128 v[212:215], v149 offset:37888
	ds_read_b128 v[216:219], v149 offset:38912
	ds_read_b128 v[228:231], v149 offset:39936
	buffer_load_dwordx4 v144, s[16:19], s60 offen lds
	s_mov_b32 m0, s38
	s_nop 0
	buffer_load_dwordx4 v146, s[16:19], s60 offen lds
	s_waitcnt vmcnt(8)
	s_waitcnt lgkmcnt(0)
	s_setprio 1
	s_barrier
	v_mfma_f32_16x16x32_bf16 v[120:123], v[132:135], v[174:177], v[120:123]
	v_mfma_f32_16x16x32_bf16 v[112:115], v[140:143], v[174:177], v[112:115]
	v_mfma_f32_16x16x32_bf16 v[100:103], v[132:135], v[182:185], v[100:103]
	v_mfma_f32_16x16x32_bf16 v[88:91], v[140:143], v[182:185], v[88:91]
	v_mfma_f32_16x16x32_bf16 v[68:71], v[132:135], v[190:193], v[68:71]
	v_mfma_f32_16x16x32_bf16 v[56:59], v[140:143], v[190:193], v[56:59]
	v_mfma_f32_16x16x32_bf16 v[36:39], v[132:135], v[216:219], v[36:39]
	v_mfma_f32_16x16x32_bf16 v[28:31], v[140:143], v[216:219], v[28:31]
	v_mfma_f32_16x16x32_bf16 v[120:123], v[136:139], v[178:181], v[120:123]
	v_mfma_f32_16x16x32_bf16 v[112:115], v[154:157], v[178:181], v[112:115]
	v_mfma_f32_16x16x32_bf16 v[100:103], v[136:139], v[186:189], v[100:103]
	v_mfma_f32_16x16x32_bf16 v[88:91], v[154:157], v[186:189], v[88:91]
	v_mfma_f32_16x16x32_bf16 v[68:71], v[136:139], v[212:215], v[68:71]
	v_mfma_f32_16x16x32_bf16 v[56:59], v[154:157], v[212:215], v[56:59]
	v_mfma_f32_16x16x32_bf16 v[36:39], v[136:139], v[228:231], v[36:39]
	v_mfma_f32_16x16x32_bf16 v[28:31], v[154:157], v[228:231], v[28:31]
	v_mfma_f32_16x16x32_bf16 v[128:131], v[158:161], v[174:177], v[128:131]
	v_mfma_f32_16x16x32_bf16 v[124:127], v[166:169], v[174:177], v[124:127]
	v_mfma_f32_16x16x32_bf16 v[116:119], v[158:161], v[182:185], v[116:119]
	v_mfma_f32_16x16x32_bf16 v[108:111], v[166:169], v[182:185], v[108:111]
	v_mfma_f32_16x16x32_bf16 v[92:95], v[158:161], v[190:193], v[92:95]
	v_mfma_f32_16x16x32_bf16 v[80:83], v[166:169], v[190:193], v[80:83]
	v_mfma_f32_16x16x32_bf16 v[64:67], v[158:161], v[216:219], v[64:67]
	v_mfma_f32_16x16x32_bf16 v[48:51], v[166:169], v[216:219], v[48:51]
	v_mfma_f32_16x16x32_bf16 v[128:131], v[162:165], v[178:181], v[128:131]
	v_mfma_f32_16x16x32_bf16 v[124:127], v[170:173], v[178:181], v[124:127]
	v_mfma_f32_16x16x32_bf16 v[116:119], v[162:165], v[186:189], v[116:119]
	v_mfma_f32_16x16x32_bf16 v[108:111], v[170:173], v[186:189], v[108:111]
	v_mfma_f32_16x16x32_bf16 v[92:95], v[162:165], v[212:215], v[92:95]
	v_mfma_f32_16x16x32_bf16 v[80:83], v[170:173], v[212:215], v[80:83]
	v_mfma_f32_16x16x32_bf16 v[64:67], v[162:165], v[228:231], v[64:67]
	v_mfma_f32_16x16x32_bf16 v[48:51], v[170:173], v[228:231], v[48:51]
	s_barrier
	s_setprio 0
	s_mov_b32 m0, s39
	s_or_b32 s60, s58, 0x80
	ds_read_b128 v[174:177], v149 offset:49152
	ds_read_b128 v[178:181], v149 offset:50176
	ds_read_b128 v[182:185], v149 offset:51200
	ds_read_b128 v[186:189], v149 offset:52224
	ds_read_b128 v[190:193], v149 offset:53248
	ds_read_b128 v[212:215], v149 offset:54272
	ds_read_b128 v[216:219], v149 offset:55296
	ds_read_b128 v[228:231], v149 offset:56320
	buffer_load_dwordx4 v145, s[12:15], s60 offen lds
	s_mov_b32 m0, s40
	s_add_i32 s58, s58, 0x40080
	buffer_load_dwordx4 v147, s[12:15], s60 offen lds
	s_mov_b32 m0, s43
	s_nop 0
	buffer_load_dwordx4 v145, s[12:15], s58 offen lds
	s_mov_b32 m0, s42
	s_nop 0
	buffer_load_dwordx4 v147, s[12:15], s58 offen lds
	s_mov_b32 m0, s41
	s_nop 0
	buffer_load_dwordx4 v144, s[16:19], s59 offen lds
	s_mov_b32 m0, s33
	s_nop 0
	buffer_load_dwordx4 v146, s[16:19], s59 offen lds
	s_waitcnt vmcnt(8)
	s_waitcnt lgkmcnt(0)
	s_setprio 1
	s_barrier
	v_mfma_f32_16x16x32_bf16 v[72:75], v[132:135], v[174:177], v[72:75]
	v_mfma_f32_16x16x32_bf16 v[60:63], v[140:143], v[174:177], v[60:63]
	v_mfma_f32_16x16x32_bf16 v[40:43], v[132:135], v[182:185], v[40:43]
	v_mfma_f32_16x16x32_bf16 v[32:35], v[140:143], v[182:185], v[32:35]
	v_mfma_f32_16x16x32_bf16 v[16:19], v[132:135], v[190:193], v[16:19]
	v_mfma_f32_16x16x32_bf16 v[12:15], v[140:143], v[190:193], v[12:15]
	v_mfma_f32_16x16x32_bf16 v[6:9], v[132:135], v[216:219], v[8:11]
	v_mfma_f32_16x16x32_bf16 v[2:5], v[140:143], v[216:219], v[2:5]
	v_mfma_f32_16x16x32_bf16 v[72:75], v[136:139], v[178:181], v[72:75]
	v_mfma_f32_16x16x32_bf16 v[60:63], v[154:157], v[178:181], v[60:63]
	v_mfma_f32_16x16x32_bf16 v[40:43], v[136:139], v[186:189], v[40:43]
	v_mfma_f32_16x16x32_bf16 v[32:35], v[154:157], v[186:189], v[32:35]
	v_mfma_f32_16x16x32_bf16 v[16:19], v[136:139], v[212:215], v[16:19]
	v_mfma_f32_16x16x32_bf16 v[12:15], v[154:157], v[212:215], v[12:15]
	v_mfma_f32_16x16x32_bf16 v[8:11], v[136:139], v[228:231], v[6:9]
	v_mfma_f32_16x16x32_bf16 v[4:7], v[154:157], v[228:231], v[2:5]
	v_mfma_f32_16x16x32_bf16 v[96:99], v[158:161], v[174:177], v[96:99]
	v_mfma_f32_16x16x32_bf16 v[104:107], v[166:169], v[174:177], v[104:107]
	v_mfma_f32_16x16x32_bf16 v[84:87], v[158:161], v[182:185], v[84:87]
	v_mfma_f32_16x16x32_bf16 v[76:79], v[166:169], v[182:185], v[76:79]
	v_mfma_f32_16x16x32_bf16 v[52:55], v[158:161], v[190:193], v[52:55]
	v_mfma_f32_16x16x32_bf16 v[44:47], v[166:169], v[190:193], v[44:47]
	v_mfma_f32_16x16x32_bf16 v[24:27], v[158:161], v[216:219], v[24:27]
	v_mfma_f32_16x16x32_bf16 v[20:23], v[166:169], v[216:219], v[20:23]
	v_mfma_f32_16x16x32_bf16 v[96:99], v[162:165], v[178:181], v[96:99]
	v_mfma_f32_16x16x32_bf16 v[104:107], v[170:173], v[178:181], v[104:107]
	v_mfma_f32_16x16x32_bf16 v[84:87], v[162:165], v[186:189], v[84:87]
	v_mfma_f32_16x16x32_bf16 v[76:79], v[170:173], v[186:189], v[76:79]
	v_mfma_f32_16x16x32_bf16 v[52:55], v[162:165], v[212:215], v[52:55]
	v_mfma_f32_16x16x32_bf16 v[44:47], v[170:173], v[212:215], v[44:47]
	v_mfma_f32_16x16x32_bf16 v[24:27], v[162:165], v[228:231], v[24:27]
	v_mfma_f32_16x16x32_bf16 v[20:23], v[170:173], v[228:231], v[20:23]
	s_barrier
	s_setprio 0
	s_add_i32 s29, s29, 2
	s_addk_i32 s56, 0x100
	s_addk_i32 s57, 0x100
	s_cmp_gt_u32 s29, 13
	s_cbranch_scc0 .LBB0_391
	v_readlane_b32 s8, v251, 45
	v_readlane_b32 s9, v251, 46
	s_and_b64 vcc, exec, s[8:9]
	s_cbranch_vccz .LBB0_394
	s_barrier

; #define PG8_WAIT_V(n) asm volatile("s_waitcnt vmcnt(" #n ")" ::: "memory")
; template <class Epi, bool ALIGN_EPI, bool SP2, class Hook>
; __device__ __forceinline__ void gemm_phase(LAS unsigned char* lds, const Gemm g, const StaticOrder& S, const Epi& E, Acc& acc, const bool fresh, const Hook& H, const int wave_id) {
;     ...
;         for (int t = t0; t < nt; t += 2) {
;             const bool last = (t == nt - 2);
;             const Src a1 = cA + (size_t)(t + 1) * kstep;
;             const Src a2 = last ? nA : cA + (size_t)(t + 2) * kstep, b2 = last ? nB : cB + (size_t)(t + 2) * kstep;
;             const Src a3 = a2 + kstep, b3 = b2 + kstep;
;             if (last && has_next) H(nxt);
;             if constexpr (SP2) {
;             PG8_TRIP_SP2(PG8_WAIT_V(8));
.LBB0_702:
	v_add_u32_e32 v70, 0x10000, v216
	v_add_u32_e32 v118, 0x14000, v216
	ds_read_b128 v[34:37], v70
	ds_read_b128 v[46:49], v70 offset:1024
	ds_read_b128 v[58:61], v70 offset:2048
	ds_read_b128 v[70:73], v70 offset:3072
	ds_read_b128 v[82:85], v118
	ds_read_b128 v[94:97], v118 offset:1024
	ds_read_b128 v[106:109], v118 offset:2048
	ds_read_b128 v[118:121], v118 offset:3072
	s_add_i32 s12, s55, 0xfffe0080
	s_cmp_eq_u32 s57, 4
	s_cselect_b32 s60, s53, s12
	s_cselect_b32 s13, s29, s77
	s_cselect_b32 s12, s28, s76
	s_cselect_b32 s15, s31, s35
	s_cselect_b32 s14, s30, s34
	s_cselect_b32 s58, s54, s56
	s_cselect_b32 s16, s2, s8
	s_cselect_b32 s17, s3, s9
	s_cselect_b32 s18, s26, s10
	s_cselect_b32 s19, s27, s11
	s_or_b32 s59, s60, 0x80
	s_mov_b32 m0, s45
	s_waitcnt vmcnt(14)
	ds_read_b128 v[130:133], v217
	ds_read_b128 v[142:145], v217 offset:1024
	ds_read_b128 v[154:157], v217 offset:2048
	ds_read_b128 v[166:169], v217 offset:3072
	ds_read_b128 v[174:177], v217 offset:4096
	ds_read_b128 v[182:185], v217 offset:5120
	ds_read_b128 v[186:189], v217 offset:6144
	ds_read_b128 v[190:193], v217 offset:7168
	buffer_load_dwordx4 v0, s[8:11], s55 offen lds
	s_mov_b32 m0, s46
	s_nop 0
	buffer_load_dwordx4 v214, s[8:11], s55 offen lds
	s_waitcnt vmcnt(8)
	s_waitcnt lgkmcnt(0)
	s_setprio 1
	s_barrier
	v_mfma_f32_16x16x32_bf16 v[178:181], v[34:37], v[130:133], v[178:181]
	v_mfma_f32_16x16x32_bf16 v[170:173], v[58:61], v[130:133], v[170:173]
	v_mfma_f32_16x16x32_bf16 v[150:153], v[34:37], v[154:157], v[150:153]
	v_mfma_f32_16x16x32_bf16 v[146:149], v[58:61], v[154:157], v[146:149]
	v_mfma_f32_16x16x32_bf16 v[126:129], v[34:37], v[174:177], v[126:129]
	v_mfma_f32_16x16x32_bf16 v[122:125], v[58:61], v[174:177], v[122:125]
	v_mfma_f32_16x16x32_bf16 v[102:105], v[34:37], v[186:189], v[102:105]
	v_mfma_f32_16x16x32_bf16 v[98:101], v[58:61], v[186:189], v[98:101]
	v_mfma_f32_16x16x32_bf16 v[178:181], v[46:49], v[142:145], v[178:181]
	v_mfma_f32_16x16x32_bf16 v[170:173], v[70:73], v[142:145], v[170:173]
	v_mfma_f32_16x16x32_bf16 v[150:153], v[46:49], v[166:169], v[150:153]
	v_mfma_f32_16x16x32_bf16 v[146:149], v[70:73], v[166:169], v[146:149]
	v_mfma_f32_16x16x32_bf16 v[126:129], v[46:49], v[182:185], v[126:129]
	v_mfma_f32_16x16x32_bf16 v[122:125], v[70:73], v[182:185], v[122:125]
	v_mfma_f32_16x16x32_bf16 v[102:105], v[46:49], v[190:193], v[102:105]
	v_mfma_f32_16x16x32_bf16 v[98:101], v[70:73], v[190:193], v[98:101]
	v_mfma_f32_16x16x32_bf16 v[162:165], v[82:85], v[130:133], v[162:165]
	v_mfma_f32_16x16x32_bf16 v[138:141], v[82:85], v[154:157], v[138:141]
	v_mfma_f32_16x16x32_bf16 v[134:137], v[106:109], v[154:157], v[134:137]
	v_mfma_f32_16x16x32_bf16 v[114:117], v[82:85], v[174:177], v[114:117]
	v_mfma_f32_16x16x32_bf16 v[110:113], v[106:109], v[174:177], v[110:113]
	v_mfma_f32_16x16x32_bf16 v[90:93], v[82:85], v[186:189], v[90:93]
	v_mfma_f32_16x16x32_bf16 v[86:89], v[106:109], v[186:189], v[86:89]
	v_mfma_f32_16x16x32_bf16 v[162:165], v[94:97], v[142:145], v[162:165]
	v_mfma_f32_16x16x32_bf16 v[130:133], v[106:109], v[130:133], v[158:161]
	v_mfma_f32_16x16x32_bf16 v[138:141], v[94:97], v[166:169], v[138:141]
	v_mfma_f32_16x16x32_bf16 v[134:137], v[118:121], v[166:169], v[134:137]
	v_mfma_f32_16x16x32_bf16 v[114:117], v[94:97], v[182:185], v[114:117]
	v_mfma_f32_16x16x32_bf16 v[110:113], v[118:121], v[182:185], v[110:113]
	v_mfma_f32_16x16x32_bf16 v[90:93], v[94:97], v[190:193], v[90:93]
	v_mfma_f32_16x16x32_bf16 v[86:89], v[118:121], v[190:193], v[86:89]
	v_mfma_f32_16x16x32_bf16 v[130:133], v[118:121], v[142:145], v[130:133]
	s_barrier
	s_setprio 0
	s_mov_b32 m0, s92
	ds_read_b128 v[142:145], v217 offset:16384
	ds_read_b128 v[154:157], v217 offset:17408
	ds_read_b128 v[158:161], v217 offset:18432
	ds_read_b128 v[166:169], v217 offset:19456
	ds_read_b128 v[174:177], v217 offset:20480
	ds_read_b128 v[182:185], v217 offset:21504
	ds_read_b128 v[186:189], v217 offset:22528
	ds_read_b128 v[190:193], v217 offset:23552
	buffer_load_dwordx4 v199, s[12:15], s58 offen lds
	s_mov_b32 m0, s93
	s_add_i32 s61, s58, 0x20000
	buffer_load_dwordx4 v215, s[12:15], s58 offen lds
	s_mov_b32 m0, s94
	s_nop 0
	buffer_load_dwordx4 v199, s[12:15], s61 offen lds
	s_mov_b32 m0, s95
	s_nop 0
	buffer_load_dwordx4 v215, s[12:15], s61 offen lds
	s_mov_b32 m0, s44
	s_nop 0
	buffer_load_dwordx4 v0, s[16:19], s60 offen lds
	s_mov_b32 m0, s36
	s_nop 0
	buffer_load_dwordx4 v214, s[16:19], s60 offen lds
	s_waitcnt vmcnt(8)
	s_waitcnt lgkmcnt(0)
	s_setprio 1
	s_barrier
	v_mfma_f32_16x16x32_bf16 v[78:81], v[34:37], v[142:145], v[78:81]
	v_mfma_f32_16x16x32_bf16 v[74:77], v[58:61], v[142:145], v[74:77]
	v_mfma_f32_16x16x32_bf16 v[54:57], v[34:37], v[158:161], v[54:57]
	v_mfma_f32_16x16x32_bf16 v[50:53], v[58:61], v[158:161], v[50:53]
	v_mfma_f32_16x16x32_bf16 v[30:33], v[34:37], v[174:177], v[30:33]
	v_mfma_f32_16x16x32_bf16 v[26:29], v[58:61], v[174:177], v[26:29]
	v_mfma_f32_16x16x32_bf16 v[14:17], v[34:37], v[186:189], v[14:17]
	v_mfma_f32_16x16x32_bf16 v[10:13], v[58:61], v[186:189], v[10:13]
	v_mfma_f32_16x16x32_bf16 v[78:81], v[46:49], v[154:157], v[78:81]
	v_mfma_f32_16x16x32_bf16 v[74:77], v[70:73], v[154:157], v[74:77]
	v_mfma_f32_16x16x32_bf16 v[54:57], v[46:49], v[166:169], v[54:57]
	v_mfma_f32_16x16x32_bf16 v[50:53], v[70:73], v[166:169], v[50:53]
	v_mfma_f32_16x16x32_bf16 v[30:33], v[46:49], v[182:185], v[30:33]
	v_mfma_f32_16x16x32_bf16 v[26:29], v[70:73], v[182:185], v[26:29]
	v_mfma_f32_16x16x32_bf16 v[14:17], v[46:49], v[190:193], v[14:17]
	v_mfma_f32_16x16x32_bf16 v[10:13], v[70:73], v[190:193], v[10:13]
	v_mfma_f32_16x16x32_bf16 v[42:45], v[82:85], v[158:161], v[42:45]
	v_mfma_f32_16x16x32_bf16 v[38:41], v[106:109], v[158:161], v[38:41]
	v_mfma_f32_16x16x32_bf16 v[22:25], v[82:85], v[174:177], v[22:25]
	v_mfma_f32_16x16x32_bf16 v[18:21], v[106:109], v[174:177], v[18:21]
	v_mfma_f32_16x16x32_bf16 v[6:9], v[82:85], v[186:189], v[6:9]
	v_mfma_f32_16x16x32_bf16 v[2:5], v[106:109], v[186:189], v[2:5]
	v_mfma_f32_16x16x32_bf16 v[34:37], v[82:85], v[142:145], v[66:69]
	v_mfma_f32_16x16x32_bf16 v[46:49], v[106:109], v[142:145], v[62:65]
	v_mfma_f32_16x16x32_bf16 v[42:45], v[94:97], v[166:169], v[42:45]
	v_mfma_f32_16x16x32_bf16 v[38:41], v[118:121], v[166:169], v[38:41]
	v_mfma_f32_16x16x32_bf16 v[22:25], v[94:97], v[182:185], v[22:25]
	v_mfma_f32_16x16x32_bf16 v[18:21], v[118:121], v[182:185], v[18:21]
	v_mfma_f32_16x16x32_bf16 v[6:9], v[94:97], v[190:193], v[6:9]
	v_mfma_f32_16x16x32_bf16 v[2:5], v[118:121], v[190:193], v[2:5]
	v_mfma_f32_16x16x32_bf16 v[34:37], v[94:97], v[154:157], v[34:37]
	v_mfma_f32_16x16x32_bf16 v[46:49], v[118:121], v[154:157], v[46:49]
	s_barrier
; #define PG8_BAR __builtin_amdgcn_s_barrier()
; template <class Epi, bool ALIGN_EPI, bool SP2, class Hook>
; __device__ __forceinline__ void gemm_phase(LAS unsigned char* lds, const Gemm g, const StaticOrder& S, const Epi& E, Acc& acc, const bool fresh, const Hook& H, const int wave_id) {
;     ...
;         if constexpr (ALIGN_EPI) { if (wr == 0) PG8_BAR; }
	s_setprio 0
	v_add_u32_e32 v70, 0x18000, v216
	v_add_u32_e32 v118, 0x1c000, v216
	ds_read_b128 v[58:61], v70
	ds_read_b128 v[62:65], v70 offset:1024
	ds_read_b128 v[66:69], v70 offset:2048
	ds_read_b128 v[70:73], v70 offset:3072
	ds_read_b128 v[82:85], v118
	ds_read_b128 v[94:97], v118 offset:1024
	ds_read_b128 v[106:109], v118 offset:2048
	ds_read_b128 v[118:121], v118 offset:3072
	s_add_i32 s60, s60, 0x20000
	s_mov_b32 m0, s37
	ds_read_b128 v[142:145], v217 offset:32768
	ds_read_b128 v[154:157], v217 offset:33792
	ds_read_b128 v[166:169], v217 offset:34816
	ds_read_b128 v[174:177], v217 offset:35840
	ds_read_b128 v[182:185], v217 offset:36864
	ds_read_b128 v[186:189], v217 offset:37888
	ds_read_b128 v[190:193], v217 offset:38912
	ds_read_b128 v[194:197], v217 offset:39936
	buffer_load_dwordx4 v0, s[16:19], s60 offen lds
	s_mov_b32 m0, s38
	s_nop 0
	buffer_load_dwordx4 v214, s[16:19], s60 offen lds
	s_waitcnt vmcnt(8)
	s_waitcnt lgkmcnt(0)
	s_setprio 1
	s_barrier
	v_mfma_f32_16x16x32_bf16 v[158:161], v[58:61], v[142:145], v[178:181]
	v_mfma_f32_16x16x32_bf16 v[178:181], v[62:65], v[154:157], v[158:161]
	v_mfma_f32_16x16x32_bf16 v[158:161], v[66:69], v[142:145], v[170:173]
	v_mfma_f32_16x16x32_bf16 v[150:153], v[58:61], v[166:169], v[150:153]
	v_mfma_f32_16x16x32_bf16 v[146:149], v[66:69], v[166:169], v[146:149]
	v_mfma_f32_16x16x32_bf16 v[126:129], v[58:61], v[182:185], v[126:129]
	v_mfma_f32_16x16x32_bf16 v[122:125], v[66:69], v[182:185], v[122:125]
	v_mfma_f32_16x16x32_bf16 v[102:105], v[58:61], v[190:193], v[102:105]
	v_mfma_f32_16x16x32_bf16 v[98:101], v[66:69], v[190:193], v[98:101]
	v_mfma_f32_16x16x32_bf16 v[170:173], v[70:73], v[154:157], v[158:161]
	v_mfma_f32_16x16x32_bf16 v[150:153], v[62:65], v[174:177], v[150:153]
	v_mfma_f32_16x16x32_bf16 v[146:149], v[70:73], v[174:177], v[146:149]
	v_mfma_f32_16x16x32_bf16 v[126:129], v[62:65], v[186:189], v[126:129]
	v_mfma_f32_16x16x32_bf16 v[122:125], v[70:73], v[186:189], v[122:125]
	v_mfma_f32_16x16x32_bf16 v[102:105], v[62:65], v[194:197], v[102:105]
	v_mfma_f32_16x16x32_bf16 v[98:101], v[70:73], v[194:197], v[98:101]
	v_mfma_f32_16x16x32_bf16 v[158:161], v[82:85], v[142:145], v[162:165]
	v_mfma_f32_16x16x32_bf16 v[130:133], v[106:109], v[142:145], v[130:133]
	v_mfma_f32_16x16x32_bf16 v[162:165], v[94:97], v[154:157], v[158:161]
	v_mfma_f32_16x16x32_bf16 v[158:161], v[118:121], v[154:157], v[130:133]
	v_mfma_f32_16x16x32_bf16 v[130:133], v[82:85], v[166:169], v[138:141]
	v_mfma_f32_16x16x32_bf16 v[138:141], v[94:97], v[174:177], v[130:133]
	v_mfma_f32_16x16x32_bf16 v[130:133], v[106:109], v[166:169], v[134:137]
	v_mfma_f32_16x16x32_bf16 v[114:117], v[82:85], v[182:185], v[114:117]
	v_mfma_f32_16x16x32_bf16 v[110:113], v[106:109], v[182:185], v[110:113]
	v_mfma_f32_16x16x32_bf16 v[90:93], v[82:85], v[190:193], v[90:93]
	v_mfma_f32_16x16x32_bf16 v[86:89], v[106:109], v[190:193], v[86:89]
	v_mfma_f32_16x16x32_bf16 v[134:137], v[118:121], v[174:177], v[130:133]
	v_mfma_f32_16x16x32_bf16 v[114:117], v[94:97], v[186:189], v[114:117]
	v_mfma_f32_16x16x32_bf16 v[110:113], v[118:121], v[186:189], v[110:113]
	v_mfma_f32_16x16x32_bf16 v[90:93], v[94:97], v[194:197], v[90:93]
	v_mfma_f32_16x16x32_bf16 v[86:89], v[118:121], v[194:197], v[86:89]
	s_barrier
	s_setprio 0
	s_mov_b32 m0, s39
	s_or_b32 s60, s58, 0x80
	ds_read_b128 v[130:133], v217 offset:49152
	ds_read_b128 v[142:145], v217 offset:50176
	ds_read_b128 v[154:157], v217 offset:51200
	ds_read_b128 v[166:169], v217 offset:52224
	ds_read_b128 v[174:177], v217 offset:53248
	ds_read_b128 v[182:185], v217 offset:54272
	ds_read_b128 v[186:189], v217 offset:55296
	ds_read_b128 v[190:193], v217 offset:56320
	buffer_load_dwordx4 v199, s[12:15], s60 offen lds
	s_mov_b32 m0, s40
	s_add_i32 s58, s58, 0x20080
	buffer_load_dwordx4 v215, s[12:15], s60 offen lds
	s_mov_b32 m0, s43
	s_nop 0
	buffer_load_dwordx4 v199, s[12:15], s58 offen lds
	s_mov_b32 m0, s42
	s_nop 0
	buffer_load_dwordx4 v215, s[12:15], s58 offen lds
	s_mov_b32 m0, s41
	s_nop 0
	buffer_load_dwordx4 v0, s[16:19], s59 offen lds
	s_mov_b32 m0, s33
	s_nop 0
	buffer_load_dwordx4 v214, s[16:19], s59 offen lds
	s_waitcnt vmcnt(8)
	s_waitcnt lgkmcnt(0)
	s_setprio 1
	s_barrier
	v_mfma_f32_16x16x32_bf16 v[78:81], v[58:61], v[130:133], v[78:81]
	v_mfma_f32_16x16x32_bf16 v[74:77], v[66:69], v[130:133], v[74:77]
	v_mfma_f32_16x16x32_bf16 v[54:57], v[58:61], v[154:157], v[54:57]
	v_mfma_f32_16x16x32_bf16 v[50:53], v[66:69], v[154:157], v[50:53]
	v_mfma_f32_16x16x32_bf16 v[30:33], v[58:61], v[174:177], v[30:33]
	v_mfma_f32_16x16x32_bf16 v[26:29], v[66:69], v[174:177], v[26:29]
	v_mfma_f32_16x16x32_bf16 v[14:17], v[58:61], v[186:189], v[14:17]
	v_mfma_f32_16x16x32_bf16 v[10:13], v[66:69], v[186:189], v[10:13]
	v_mfma_f32_16x16x32_bf16 v[78:81], v[62:65], v[142:145], v[78:81]
	v_mfma_f32_16x16x32_bf16 v[74:77], v[70:73], v[142:145], v[74:77]
	v_mfma_f32_16x16x32_bf16 v[54:57], v[62:65], v[166:169], v[54:57]
	v_mfma_f32_16x16x32_bf16 v[50:53], v[70:73], v[166:169], v[50:53]
	v_mfma_f32_16x16x32_bf16 v[30:33], v[62:65], v[182:185], v[30:33]
	v_mfma_f32_16x16x32_bf16 v[26:29], v[70:73], v[182:185], v[26:29]
	v_mfma_f32_16x16x32_bf16 v[14:17], v[62:65], v[190:193], v[14:17]
	v_mfma_f32_16x16x32_bf16 v[10:13], v[70:73], v[190:193], v[10:13]
	v_mfma_f32_16x16x32_bf16 v[34:37], v[82:85], v[130:133], v[34:37]
	v_mfma_f32_16x16x32_bf16 v[66:69], v[94:97], v[142:145], v[34:37]
	v_mfma_f32_16x16x32_bf16 v[34:37], v[106:109], v[130:133], v[46:49]
	v_mfma_f32_16x16x32_bf16 v[62:65], v[118:121], v[142:145], v[34:37]
	v_mfma_f32_16x16x32_bf16 v[34:37], v[82:85], v[154:157], v[42:45]
	v_mfma_f32_16x16x32_bf16 v[42:45], v[94:97], v[166:169], v[34:37]
	v_mfma_f32_16x16x32_bf16 v[34:37], v[106:109], v[154:157], v[38:41]
	v_mfma_f32_16x16x32_bf16 v[22:25], v[82:85], v[174:177], v[22:25]
	v_mfma_f32_16x16x32_bf16 v[18:21], v[106:109], v[174:177], v[18:21]
	v_mfma_f32_16x16x32_bf16 v[6:9], v[82:85], v[186:189], v[6:9]
	v_mfma_f32_16x16x32_bf16 v[2:5], v[106:109], v[186:189], v[2:5]
	v_mfma_f32_16x16x32_bf16 v[38:41], v[118:121], v[166:169], v[34:37]
	v_mfma_f32_16x16x32_bf16 v[22:25], v[94:97], v[182:185], v[22:25]
	v_mfma_f32_16x16x32_bf16 v[18:21], v[118:121], v[182:185], v[18:21]
	v_mfma_f32_16x16x32_bf16 v[6:9], v[94:97], v[190:193], v[6:9]
	v_mfma_f32_16x16x32_bf16 v[2:5], v[118:121], v[190:193], v[2:5]
	s_barrier
	s_setprio 0
	s_add_i32 s57, s57, 2
	s_addk_i32 s55, 0x100
	s_addk_i32 s56, 0x100
	s_cmp_gt_u32 s57, 5
	s_cbranch_scc0 .LBB0_702
	v_readlane_b32 s8, v251, 45
	v_readlane_b32 s9, v251, 46
	s_and_b64 vcc, exec, s[8:9]
	s_cbranch_vccz .LBB0_705
	s_barrier

; template <class Epi, bool ALIGN_EPI, bool SP2, class Hook>
; __device__ __forceinline__ void gemm_phase(LAS unsigned char* lds, const Gemm g, const StaticOrder& S, const Epi& E, Acc& acc, const bool fresh, const Hook& H, const int wave_id) {
;     ...
;         for (int t = t0; t < nt; t += 2) {
;             const bool last = (t == nt - 2);
;             const Src a1 = cA + (size_t)(t + 1) * kstep;
;             const Src a2 = last ? nA : cA + (size_t)(t + 2) * kstep, b2 = last ? nB : cB + (size_t)(t + 2) * kstep;
;             const Src a3 = a2 + kstep, b3 = b2 + kstep;
.LBB0_779:
	v_add_u32_e32 v0, 0x10000, v230
	s_waitcnt vmcnt(0)
	ds_read_b128 v[130:133], v0
	ds_read_b128 v[134:137], v0 offset:1024
	ds_read_b128 v[138:141], v0 offset:2048
	ds_read_b128 v[142:145], v0 offset:3072
	v_add_u32_e32 v0, 0x14000, v230
	ds_read_b128 v[146:149], v0
	ds_read_b128 v[150:153], v0 offset:1024
	ds_read_b128 v[154:157], v0 offset:2048
	ds_read_b128 v[158:161], v0 offset:3072
	s_add_i32 s12, s2, 0xfffe0080
	s_cmp_eq_u32 s63, 4
	s_cselect_b32 s66, s60, s12
	s_cselect_b32 s13, s53, s77
	s_cselect_b32 s12, s52, s76
	s_cselect_b32 s15, s55, s7
	s_cselect_b32 s14, s54, s6
	s_cselect_b32 s64, s61, s3
	s_cselect_b32 s16, s34, s8
	s_cselect_b32 s17, s35, s9
	s_cselect_b32 s18, s50, s10
	s_cselect_b32 s19, s51, s11
	s_or_b32 s65, s66, 0x80
	s_mov_b32 m0, s45
	ds_read_b128 v[162:165], v231
	ds_read_b128 v[166:169], v231 offset:1024
	ds_read_b128 v[170:173], v231 offset:2048
	ds_read_b128 v[174:177], v231 offset:3072
	ds_read_b128 v[178:181], v231 offset:4096
	ds_read_b128 v[182:185], v231 offset:5120
	ds_read_b128 v[186:189], v231 offset:6144
	ds_read_b128 v[190:193], v231 offset:7168
	buffer_load_dwordx4 v199, s[8:11], s2 offen lds
	s_mov_b32 m0, s46
	s_nop 0
	buffer_load_dwordx4 v228, s[8:11], s2 offen lds
	s_waitcnt vmcnt(8)
	s_waitcnt lgkmcnt(0)
	s_setprio 1
	s_barrier
	v_mfma_f32_16x16x32_bf16 v[126:129], v[130:133], v[162:165], v[126:129]
	v_mfma_f32_16x16x32_bf16 v[122:125], v[138:141], v[162:165], v[122:125]
	v_mfma_f32_16x16x32_bf16 v[118:121], v[130:133], v[170:173], v[118:121]
	v_mfma_f32_16x16x32_bf16 v[114:117], v[138:141], v[170:173], v[114:117]
	v_mfma_f32_16x16x32_bf16 v[110:113], v[130:133], v[178:181], v[110:113]
	v_mfma_f32_16x16x32_bf16 v[106:109], v[138:141], v[178:181], v[106:109]
	v_mfma_f32_16x16x32_bf16 v[102:105], v[130:133], v[186:189], v[102:105]
	v_mfma_f32_16x16x32_bf16 v[98:101], v[138:141], v[186:189], v[98:101]
	v_mfma_f32_16x16x32_bf16 v[126:129], v[134:137], v[166:169], v[126:129]
	v_mfma_f32_16x16x32_bf16 v[122:125], v[142:145], v[166:169], v[122:125]
	v_mfma_f32_16x16x32_bf16 v[118:121], v[134:137], v[174:177], v[118:121]
	v_mfma_f32_16x16x32_bf16 v[114:117], v[142:145], v[174:177], v[114:117]
	v_mfma_f32_16x16x32_bf16 v[110:113], v[134:137], v[182:185], v[110:113]
	v_mfma_f32_16x16x32_bf16 v[106:109], v[142:145], v[182:185], v[106:109]
	v_mfma_f32_16x16x32_bf16 v[102:105], v[134:137], v[190:193], v[102:105]
	v_mfma_f32_16x16x32_bf16 v[98:101], v[142:145], v[190:193], v[98:101]
	v_mfma_f32_16x16x32_bf16 v[94:97], v[146:149], v[162:165], v[94:97]
	v_mfma_f32_16x16x32_bf16 v[90:93], v[154:157], v[162:165], v[90:93]
	v_mfma_f32_16x16x32_bf16 v[86:89], v[146:149], v[170:173], v[86:89]
	v_mfma_f32_16x16x32_bf16 v[82:85], v[154:157], v[170:173], v[82:85]
	v_mfma_f32_16x16x32_bf16 v[78:81], v[146:149], v[178:181], v[78:81]
	v_mfma_f32_16x16x32_bf16 v[74:77], v[154:157], v[178:181], v[74:77]
	v_mfma_f32_16x16x32_bf16 v[70:73], v[146:149], v[186:189], v[70:73]
	v_mfma_f32_16x16x32_bf16 v[66:69], v[154:157], v[186:189], v[66:69]
	v_mfma_f32_16x16x32_bf16 v[94:97], v[150:153], v[166:169], v[94:97]
	v_mfma_f32_16x16x32_bf16 v[90:93], v[158:161], v[166:169], v[90:93]
	v_mfma_f32_16x16x32_bf16 v[86:89], v[150:153], v[174:177], v[86:89]
	v_mfma_f32_16x16x32_bf16 v[82:85], v[158:161], v[174:177], v[82:85]
	v_mfma_f32_16x16x32_bf16 v[78:81], v[150:153], v[182:185], v[78:81]
	v_mfma_f32_16x16x32_bf16 v[74:77], v[158:161], v[182:185], v[74:77]
	v_mfma_f32_16x16x32_bf16 v[70:73], v[150:153], v[190:193], v[70:73]
	v_mfma_f32_16x16x32_bf16 v[66:69], v[158:161], v[190:193], v[66:69]
	s_barrier
	s_setprio 0
	s_mov_b32 m0, s92
	ds_read_b128 v[162:165], v231 offset:16384
	ds_read_b128 v[166:169], v231 offset:17408
	ds_read_b128 v[170:173], v231 offset:18432
	ds_read_b128 v[174:177], v231 offset:19456
	ds_read_b128 v[178:181], v231 offset:20480
	ds_read_b128 v[182:185], v231 offset:21504
	ds_read_b128 v[186:189], v231 offset:22528
	ds_read_b128 v[190:193], v231 offset:23552
	buffer_load_dwordx4 v227, s[12:15], s64 offen lds
	s_mov_b32 m0, s93
	s_add_i32 s67, s64, 0x20000
	buffer_load_dwordx4 v229, s[12:15], s64 offen lds
	s_mov_b32 m0, s94
	s_nop 0
	buffer_load_dwordx4 v227, s[12:15], s67 offen lds
	s_mov_b32 m0, s95
	s_nop 0
	buffer_load_dwordx4 v229, s[12:15], s67 offen lds
	s_mov_b32 m0, s44
	s_nop 0
	buffer_load_dwordx4 v199, s[16:19], s66 offen lds
	s_mov_b32 m0, s36
	s_nop 0
	buffer_load_dwordx4 v228, s[16:19], s66 offen lds
	s_waitcnt vmcnt(8)
	s_waitcnt lgkmcnt(0)
	s_setprio 1
	s_barrier
	v_mfma_f32_16x16x32_bf16 v[62:65], v[130:133], v[162:165], v[62:65]
	v_mfma_f32_16x16x32_bf16 v[58:61], v[138:141], v[162:165], v[58:61]
	v_mfma_f32_16x16x32_bf16 v[54:57], v[130:133], v[170:173], v[54:57]
	v_mfma_f32_16x16x32_bf16 v[50:53], v[138:141], v[170:173], v[50:53]
	v_mfma_f32_16x16x32_bf16 v[46:49], v[130:133], v[178:181], v[46:49]
	v_mfma_f32_16x16x32_bf16 v[42:45], v[138:141], v[178:181], v[42:45]
	v_mfma_f32_16x16x32_bf16 v[38:41], v[130:133], v[186:189], v[38:41]
	v_mfma_f32_16x16x32_bf16 v[34:37], v[138:141], v[186:189], v[34:37]
	v_mfma_f32_16x16x32_bf16 v[62:65], v[134:137], v[166:169], v[62:65]
	v_mfma_f32_16x16x32_bf16 v[58:61], v[142:145], v[166:169], v[58:61]
	v_mfma_f32_16x16x32_bf16 v[54:57], v[134:137], v[174:177], v[54:57]
	v_mfma_f32_16x16x32_bf16 v[50:53], v[142:145], v[174:177], v[50:53]
	v_mfma_f32_16x16x32_bf16 v[46:49], v[134:137], v[182:185], v[46:49]
	v_mfma_f32_16x16x32_bf16 v[42:45], v[142:145], v[182:185], v[42:45]
	v_mfma_f32_16x16x32_bf16 v[38:41], v[134:137], v[190:193], v[38:41]
	v_mfma_f32_16x16x32_bf16 v[34:37], v[142:145], v[190:193], v[34:37]
	v_mfma_f32_16x16x32_bf16 v[30:33], v[146:149], v[162:165], v[30:33]
	v_mfma_f32_16x16x32_bf16 v[26:29], v[154:157], v[162:165], v[26:29]
	v_mfma_f32_16x16x32_bf16 v[22:25], v[146:149], v[170:173], v[22:25]
	v_mfma_f32_16x16x32_bf16 v[18:21], v[154:157], v[170:173], v[18:21]
	v_mfma_f32_16x16x32_bf16 v[14:17], v[146:149], v[178:181], v[14:17]
	v_mfma_f32_16x16x32_bf16 v[10:13], v[154:157], v[178:181], v[10:13]
	v_mfma_f32_16x16x32_bf16 v[6:9], v[146:149], v[186:189], v[6:9]
	v_mfma_f32_16x16x32_bf16 v[2:5], v[154:157], v[186:189], v[2:5]
	v_mfma_f32_16x16x32_bf16 v[30:33], v[150:153], v[166:169], v[30:33]
	v_mfma_f32_16x16x32_bf16 v[26:29], v[158:161], v[166:169], v[26:29]
	v_mfma_f32_16x16x32_bf16 v[22:25], v[150:153], v[174:177], v[22:25]
	v_mfma_f32_16x16x32_bf16 v[18:21], v[158:161], v[174:177], v[18:21]
	v_mfma_f32_16x16x32_bf16 v[14:17], v[150:153], v[182:185], v[14:17]
	v_mfma_f32_16x16x32_bf16 v[10:13], v[158:161], v[182:185], v[10:13]
	v_mfma_f32_16x16x32_bf16 v[6:9], v[150:153], v[190:193], v[6:9]
	v_mfma_f32_16x16x32_bf16 v[2:5], v[158:161], v[190:193], v[2:5]
	s_barrier
; #define PG8_BAR __builtin_amdgcn_s_barrier()
; template <class Epi, bool ALIGN_EPI, bool SP2, class Hook>
; __device__ __forceinline__ void gemm_phase(LAS unsigned char* lds, const Gemm g, const StaticOrder& S, const Epi& E, Acc& acc, const bool fresh, const Hook& H, const int wave_id) {
;     ...
;         if constexpr (ALIGN_EPI) { if (wr == 0) PG8_BAR; }
	s_setprio 0
	v_add_u32_e32 v0, 0x18000, v230
	ds_read_b128 v[130:133], v0
	ds_read_b128 v[134:137], v0 offset:1024
	ds_read_b128 v[138:141], v0 offset:2048
	ds_read_b128 v[142:145], v0 offset:3072
	v_add_u32_e32 v0, 0x1c000, v230
	ds_read_b128 v[146:149], v0
	ds_read_b128 v[150:153], v0 offset:1024
	ds_read_b128 v[154:157], v0 offset:2048
	ds_read_b128 v[158:161], v0 offset:3072
	s_add_i32 s66, s66, 0x20000
	s_mov_b32 m0, s37
	ds_read_b128 v[162:165], v231 offset:32768
	ds_read_b128 v[166:169], v231 offset:33792
	ds_read_b128 v[170:173], v231 offset:34816
	ds_read_b128 v[174:177], v231 offset:35840
	ds_read_b128 v[178:181], v231 offset:36864
	ds_read_b128 v[182:185], v231 offset:37888
	ds_read_b128 v[186:189], v231 offset:38912
	ds_read_b128 v[190:193], v231 offset:39936
	buffer_load_dwordx4 v199, s[16:19], s66 offen lds
	s_mov_b32 m0, s38
	s_nop 0
	buffer_load_dwordx4 v228, s[16:19], s66 offen lds
	s_waitcnt vmcnt(8)
	s_waitcnt lgkmcnt(0)
	s_setprio 1
	s_barrier
	v_mfma_f32_16x16x32_bf16 v[126:129], v[130:133], v[162:165], v[126:129]
	v_mfma_f32_16x16x32_bf16 v[122:125], v[138:141], v[162:165], v[122:125]
	v_mfma_f32_16x16x32_bf16 v[118:121], v[130:133], v[170:173], v[118:121]
	v_mfma_f32_16x16x32_bf16 v[114:117], v[138:141], v[170:173], v[114:117]
	v_mfma_f32_16x16x32_bf16 v[110:113], v[130:133], v[178:181], v[110:113]
	v_mfma_f32_16x16x32_bf16 v[106:109], v[138:141], v[178:181], v[106:109]
	v_mfma_f32_16x16x32_bf16 v[102:105], v[130:133], v[186:189], v[102:105]
	v_mfma_f32_16x16x32_bf16 v[98:101], v[138:141], v[186:189], v[98:101]
	v_mfma_f32_16x16x32_bf16 v[126:129], v[134:137], v[166:169], v[126:129]
	v_mfma_f32_16x16x32_bf16 v[122:125], v[142:145], v[166:169], v[122:125]
	v_mfma_f32_16x16x32_bf16 v[118:121], v[134:137], v[174:177], v[118:121]
	v_mfma_f32_16x16x32_bf16 v[114:117], v[142:145], v[174:177], v[114:117]
	v_mfma_f32_16x16x32_bf16 v[110:113], v[134:137], v[182:185], v[110:113]
	v_mfma_f32_16x16x32_bf16 v[106:109], v[142:145], v[182:185], v[106:109]
	v_mfma_f32_16x16x32_bf16 v[102:105], v[134:137], v[190:193], v[102:105]
	v_mfma_f32_16x16x32_bf16 v[98:101], v[142:145], v[190:193], v[98:101]
	v_mfma_f32_16x16x32_bf16 v[94:97], v[146:149], v[162:165], v[94:97]
	v_mfma_f32_16x16x32_bf16 v[90:93], v[154:157], v[162:165], v[90:93]
	v_mfma_f32_16x16x32_bf16 v[86:89], v[146:149], v[170:173], v[86:89]
	v_mfma_f32_16x16x32_bf16 v[82:85], v[154:157], v[170:173], v[82:85]
	v_mfma_f32_16x16x32_bf16 v[78:81], v[146:149], v[178:181], v[78:81]
	v_mfma_f32_16x16x32_bf16 v[74:77], v[154:157], v[178:181], v[74:77]
	v_mfma_f32_16x16x32_bf16 v[70:73], v[146:149], v[186:189], v[70:73]
	v_mfma_f32_16x16x32_bf16 v[66:69], v[154:157], v[186:189], v[66:69]
	v_mfma_f32_16x16x32_bf16 v[94:97], v[150:153], v[166:169], v[94:97]
	v_mfma_f32_16x16x32_bf16 v[90:93], v[158:161], v[166:169], v[90:93]
	v_mfma_f32_16x16x32_bf16 v[86:89], v[150:153], v[174:177], v[86:89]
	v_mfma_f32_16x16x32_bf16 v[82:85], v[158:161], v[174:177], v[82:85]
	v_mfma_f32_16x16x32_bf16 v[78:81], v[150:153], v[182:185], v[78:81]
	v_mfma_f32_16x16x32_bf16 v[74:77], v[158:161], v[182:185], v[74:77]
	v_mfma_f32_16x16x32_bf16 v[70:73], v[150:153], v[190:193], v[70:73]
	v_mfma_f32_16x16x32_bf16 v[66:69], v[158:161], v[190:193], v[66:69]
	s_barrier
	s_setprio 0
	s_mov_b32 m0, s39
	s_or_b32 s66, s64, 0x80
	ds_read_b128 v[162:165], v231 offset:49152
	ds_read_b128 v[166:169], v231 offset:50176
	ds_read_b128 v[170:173], v231 offset:51200
	ds_read_b128 v[174:177], v231 offset:52224
	ds_read_b128 v[178:181], v231 offset:53248
	ds_read_b128 v[182:185], v231 offset:54272
	ds_read_b128 v[186:189], v231 offset:55296
	ds_read_b128 v[190:193], v231 offset:56320
	buffer_load_dwordx4 v227, s[12:15], s66 offen lds
	s_mov_b32 m0, s40
	s_add_i32 s64, s64, 0x20080
	buffer_load_dwordx4 v229, s[12:15], s66 offen lds
	s_mov_b32 m0, s43
	s_nop 0
	buffer_load_dwordx4 v227, s[12:15], s64 offen lds
	s_mov_b32 m0, s42
	s_nop 0
	buffer_load_dwordx4 v229, s[12:15], s64 offen lds
	s_mov_b32 m0, s41
	s_nop 0
	buffer_load_dwordx4 v199, s[16:19], s65 offen lds
	s_mov_b32 m0, s33
	s_nop 0
	buffer_load_dwordx4 v228, s[16:19], s65 offen lds
	s_waitcnt vmcnt(8)
	s_waitcnt lgkmcnt(0)
	s_setprio 1
	s_barrier
	v_mfma_f32_16x16x32_bf16 v[62:65], v[130:133], v[162:165], v[62:65]
	v_mfma_f32_16x16x32_bf16 v[58:61], v[138:141], v[162:165], v[58:61]
	v_mfma_f32_16x16x32_bf16 v[54:57], v[130:133], v[170:173], v[54:57]
	v_mfma_f32_16x16x32_bf16 v[50:53], v[138:141], v[170:173], v[50:53]
	v_mfma_f32_16x16x32_bf16 v[46:49], v[130:133], v[178:181], v[46:49]
	v_mfma_f32_16x16x32_bf16 v[42:45], v[138:141], v[178:181], v[42:45]
	v_mfma_f32_16x16x32_bf16 v[38:41], v[130:133], v[186:189], v[38:41]
	v_mfma_f32_16x16x32_bf16 v[34:37], v[138:141], v[186:189], v[34:37]
	v_mfma_f32_16x16x32_bf16 v[62:65], v[134:137], v[166:169], v[62:65]
	v_mfma_f32_16x16x32_bf16 v[58:61], v[142:145], v[166:169], v[58:61]
	v_mfma_f32_16x16x32_bf16 v[54:57], v[134:137], v[174:177], v[54:57]
	v_mfma_f32_16x16x32_bf16 v[50:53], v[142:145], v[174:177], v[50:53]
	v_mfma_f32_16x16x32_bf16 v[46:49], v[134:137], v[182:185], v[46:49]
	v_mfma_f32_16x16x32_bf16 v[42:45], v[142:145], v[182:185], v[42:45]
	v_mfma_f32_16x16x32_bf16 v[38:41], v[134:137], v[190:193], v[38:41]
	v_mfma_f32_16x16x32_bf16 v[34:37], v[142:145], v[190:193], v[34:37]
	v_mfma_f32_16x16x32_bf16 v[30:33], v[146:149], v[162:165], v[30:33]
	v_mfma_f32_16x16x32_bf16 v[26:29], v[154:157], v[162:165], v[26:29]
	v_mfma_f32_16x16x32_bf16 v[22:25], v[146:149], v[170:173], v[22:25]
	v_mfma_f32_16x16x32_bf16 v[18:21], v[154:157], v[170:173], v[18:21]
	v_mfma_f32_16x16x32_bf16 v[14:17], v[146:149], v[178:181], v[14:17]
	v_mfma_f32_16x16x32_bf16 v[10:13], v[154:157], v[178:181], v[10:13]
	v_mfma_f32_16x16x32_bf16 v[6:9], v[146:149], v[186:189], v[6:9]
	v_mfma_f32_16x16x32_bf16 v[2:5], v[154:157], v[186:189], v[2:5]
	v_mfma_f32_16x16x32_bf16 v[30:33], v[150:153], v[166:169], v[30:33]
	v_mfma_f32_16x16x32_bf16 v[26:29], v[158:161], v[166:169], v[26:29]
	v_mfma_f32_16x16x32_bf16 v[22:25], v[150:153], v[174:177], v[22:25]
	v_mfma_f32_16x16x32_bf16 v[18:21], v[158:161], v[174:177], v[18:21]
	v_mfma_f32_16x16x32_bf16 v[14:17], v[150:153], v[182:185], v[14:17]
	v_mfma_f32_16x16x32_bf16 v[10:13], v[158:161], v[182:185], v[10:13]
	v_mfma_f32_16x16x32_bf16 v[6:9], v[150:153], v[190:193], v[6:9]
	v_mfma_f32_16x16x32_bf16 v[2:5], v[158:161], v[190:193], v[2:5]
	s_barrier
	s_setprio 0
	s_add_i32 s63, s63, 2
	s_addk_i32 s2, 0x100
	s_addk_i32 s3, 0x100
	s_cmp_gt_u32 s63, 5
	s_cbranch_scc0 .LBB0_779
	v_readlane_b32 s2, v251, 45
	v_readlane_b32 s3, v251, 46
	s_and_b64 vcc, exec, s[2:3]
	s_cbranch_vccz .LBB0_782
	s_barrier

; template <class Epi, bool ALIGN_EPI, bool SP2, class Hook>
; __device__ __forceinline__ void gemm_phase(LAS unsigned char* lds, const Gemm g, const StaticOrder& S, const Epi& E, Acc& acc, const bool fresh, const Hook& H, const int wave_id) {
;     ...
;         for (int t = t0; t < nt; t += 2) {
;             const bool last = (t == nt - 2);
;             const Src a1 = cA + (size_t)(t + 1) * kstep;
;             const Src a2 = last ? nA : cA + (size_t)(t + 2) * kstep, b2 = last ? nB : cB + (size_t)(t + 2) * kstep;
;             const Src a3 = a2 + kstep, b3 = b2 + kstep;
.LBB0_903:
	v_add_u32_e32 v70, 0x10000, v216
	v_add_u32_e32 v118, 0x14000, v216
	ds_read_b128 v[34:37], v70
	ds_read_b128 v[46:49], v70 offset:1024
	ds_read_b128 v[58:61], v70 offset:2048
	ds_read_b128 v[70:73], v70 offset:3072
	ds_read_b128 v[82:85], v118
	ds_read_b128 v[94:97], v118 offset:1024
	ds_read_b128 v[106:109], v118 offset:2048
	ds_read_b128 v[118:121], v118 offset:3072
	s_add_i32 s12, s55, 0xfffe0080
	s_cmp_eq_u32 s57, 4
	s_cselect_b32 s60, s53, s12
	s_cselect_b32 s13, s29, s77
	s_cselect_b32 s12, s28, s76
	s_cselect_b32 s15, s31, s35
	s_cselect_b32 s14, s30, s34
	s_cselect_b32 s58, s54, s56
	s_cselect_b32 s16, s2, s8
	s_cselect_b32 s17, s3, s9
	s_cselect_b32 s18, s26, s10
	s_cselect_b32 s19, s27, s11
	s_or_b32 s59, s60, 0x80
	s_mov_b32 m0, s45
	ds_read_b128 v[130:133], v217
	ds_read_b128 v[142:145], v217 offset:1024
	ds_read_b128 v[154:157], v217 offset:2048
	ds_read_b128 v[166:169], v217 offset:3072
	ds_read_b128 v[174:177], v217 offset:4096
	ds_read_b128 v[182:185], v217 offset:5120
	ds_read_b128 v[186:189], v217 offset:6144
	ds_read_b128 v[190:193], v217 offset:7168
	buffer_load_dwordx4 v0, s[8:11], s55 offen lds
	s_mov_b32 m0, s46
	s_nop 0
	buffer_load_dwordx4 v214, s[8:11], s55 offen lds
	s_waitcnt vmcnt(8)
	s_waitcnt lgkmcnt(0)
	s_setprio 1
	s_barrier
	v_mfma_f32_16x16x32_bf16 v[178:181], v[34:37], v[130:133], v[178:181]
	v_mfma_f32_16x16x32_bf16 v[170:173], v[58:61], v[130:133], v[170:173]
	v_mfma_f32_16x16x32_bf16 v[150:153], v[34:37], v[154:157], v[150:153]
	v_mfma_f32_16x16x32_bf16 v[146:149], v[58:61], v[154:157], v[146:149]
	v_mfma_f32_16x16x32_bf16 v[126:129], v[34:37], v[174:177], v[126:129]
	v_mfma_f32_16x16x32_bf16 v[122:125], v[58:61], v[174:177], v[122:125]
	v_mfma_f32_16x16x32_bf16 v[102:105], v[34:37], v[186:189], v[102:105]
	v_mfma_f32_16x16x32_bf16 v[98:101], v[58:61], v[186:189], v[98:101]
	v_mfma_f32_16x16x32_bf16 v[178:181], v[46:49], v[142:145], v[178:181]
	v_mfma_f32_16x16x32_bf16 v[170:173], v[70:73], v[142:145], v[170:173]
	v_mfma_f32_16x16x32_bf16 v[150:153], v[46:49], v[166:169], v[150:153]
	v_mfma_f32_16x16x32_bf16 v[146:149], v[70:73], v[166:169], v[146:149]
	v_mfma_f32_16x16x32_bf16 v[126:129], v[46:49], v[182:185], v[126:129]
	v_mfma_f32_16x16x32_bf16 v[122:125], v[70:73], v[182:185], v[122:125]
	v_mfma_f32_16x16x32_bf16 v[102:105], v[46:49], v[190:193], v[102:105]
	v_mfma_f32_16x16x32_bf16 v[98:101], v[70:73], v[190:193], v[98:101]
	v_mfma_f32_16x16x32_bf16 v[162:165], v[82:85], v[130:133], v[162:165]
	v_mfma_f32_16x16x32_bf16 v[138:141], v[82:85], v[154:157], v[138:141]
	v_mfma_f32_16x16x32_bf16 v[134:137], v[106:109], v[154:157], v[134:137]
	v_mfma_f32_16x16x32_bf16 v[114:117], v[82:85], v[174:177], v[114:117]
	v_mfma_f32_16x16x32_bf16 v[110:113], v[106:109], v[174:177], v[110:113]
	v_mfma_f32_16x16x32_bf16 v[90:93], v[82:85], v[186:189], v[90:93]
	v_mfma_f32_16x16x32_bf16 v[86:89], v[106:109], v[186:189], v[86:89]
	v_mfma_f32_16x16x32_bf16 v[162:165], v[94:97], v[142:145], v[162:165]
	v_mfma_f32_16x16x32_bf16 v[130:133], v[106:109], v[130:133], v[158:161]
	v_mfma_f32_16x16x32_bf16 v[138:141], v[94:97], v[166:169], v[138:141]
	v_mfma_f32_16x16x32_bf16 v[134:137], v[118:121], v[166:169], v[134:137]
	v_mfma_f32_16x16x32_bf16 v[114:117], v[94:97], v[182:185], v[114:117]
	v_mfma_f32_16x16x32_bf16 v[110:113], v[118:121], v[182:185], v[110:113]
	v_mfma_f32_16x16x32_bf16 v[90:93], v[94:97], v[190:193], v[90:93]
	v_mfma_f32_16x16x32_bf16 v[86:89], v[118:121], v[190:193], v[86:89]
	v_mfma_f32_16x16x32_bf16 v[130:133], v[118:121], v[142:145], v[130:133]
	s_barrier
	s_setprio 0
	s_mov_b32 m0, s92
	ds_read_b128 v[142:145], v217 offset:16384
	ds_read_b128 v[154:157], v217 offset:17408
	ds_read_b128 v[158:161], v217 offset:18432
	ds_read_b128 v[166:169], v217 offset:19456
	ds_read_b128 v[174:177], v217 offset:20480
	ds_read_b128 v[182:185], v217 offset:21504
	ds_read_b128 v[186:189], v217 offset:22528
	ds_read_b128 v[190:193], v217 offset:23552
	buffer_load_dwordx4 v199, s[12:15], s58 offen lds
	s_mov_b32 m0, s93
	s_add_i32 s61, s58, 0x20000
	buffer_load_dwordx4 v215, s[12:15], s58 offen lds
	s_mov_b32 m0, s94
	s_nop 0
	buffer_load_dwordx4 v199, s[12:15], s61 offen lds
	s_mov_b32 m0, s95
	s_nop 0
	buffer_load_dwordx4 v215, s[12:15], s61 offen lds
	s_mov_b32 m0, s44
	s_nop 0
	buffer_load_dwordx4 v0, s[16:19], s60 offen lds
	s_mov_b32 m0, s36
	s_nop 0
	buffer_load_dwordx4 v214, s[16:19], s60 offen lds
	s_waitcnt vmcnt(8)
	s_waitcnt lgkmcnt(0)
	s_setprio 1
	s_barrier
	v_mfma_f32_16x16x32_bf16 v[78:81], v[34:37], v[142:145], v[78:81]
	v_mfma_f32_16x16x32_bf16 v[74:77], v[58:61], v[142:145], v[74:77]
	v_mfma_f32_16x16x32_bf16 v[54:57], v[34:37], v[158:161], v[54:57]
	v_mfma_f32_16x16x32_bf16 v[50:53], v[58:61], v[158:161], v[50:53]
	v_mfma_f32_16x16x32_bf16 v[30:33], v[34:37], v[174:177], v[30:33]
	v_mfma_f32_16x16x32_bf16 v[26:29], v[58:61], v[174:177], v[26:29]
	v_mfma_f32_16x16x32_bf16 v[14:17], v[34:37], v[186:189], v[14:17]
	v_mfma_f32_16x16x32_bf16 v[10:13], v[58:61], v[186:189], v[10:13]
	v_mfma_f32_16x16x32_bf16 v[78:81], v[46:49], v[154:157], v[78:81]
	v_mfma_f32_16x16x32_bf16 v[74:77], v[70:73], v[154:157], v[74:77]
	v_mfma_f32_16x16x32_bf16 v[54:57], v[46:49], v[166:169], v[54:57]
	v_mfma_f32_16x16x32_bf16 v[50:53], v[70:73], v[166:169], v[50:53]
	v_mfma_f32_16x16x32_bf16 v[30:33], v[46:49], v[182:185], v[30:33]
	v_mfma_f32_16x16x32_bf16 v[26:29], v[70:73], v[182:185], v[26:29]
	v_mfma_f32_16x16x32_bf16 v[14:17], v[46:49], v[190:193], v[14:17]
	v_mfma_f32_16x16x32_bf16 v[10:13], v[70:73], v[190:193], v[10:13]
	v_mfma_f32_16x16x32_bf16 v[42:45], v[82:85], v[158:161], v[42:45]
	v_mfma_f32_16x16x32_bf16 v[38:41], v[106:109], v[158:161], v[38:41]
	v_mfma_f32_16x16x32_bf16 v[22:25], v[82:85], v[174:177], v[22:25]
	v_mfma_f32_16x16x32_bf16 v[18:21], v[106:109], v[174:177], v[18:21]
	v_mfma_f32_16x16x32_bf16 v[6:9], v[82:85], v[186:189], v[6:9]
	v_mfma_f32_16x16x32_bf16 v[2:5], v[106:109], v[186:189], v[2:5]
	v_mfma_f32_16x16x32_bf16 v[34:37], v[82:85], v[142:145], v[66:69]
	v_mfma_f32_16x16x32_bf16 v[46:49], v[106:109], v[142:145], v[62:65]
	v_mfma_f32_16x16x32_bf16 v[42:45], v[94:97], v[166:169], v[42:45]
	v_mfma_f32_16x16x32_bf16 v[38:41], v[118:121], v[166:169], v[38:41]
	v_mfma_f32_16x16x32_bf16 v[22:25], v[94:97], v[182:185], v[22:25]
	v_mfma_f32_16x16x32_bf16 v[18:21], v[118:121], v[182:185], v[18:21]
	v_mfma_f32_16x16x32_bf16 v[6:9], v[94:97], v[190:193], v[6:9]
	v_mfma_f32_16x16x32_bf16 v[2:5], v[118:121], v[190:193], v[2:5]
	v_mfma_f32_16x16x32_bf16 v[34:37], v[94:97], v[154:157], v[34:37]
	v_mfma_f32_16x16x32_bf16 v[46:49], v[118:121], v[154:157], v[46:49]
	s_barrier
; #define PG8_BAR __builtin_amdgcn_s_barrier()
; template <class Epi, bool ALIGN_EPI, bool SP2, class Hook>
; __device__ __forceinline__ void gemm_phase(LAS unsigned char* lds, const Gemm g, const StaticOrder& S, const Epi& E, Acc& acc, const bool fresh, const Hook& H, const int wave_id) {
;     ...
;         if constexpr (ALIGN_EPI) { if (wr == 0) PG8_BAR; }
	s_setprio 0
	v_add_u32_e32 v70, 0x18000, v216
	v_add_u32_e32 v118, 0x1c000, v216
	ds_read_b128 v[58:61], v70
	ds_read_b128 v[62:65], v70 offset:1024
	ds_read_b128 v[66:69], v70 offset:2048
	ds_read_b128 v[70:73], v70 offset:3072
	ds_read_b128 v[82:85], v118
	ds_read_b128 v[94:97], v118 offset:1024
	ds_read_b128 v[106:109], v118 offset:2048
	ds_read_b128 v[118:121], v118 offset:3072
	s_add_i32 s60, s60, 0x20000
	s_mov_b32 m0, s37
	ds_read_b128 v[142:145], v217 offset:32768
	ds_read_b128 v[154:157], v217 offset:33792
	ds_read_b128 v[166:169], v217 offset:34816
	ds_read_b128 v[174:177], v217 offset:35840
	ds_read_b128 v[182:185], v217 offset:36864
	ds_read_b128 v[186:189], v217 offset:37888
	ds_read_b128 v[190:193], v217 offset:38912
	ds_read_b128 v[194:197], v217 offset:39936
	buffer_load_dwordx4 v0, s[16:19], s60 offen lds
	s_mov_b32 m0, s38
	s_nop 0
	buffer_load_dwordx4 v214, s[16:19], s60 offen lds
	s_waitcnt vmcnt(8)
	s_waitcnt lgkmcnt(0)
	s_setprio 1
	s_barrier
	v_mfma_f32_16x16x32_bf16 v[158:161], v[58:61], v[142:145], v[178:181]
	v_mfma_f32_16x16x32_bf16 v[178:181], v[62:65], v[154:157], v[158:161]
	v_mfma_f32_16x16x32_bf16 v[158:161], v[66:69], v[142:145], v[170:173]
	v_mfma_f32_16x16x32_bf16 v[150:153], v[58:61], v[166:169], v[150:153]
	v_mfma_f32_16x16x32_bf16 v[146:149], v[66:69], v[166:169], v[146:149]
	v_mfma_f32_16x16x32_bf16 v[126:129], v[58:61], v[182:185], v[126:129]
	v_mfma_f32_16x16x32_bf16 v[122:125], v[66:69], v[182:185], v[122:125]
	v_mfma_f32_16x16x32_bf16 v[102:105], v[58:61], v[190:193], v[102:105]
	v_mfma_f32_16x16x32_bf16 v[98:101], v[66:69], v[190:193], v[98:101]
	v_mfma_f32_16x16x32_bf16 v[170:173], v[70:73], v[154:157], v[158:161]
	v_mfma_f32_16x16x32_bf16 v[150:153], v[62:65], v[174:177], v[150:153]
	v_mfma_f32_16x16x32_bf16 v[146:149], v[70:73], v[174:177], v[146:149]
	v_mfma_f32_16x16x32_bf16 v[126:129], v[62:65], v[186:189], v[126:129]
	v_mfma_f32_16x16x32_bf16 v[122:125], v[70:73], v[186:189], v[122:125]
	v_mfma_f32_16x16x32_bf16 v[102:105], v[62:65], v[194:197], v[102:105]
	v_mfma_f32_16x16x32_bf16 v[98:101], v[70:73], v[194:197], v[98:101]
	v_mfma_f32_16x16x32_bf16 v[158:161], v[82:85], v[142:145], v[162:165]
	v_mfma_f32_16x16x32_bf16 v[130:133], v[106:109], v[142:145], v[130:133]
	v_mfma_f32_16x16x32_bf16 v[162:165], v[94:97], v[154:157], v[158:161]
	v_mfma_f32_16x16x32_bf16 v[158:161], v[118:121], v[154:157], v[130:133]
	v_mfma_f32_16x16x32_bf16 v[130:133], v[82:85], v[166:169], v[138:141]
	v_mfma_f32_16x16x32_bf16 v[138:141], v[94:97], v[174:177], v[130:133]
	v_mfma_f32_16x16x32_bf16 v[130:133], v[106:109], v[166:169], v[134:137]
	v_mfma_f32_16x16x32_bf16 v[114:117], v[82:85], v[182:185], v[114:117]
	v_mfma_f32_16x16x32_bf16 v[110:113], v[106:109], v[182:185], v[110:113]
	v_mfma_f32_16x16x32_bf16 v[90:93], v[82:85], v[190:193], v[90:93]
	v_mfma_f32_16x16x32_bf16 v[86:89], v[106:109], v[190:193], v[86:89]
	v_mfma_f32_16x16x32_bf16 v[134:137], v[118:121], v[174:177], v[130:133]
	v_mfma_f32_16x16x32_bf16 v[114:117], v[94:97], v[186:189], v[114:117]
	v_mfma_f32_16x16x32_bf16 v[110:113], v[118:121], v[186:189], v[110:113]
	v_mfma_f32_16x16x32_bf16 v[90:93], v[94:97], v[194:197], v[90:93]
	v_mfma_f32_16x16x32_bf16 v[86:89], v[118:121], v[194:197], v[86:89]
	s_barrier
	s_setprio 0
	s_mov_b32 m0, s39
	s_or_b32 s60, s58, 0x80
	ds_read_b128 v[130:133], v217 offset:49152
	ds_read_b128 v[142:145], v217 offset:50176
	ds_read_b128 v[154:157], v217 offset:51200
	ds_read_b128 v[166:169], v217 offset:52224
	ds_read_b128 v[174:177], v217 offset:53248
	ds_read_b128 v[182:185], v217 offset:54272
	ds_read_b128 v[186:189], v217 offset:55296
	ds_read_b128 v[190:193], v217 offset:56320
	buffer_load_dwordx4 v199, s[12:15], s60 offen lds
	s_mov_b32 m0, s40
	s_add_i32 s58, s58, 0x20080
	buffer_load_dwordx4 v215, s[12:15], s60 offen lds
	s_mov_b32 m0, s43
	s_nop 0
	buffer_load_dwordx4 v199, s[12:15], s58 offen lds
	s_mov_b32 m0, s42
	s_nop 0
	buffer_load_dwordx4 v215, s[12:15], s58 offen lds
	s_mov_b32 m0, s41
	s_nop 0
	buffer_load_dwordx4 v0, s[16:19], s59 offen lds
	s_mov_b32 m0, s33
	s_nop 0
	buffer_load_dwordx4 v214, s[16:19], s59 offen lds
	s_waitcnt vmcnt(8)
	s_waitcnt lgkmcnt(0)
	s_setprio 1
	s_barrier
	v_mfma_f32_16x16x32_bf16 v[78:81], v[58:61], v[130:133], v[78:81]
	v_mfma_f32_16x16x32_bf16 v[74:77], v[66:69], v[130:133], v[74:77]
	v_mfma_f32_16x16x32_bf16 v[54:57], v[58:61], v[154:157], v[54:57]
	v_mfma_f32_16x16x32_bf16 v[50:53], v[66:69], v[154:157], v[50:53]
	v_mfma_f32_16x16x32_bf16 v[30:33], v[58:61], v[174:177], v[30:33]
	v_mfma_f32_16x16x32_bf16 v[26:29], v[66:69], v[174:177], v[26:29]
	v_mfma_f32_16x16x32_bf16 v[14:17], v[58:61], v[186:189], v[14:17]
	v_mfma_f32_16x16x32_bf16 v[10:13], v[66:69], v[186:189], v[10:13]
	v_mfma_f32_16x16x32_bf16 v[78:81], v[62:65], v[142:145], v[78:81]
	v_mfma_f32_16x16x32_bf16 v[74:77], v[70:73], v[142:145], v[74:77]
	v_mfma_f32_16x16x32_bf16 v[54:57], v[62:65], v[166:169], v[54:57]
	v_mfma_f32_16x16x32_bf16 v[50:53], v[70:73], v[166:169], v[50:53]
	v_mfma_f32_16x16x32_bf16 v[30:33], v[62:65], v[182:185], v[30:33]
	v_mfma_f32_16x16x32_bf16 v[26:29], v[70:73], v[182:185], v[26:29]
	v_mfma_f32_16x16x32_bf16 v[14:17], v[62:65], v[190:193], v[14:17]
	v_mfma_f32_16x16x32_bf16 v[10:13], v[70:73], v[190:193], v[10:13]
	v_mfma_f32_16x16x32_bf16 v[34:37], v[82:85], v[130:133], v[34:37]
	v_mfma_f32_16x16x32_bf16 v[66:69], v[94:97], v[142:145], v[34:37]
	v_mfma_f32_16x16x32_bf16 v[34:37], v[106:109], v[130:133], v[46:49]
	v_mfma_f32_16x16x32_bf16 v[62:65], v[118:121], v[142:145], v[34:37]
	v_mfma_f32_16x16x32_bf16 v[34:37], v[82:85], v[154:157], v[42:45]
	v_mfma_f32_16x16x32_bf16 v[42:45], v[94:97], v[166:169], v[34:37]
	v_mfma_f32_16x16x32_bf16 v[34:37], v[106:109], v[154:157], v[38:41]
	v_mfma_f32_16x16x32_bf16 v[22:25], v[82:85], v[174:177], v[22:25]
	v_mfma_f32_16x16x32_bf16 v[18:21], v[106:109], v[174:177], v[18:21]
	v_mfma_f32_16x16x32_bf16 v[6:9], v[82:85], v[186:189], v[6:9]
	v_mfma_f32_16x16x32_bf16 v[2:5], v[106:109], v[186:189], v[2:5]
	v_mfma_f32_16x16x32_bf16 v[38:41], v[118:121], v[166:169], v[34:37]
	v_mfma_f32_16x16x32_bf16 v[22:25], v[94:97], v[182:185], v[22:25]
	v_mfma_f32_16x16x32_bf16 v[18:21], v[118:121], v[182:185], v[18:21]
	v_mfma_f32_16x16x32_bf16 v[6:9], v[94:97], v[190:193], v[6:9]
	v_mfma_f32_16x16x32_bf16 v[2:5], v[118:121], v[190:193], v[2:5]
	s_barrier
	s_setprio 0
	s_add_i32 s57, s57, 2
	s_addk_i32 s55, 0x100
	s_addk_i32 s56, 0x100
	s_cmp_gt_u32 s57, 5
	s_cbranch_scc0 .LBB0_903
	v_readlane_b32 s8, v251, 45
	v_readlane_b32 s9, v251, 46
	s_and_b64 vcc, exec, s[8:9]
	s_cbranch_vccz .LBB0_906
	s_barrier

; template <class Epi, bool ALIGN_EPI, bool SP2, class Hook>
; __device__ __forceinline__ void gemm_phase(LAS unsigned char* lds, const Gemm g, const StaticOrder& S, const Epi& E, Acc& acc, const bool fresh, const Hook& H, const int wave_id) {
;     ...
;         for (int t = t0; t < nt; t += 2) {
;             const bool last = (t == nt - 2);
;             const Src a1 = cA + (size_t)(t + 1) * kstep;
;             const Src a2 = last ? nA : cA + (size_t)(t + 2) * kstep, b2 = last ? nB : cB + (size_t)(t + 2) * kstep;
;             const Src a3 = a2 + kstep, b3 = b2 + kstep;
.LBB0_1029:
.LBB0_1030:
	v_add_u32_e32 v0, 0x10000, v230
	s_waitcnt vmcnt(0)
	ds_read_b128 v[130:133], v0
	ds_read_b128 v[134:137], v0 offset:1024
	ds_read_b128 v[138:141], v0 offset:2048
	ds_read_b128 v[142:145], v0 offset:3072
	v_add_u32_e32 v0, 0x14000, v230
	ds_read_b128 v[146:149], v0
	ds_read_b128 v[150:153], v0 offset:1024
	ds_read_b128 v[154:157], v0 offset:2048
	ds_read_b128 v[158:161], v0 offset:3072
	s_lshl_b32 s55, s20, 7
	s_add_i32 s18, s73, s55
	s_and_b64 s[12:13], s[16:17], exec
	s_cselect_b32 s13, s31, s9
	s_cselect_b32 s12, s30, s8
	s_cselect_b32 s15, s35, s11
	s_cselect_b32 s14, s34, s10
	s_cselect_b32 s56, s68, s18
	s_add_i32 s21, s74, s55
	s_and_b64 s[16:17], s[16:17], exec
	s_cselect_b32 s54, s69, s21
	s_cselect_b32 s17, s51, s77
	s_cselect_b32 s16, s50, s76
	s_cselect_b32 s19, s53, s7
	s_cselect_b32 s18, s52, s6
	s_or_b32 s21, s56, 0x80
	s_or_b32 s57, s54, 0x80
	s_add_i32 s55, s55, s75
	s_mov_b32 m0, s45
	ds_read_b128 v[162:165], v231
	ds_read_b128 v[166:169], v231 offset:1024
	ds_read_b128 v[170:173], v231 offset:2048
	ds_read_b128 v[174:177], v231 offset:3072
	ds_read_b128 v[178:181], v231 offset:4096
	ds_read_b128 v[182:185], v231 offset:5120
	ds_read_b128 v[186:189], v231 offset:6144
	ds_read_b128 v[190:193], v231 offset:7168
	buffer_load_dwordx4 v199, s[8:11], s55 offen lds
	s_mov_b32 m0, s46
	s_nop 0
	buffer_load_dwordx4 v228, s[8:11], s55 offen lds
	s_waitcnt vmcnt(8)
	s_waitcnt lgkmcnt(0)
	s_setprio 1
	s_barrier
	v_mfma_f32_16x16x32_bf16 v[126:129], v[130:133], v[162:165], v[126:129]
	v_mfma_f32_16x16x32_bf16 v[122:125], v[138:141], v[162:165], v[122:125]
	v_mfma_f32_16x16x32_bf16 v[118:121], v[130:133], v[170:173], v[118:121]
	v_mfma_f32_16x16x32_bf16 v[114:117], v[138:141], v[170:173], v[114:117]
	v_mfma_f32_16x16x32_bf16 v[110:113], v[130:133], v[178:181], v[110:113]
	v_mfma_f32_16x16x32_bf16 v[106:109], v[138:141], v[178:181], v[106:109]
	v_mfma_f32_16x16x32_bf16 v[102:105], v[130:133], v[186:189], v[102:105]
	v_mfma_f32_16x16x32_bf16 v[98:101], v[138:141], v[186:189], v[98:101]
	v_mfma_f32_16x16x32_bf16 v[126:129], v[134:137], v[166:169], v[126:129]
	v_mfma_f32_16x16x32_bf16 v[122:125], v[142:145], v[166:169], v[122:125]
	v_mfma_f32_16x16x32_bf16 v[118:121], v[134:137], v[174:177], v[118:121]
	v_mfma_f32_16x16x32_bf16 v[114:117], v[142:145], v[174:177], v[114:117]
	v_mfma_f32_16x16x32_bf16 v[110:113], v[134:137], v[182:185], v[110:113]
	v_mfma_f32_16x16x32_bf16 v[106:109], v[142:145], v[182:185], v[106:109]
	v_mfma_f32_16x16x32_bf16 v[102:105], v[134:137], v[190:193], v[102:105]
	v_mfma_f32_16x16x32_bf16 v[98:101], v[142:145], v[190:193], v[98:101]
	v_mfma_f32_16x16x32_bf16 v[94:97], v[146:149], v[162:165], v[94:97]
	v_mfma_f32_16x16x32_bf16 v[90:93], v[154:157], v[162:165], v[90:93]
	v_mfma_f32_16x16x32_bf16 v[86:89], v[146:149], v[170:173], v[86:89]
	v_mfma_f32_16x16x32_bf16 v[82:85], v[154:157], v[170:173], v[82:85]
	v_mfma_f32_16x16x32_bf16 v[78:81], v[146:149], v[178:181], v[78:81]
	v_mfma_f32_16x16x32_bf16 v[74:77], v[154:157], v[178:181], v[74:77]
	v_mfma_f32_16x16x32_bf16 v[70:73], v[146:149], v[186:189], v[70:73]
	v_mfma_f32_16x16x32_bf16 v[66:69], v[154:157], v[186:189], v[66:69]
	v_mfma_f32_16x16x32_bf16 v[94:97], v[150:153], v[166:169], v[94:97]
	v_mfma_f32_16x16x32_bf16 v[90:93], v[158:161], v[166:169], v[90:93]
	v_mfma_f32_16x16x32_bf16 v[86:89], v[150:153], v[174:177], v[86:89]
	v_mfma_f32_16x16x32_bf16 v[82:85], v[158:161], v[174:177], v[82:85]
	v_mfma_f32_16x16x32_bf16 v[78:81], v[150:153], v[182:185], v[78:81]
	v_mfma_f32_16x16x32_bf16 v[74:77], v[158:161], v[182:185], v[74:77]
	v_mfma_f32_16x16x32_bf16 v[70:73], v[150:153], v[190:193], v[70:73]
	v_mfma_f32_16x16x32_bf16 v[66:69], v[158:161], v[190:193], v[66:69]
	s_barrier
	s_setprio 0
	s_mov_b32 m0, s92
	ds_read_b128 v[162:165], v231 offset:16384
	ds_read_b128 v[166:169], v231 offset:17408
	ds_read_b128 v[170:173], v231 offset:18432
	ds_read_b128 v[174:177], v231 offset:19456
	ds_read_b128 v[178:181], v231 offset:20480
	ds_read_b128 v[182:185], v231 offset:21504
	ds_read_b128 v[186:189], v231 offset:22528
	ds_read_b128 v[190:193], v231 offset:23552
	buffer_load_dwordx4 v227, s[16:19], s54 offen lds
	s_mov_b32 m0, s93
	s_add_i32 s55, s54, 0x20000
	buffer_load_dwordx4 v229, s[16:19], s54 offen lds
	s_mov_b32 m0, s94
	s_nop 0
	buffer_load_dwordx4 v227, s[16:19], s55 offen lds
	s_mov_b32 m0, s95
	s_nop 0
	buffer_load_dwordx4 v229, s[16:19], s55 offen lds
	s_mov_b32 m0, s44
	s_nop 0
	buffer_load_dwordx4 v199, s[12:15], s56 offen lds
	s_mov_b32 m0, s36
	s_nop 0
	buffer_load_dwordx4 v228, s[12:15], s56 offen lds
	s_waitcnt vmcnt(8)
	s_waitcnt lgkmcnt(0)
	s_setprio 1
	s_barrier
	v_mfma_f32_16x16x32_bf16 v[62:65], v[130:133], v[162:165], v[62:65]
	v_mfma_f32_16x16x32_bf16 v[58:61], v[138:141], v[162:165], v[58:61]
	v_mfma_f32_16x16x32_bf16 v[54:57], v[130:133], v[170:173], v[54:57]
	v_mfma_f32_16x16x32_bf16 v[50:53], v[138:141], v[170:173], v[50:53]
	v_mfma_f32_16x16x32_bf16 v[46:49], v[130:133], v[178:181], v[46:49]
	v_mfma_f32_16x16x32_bf16 v[42:45], v[138:141], v[178:181], v[42:45]
	v_mfma_f32_16x16x32_bf16 v[38:41], v[130:133], v[186:189], v[38:41]
	v_mfma_f32_16x16x32_bf16 v[34:37], v[138:141], v[186:189], v[34:37]
	v_mfma_f32_16x16x32_bf16 v[62:65], v[134:137], v[166:169], v[62:65]
	v_mfma_f32_16x16x32_bf16 v[58:61], v[142:145], v[166:169], v[58:61]
	v_mfma_f32_16x16x32_bf16 v[54:57], v[134:137], v[174:177], v[54:57]
	v_mfma_f32_16x16x32_bf16 v[50:53], v[142:145], v[174:177], v[50:53]
	v_mfma_f32_16x16x32_bf16 v[46:49], v[134:137], v[182:185], v[46:49]
	v_mfma_f32_16x16x32_bf16 v[42:45], v[142:145], v[182:185], v[42:45]
	v_mfma_f32_16x16x32_bf16 v[38:41], v[134:137], v[190:193], v[38:41]
	v_mfma_f32_16x16x32_bf16 v[34:37], v[142:145], v[190:193], v[34:37]
	v_mfma_f32_16x16x32_bf16 v[30:33], v[146:149], v[162:165], v[30:33]
	v_mfma_f32_16x16x32_bf16 v[26:29], v[154:157], v[162:165], v[26:29]
	v_mfma_f32_16x16x32_bf16 v[22:25], v[146:149], v[170:173], v[22:25]
	v_mfma_f32_16x16x32_bf16 v[18:21], v[154:157], v[170:173], v[18:21]
	v_mfma_f32_16x16x32_bf16 v[14:17], v[146:149], v[178:181], v[14:17]
	v_mfma_f32_16x16x32_bf16 v[10:13], v[154:157], v[178:181], v[10:13]
	v_mfma_f32_16x16x32_bf16 v[6:9], v[146:149], v[186:189], v[6:9]
	v_mfma_f32_16x16x32_bf16 v[2:5], v[154:157], v[186:189], v[2:5]
	v_mfma_f32_16x16x32_bf16 v[30:33], v[150:153], v[166:169], v[30:33]
	v_mfma_f32_16x16x32_bf16 v[26:29], v[158:161], v[166:169], v[26:29]
	v_mfma_f32_16x16x32_bf16 v[22:25], v[150:153], v[174:177], v[22:25]
	v_mfma_f32_16x16x32_bf16 v[18:21], v[158:161], v[174:177], v[18:21]
	v_mfma_f32_16x16x32_bf16 v[14:17], v[150:153], v[182:185], v[14:17]
	v_mfma_f32_16x16x32_bf16 v[10:13], v[158:161], v[182:185], v[10:13]
	v_mfma_f32_16x16x32_bf16 v[6:9], v[150:153], v[190:193], v[6:9]
	v_mfma_f32_16x16x32_bf16 v[2:5], v[158:161], v[190:193], v[2:5]
	s_barrier
	s_setprio 0
	v_add_u32_e32 v0, 0x18000, v230
	ds_read_b128 v[130:133], v0
	ds_read_b128 v[134:137], v0 offset:1024
	ds_read_b128 v[138:141], v0 offset:2048
	ds_read_b128 v[142:145], v0 offset:3072
	v_add_u32_e32 v0, 0x1c000, v230
	ds_read_b128 v[146:149], v0
	ds_read_b128 v[150:153], v0 offset:1024
	ds_read_b128 v[154:157], v0 offset:2048
	ds_read_b128 v[158:161], v0 offset:3072
	s_add_i32 s56, s56, 0x20000
	s_mov_b32 m0, s37
	ds_read_b128 v[162:165], v231 offset:32768
	ds_read_b128 v[166:169], v231 offset:33792
	ds_read_b128 v[170:173], v231 offset:34816
	ds_read_b128 v[174:177], v231 offset:35840
	ds_read_b128 v[178:181], v231 offset:36864
	ds_read_b128 v[182:185], v231 offset:37888
	ds_read_b128 v[186:189], v231 offset:38912
	ds_read_b128 v[190:193], v231 offset:39936
	buffer_load_dwordx4 v199, s[12:15], s56 offen lds
	s_mov_b32 m0, s38
	s_nop 0
	buffer_load_dwordx4 v228, s[12:15], s56 offen lds
	s_waitcnt vmcnt(8)
	s_waitcnt lgkmcnt(0)
	s_setprio 1
	s_barrier
	v_mfma_f32_16x16x32_bf16 v[126:129], v[130:133], v[162:165], v[126:129]
	v_mfma_f32_16x16x32_bf16 v[122:125], v[138:141], v[162:165], v[122:125]
	v_mfma_f32_16x16x32_bf16 v[118:121], v[130:133], v[170:173], v[118:121]
	v_mfma_f32_16x16x32_bf16 v[114:117], v[138:141], v[170:173], v[114:117]
	v_mfma_f32_16x16x32_bf16 v[110:113], v[130:133], v[178:181], v[110:113]
	v_mfma_f32_16x16x32_bf16 v[106:109], v[138:141], v[178:181], v[106:109]
	v_mfma_f32_16x16x32_bf16 v[102:105], v[130:133], v[186:189], v[102:105]
	v_mfma_f32_16x16x32_bf16 v[98:101], v[138:141], v[186:189], v[98:101]
	v_mfma_f32_16x16x32_bf16 v[126:129], v[134:137], v[166:169], v[126:129]
	v_mfma_f32_16x16x32_bf16 v[122:125], v[142:145], v[166:169], v[122:125]
	v_mfma_f32_16x16x32_bf16 v[118:121], v[134:137], v[174:177], v[118:121]
	v_mfma_f32_16x16x32_bf16 v[114:117], v[142:145], v[174:177], v[114:117]
	v_mfma_f32_16x16x32_bf16 v[110:113], v[134:137], v[182:185], v[110:113]
	v_mfma_f32_16x16x32_bf16 v[106:109], v[142:145], v[182:185], v[106:109]
	v_mfma_f32_16x16x32_bf16 v[102:105], v[134:137], v[190:193], v[102:105]
	v_mfma_f32_16x16x32_bf16 v[98:101], v[142:145], v[190:193], v[98:101]
	v_mfma_f32_16x16x32_bf16 v[94:97], v[146:149], v[162:165], v[94:97]
	v_mfma_f32_16x16x32_bf16 v[90:93], v[154:157], v[162:165], v[90:93]
	v_mfma_f32_16x16x32_bf16 v[86:89], v[146:149], v[170:173], v[86:89]
	v_mfma_f32_16x16x32_bf16 v[82:85], v[154:157], v[170:173], v[82:85]
	v_mfma_f32_16x16x32_bf16 v[78:81], v[146:149], v[178:181], v[78:81]
	v_mfma_f32_16x16x32_bf16 v[74:77], v[154:157], v[178:181], v[74:77]
	v_mfma_f32_16x16x32_bf16 v[70:73], v[146:149], v[186:189], v[70:73]
	v_mfma_f32_16x16x32_bf16 v[66:69], v[154:157], v[186:189], v[66:69]
	v_mfma_f32_16x16x32_bf16 v[94:97], v[150:153], v[166:169], v[94:97]
	v_mfma_f32_16x16x32_bf16 v[90:93], v[158:161], v[166:169], v[90:93]
	v_mfma_f32_16x16x32_bf16 v[86:89], v[150:153], v[174:177], v[86:89]
	v_mfma_f32_16x16x32_bf16 v[82:85], v[158:161], v[174:177], v[82:85]
	v_mfma_f32_16x16x32_bf16 v[78:81], v[150:153], v[182:185], v[78:81]
	v_mfma_f32_16x16x32_bf16 v[74:77], v[158:161], v[182:185], v[74:77]
	v_mfma_f32_16x16x32_bf16 v[70:73], v[150:153], v[190:193], v[70:73]
	v_mfma_f32_16x16x32_bf16 v[66:69], v[158:161], v[190:193], v[66:69]
	s_barrier
; template <class Epi, bool ALIGN_EPI, bool SP2, class Hook>
; __device__ __forceinline__ void gemm_phase(LAS unsigned char* lds, const Gemm g, const StaticOrder& S, const Epi& E, Acc& acc, const bool fresh, const Hook& H, const int wave_id) {
;     ...
;         for (int t = t0; t < nt; t += 2) {
	s_setprio 0
	s_mov_b32 m0, s39
	ds_read_b128 v[162:165], v231 offset:49152
	ds_read_b128 v[166:169], v231 offset:50176
	ds_read_b128 v[170:173], v231 offset:51200
	ds_read_b128 v[174:177], v231 offset:52224
	ds_read_b128 v[178:181], v231 offset:53248
	ds_read_b128 v[182:185], v231 offset:54272
	ds_read_b128 v[186:189], v231 offset:55296
	ds_read_b128 v[190:193], v231 offset:56320
	buffer_load_dwordx4 v227, s[16:19], s57 offen lds
	s_mov_b32 m0, s40
	s_add_i32 s54, s54, 0x20080
	buffer_load_dwordx4 v229, s[16:19], s57 offen lds
	s_mov_b32 m0, s43
	s_nop 0
	buffer_load_dwordx4 v227, s[16:19], s54 offen lds
	s_mov_b32 m0, s42
	s_nop 0
	buffer_load_dwordx4 v229, s[16:19], s54 offen lds
	s_mov_b32 m0, s41
	s_nop 0
	buffer_load_dwordx4 v199, s[12:15], s21 offen lds
	s_mov_b32 m0, s33
	s_nop 0
	buffer_load_dwordx4 v228, s[12:15], s21 offen lds
	s_waitcnt vmcnt(8)
	s_waitcnt lgkmcnt(0)
	s_setprio 1
	s_barrier
	v_mfma_f32_16x16x32_bf16 v[62:65], v[130:133], v[162:165], v[62:65]
	v_mfma_f32_16x16x32_bf16 v[58:61], v[138:141], v[162:165], v[58:61]
	v_mfma_f32_16x16x32_bf16 v[54:57], v[130:133], v[170:173], v[54:57]
	v_mfma_f32_16x16x32_bf16 v[50:53], v[138:141], v[170:173], v[50:53]
	v_mfma_f32_16x16x32_bf16 v[46:49], v[130:133], v[178:181], v[46:49]
	v_mfma_f32_16x16x32_bf16 v[42:45], v[138:141], v[178:181], v[42:45]
	v_mfma_f32_16x16x32_bf16 v[38:41], v[130:133], v[186:189], v[38:41]
	v_mfma_f32_16x16x32_bf16 v[34:37], v[138:141], v[186:189], v[34:37]
	v_mfma_f32_16x16x32_bf16 v[62:65], v[134:137], v[166:169], v[62:65]
	v_mfma_f32_16x16x32_bf16 v[58:61], v[142:145], v[166:169], v[58:61]
	v_mfma_f32_16x16x32_bf16 v[54:57], v[134:137], v[174:177], v[54:57]
	v_mfma_f32_16x16x32_bf16 v[50:53], v[142:145], v[174:177], v[50:53]
	v_mfma_f32_16x16x32_bf16 v[46:49], v[134:137], v[182:185], v[46:49]
	v_mfma_f32_16x16x32_bf16 v[42:45], v[142:145], v[182:185], v[42:45]
	v_mfma_f32_16x16x32_bf16 v[38:41], v[134:137], v[190:193], v[38:41]
	v_mfma_f32_16x16x32_bf16 v[34:37], v[142:145], v[190:193], v[34:37]
	v_mfma_f32_16x16x32_bf16 v[30:33], v[146:149], v[162:165], v[30:33]
	v_mfma_f32_16x16x32_bf16 v[26:29], v[154:157], v[162:165], v[26:29]
	v_mfma_f32_16x16x32_bf16 v[22:25], v[146:149], v[170:173], v[22:25]
	v_mfma_f32_16x16x32_bf16 v[18:21], v[154:157], v[170:173], v[18:21]
	v_mfma_f32_16x16x32_bf16 v[14:17], v[146:149], v[178:181], v[14:17]
	v_mfma_f32_16x16x32_bf16 v[10:13], v[154:157], v[178:181], v[10:13]
	v_mfma_f32_16x16x32_bf16 v[6:9], v[146:149], v[186:189], v[6:9]
	v_mfma_f32_16x16x32_bf16 v[2:5], v[154:157], v[186:189], v[2:5]
	v_mfma_f32_16x16x32_bf16 v[30:33], v[150:153], v[166:169], v[30:33]
	v_mfma_f32_16x16x32_bf16 v[26:29], v[158:161], v[166:169], v[26:29]
	v_mfma_f32_16x16x32_bf16 v[22:25], v[150:153], v[174:177], v[22:25]
	v_mfma_f32_16x16x32_bf16 v[18:21], v[158:161], v[174:177], v[18:21]
	v_mfma_f32_16x16x32_bf16 v[14:17], v[150:153], v[182:185], v[14:17]
	v_mfma_f32_16x16x32_bf16 v[10:13], v[158:161], v[182:185], v[10:13]
	v_mfma_f32_16x16x32_bf16 v[6:9], v[150:153], v[190:193], v[6:9]
	v_mfma_f32_16x16x32_bf16 v[2:5], v[158:161], v[190:193], v[2:5]
	s_barrier
	s_setprio 0
	s_add_i32 s12, s20, 2
	s_cmp_gt_u32 s20, 5
	s_cbranch_scc1 .LBB0_1032
	s_mov_b32 s20, s12
	s_branch .LBB0_951

; template <class Epi, bool ALIGN_EPI, bool SP2, class Hook>
; __device__ __forceinline__ void gemm_phase(LAS unsigned char* lds, const Gemm g, const StaticOrder& S, const Epi& E, Acc& acc, const bool fresh, const Hook& H, const int wave_id) {
;     ...
;         for (int t = t0; t < nt; t += 2) {
;             const bool last = (t == nt - 2);
;             const Src a1 = cA + (size_t)(t + 1) * kstep;
;             const Src a2 = last ? nA : cA + (size_t)(t + 2) * kstep, b2 = last ? nB : cB + (size_t)(t + 2) * kstep;
;             const Src a3 = a2 + kstep, b3 = b2 + kstep;
.LBB0_1235:
	v_add_u32_e32 v142, 0x10000, v161
	v_add_u32_e32 v163, 0x14000, v161
	ds_read_b128 v[130:133], v142
	ds_read_b128 v[134:137], v142 offset:1024
	ds_read_b128 v[138:141], v142 offset:2048
	ds_read_b128 v[142:145], v142 offset:3072
	ds_read_b128 v[146:149], v163
	ds_read_b128 v[150:153], v163 offset:1024
	ds_read_b128 v[154:157], v163 offset:2048
	ds_read_b128 v[164:167], v163 offset:3072
	s_add_i32 s16, s2, 0xfffc0080
	s_cmp_eq_u32 s59, 12
	s_cselect_b32 s62, s55, s16
	s_cselect_b32 s17, s31, s9
	s_cselect_b32 s16, s30, s8
	s_cselect_b32 s19, s35, s51
	s_cselect_b32 s18, s34, s50
	s_cselect_b32 s60, s56, s3
	s_cselect_b32 s20, s26, s12
	s_cselect_b32 s21, s27, s13
	s_cselect_b32 s22, s28, s14
	s_cselect_b32 s23, s29, s15
	s_or_b32 s61, s62, 0x80
	s_mov_b32 m0, s45
	ds_read_b128 v[168:171], v162
	ds_read_b128 v[172:175], v162 offset:1024
	ds_read_b128 v[176:179], v162 offset:2048
	ds_read_b128 v[180:183], v162 offset:3072
	ds_read_b128 v[184:187], v162 offset:4096
	ds_read_b128 v[188:191], v162 offset:5120
	ds_read_b128 v[192:195], v162 offset:6144
	ds_read_b128 v[200:203], v162 offset:7168
	buffer_load_dwordx4 v0, s[12:15], s2 offen lds
	s_mov_b32 m0, s46
	s_nop 0
	buffer_load_dwordx4 v159, s[12:15], s2 offen lds
	s_waitcnt vmcnt(8)
	s_waitcnt lgkmcnt(0)
	s_setprio 1
	s_barrier
	v_mfma_f32_16x16x32_bf16 v[126:129], v[130:133], v[168:171], v[126:129]
	v_mfma_f32_16x16x32_bf16 v[122:125], v[138:141], v[168:171], v[122:125]
	v_mfma_f32_16x16x32_bf16 v[110:113], v[130:133], v[176:179], v[110:113]
	v_mfma_f32_16x16x32_bf16 v[106:109], v[138:141], v[176:179], v[106:109]
	v_mfma_f32_16x16x32_bf16 v[94:97], v[130:133], v[184:187], v[94:97]
	v_mfma_f32_16x16x32_bf16 v[90:93], v[138:141], v[184:187], v[90:93]
	v_mfma_f32_16x16x32_bf16 v[78:81], v[130:133], v[192:195], v[78:81]
	v_mfma_f32_16x16x32_bf16 v[74:77], v[138:141], v[192:195], v[74:77]
	v_mfma_f32_16x16x32_bf16 v[126:129], v[134:137], v[172:175], v[126:129]
	v_mfma_f32_16x16x32_bf16 v[122:125], v[142:145], v[172:175], v[122:125]
	v_mfma_f32_16x16x32_bf16 v[110:113], v[134:137], v[180:183], v[110:113]
	v_mfma_f32_16x16x32_bf16 v[106:109], v[142:145], v[180:183], v[106:109]
	v_mfma_f32_16x16x32_bf16 v[94:97], v[134:137], v[188:191], v[94:97]
	v_mfma_f32_16x16x32_bf16 v[90:93], v[142:145], v[188:191], v[90:93]
	v_mfma_f32_16x16x32_bf16 v[78:81], v[134:137], v[200:203], v[78:81]
	v_mfma_f32_16x16x32_bf16 v[74:77], v[142:145], v[200:203], v[74:77]
	v_mfma_f32_16x16x32_bf16 v[118:121], v[146:149], v[168:171], v[118:121]
	v_mfma_f32_16x16x32_bf16 v[114:117], v[154:157], v[168:171], v[114:117]
	v_mfma_f32_16x16x32_bf16 v[102:105], v[146:149], v[176:179], v[102:105]
	v_mfma_f32_16x16x32_bf16 v[98:101], v[154:157], v[176:179], v[98:101]
	v_mfma_f32_16x16x32_bf16 v[86:89], v[146:149], v[184:187], v[86:89]
	v_mfma_f32_16x16x32_bf16 v[82:85], v[154:157], v[184:187], v[82:85]
	v_mfma_f32_16x16x32_bf16 v[70:73], v[146:149], v[192:195], v[70:73]
	v_mfma_f32_16x16x32_bf16 v[66:69], v[154:157], v[192:195], v[66:69]
	v_mfma_f32_16x16x32_bf16 v[118:121], v[150:153], v[172:175], v[118:121]
	v_mfma_f32_16x16x32_bf16 v[114:117], v[164:167], v[172:175], v[114:117]
	v_mfma_f32_16x16x32_bf16 v[102:105], v[150:153], v[180:183], v[102:105]
	v_mfma_f32_16x16x32_bf16 v[98:101], v[164:167], v[180:183], v[98:101]
	v_mfma_f32_16x16x32_bf16 v[86:89], v[150:153], v[188:191], v[86:89]
	v_mfma_f32_16x16x32_bf16 v[82:85], v[164:167], v[188:191], v[82:85]
	v_mfma_f32_16x16x32_bf16 v[70:73], v[150:153], v[200:203], v[70:73]
	v_mfma_f32_16x16x32_bf16 v[66:69], v[164:167], v[200:203], v[66:69]
	s_barrier
	s_setprio 0
	s_mov_b32 m0, s92
	ds_read_b128 v[168:171], v162 offset:16384
	ds_read_b128 v[172:175], v162 offset:17408
	ds_read_b128 v[176:179], v162 offset:18432
	ds_read_b128 v[180:183], v162 offset:19456
	ds_read_b128 v[184:187], v162 offset:20480
	ds_read_b128 v[188:191], v162 offset:21504
	ds_read_b128 v[192:195], v162 offset:22528
	ds_read_b128 v[200:203], v162 offset:23552
	buffer_load_dwordx4 v158, s[16:19], s60 offen lds
	s_mov_b32 m0, s93
	s_add_i32 s63, s60, 0x40000
	buffer_load_dwordx4 v160, s[16:19], s60 offen lds
	s_mov_b32 m0, s94
	s_nop 0
	buffer_load_dwordx4 v158, s[16:19], s63 offen lds
	s_mov_b32 m0, s95
	s_nop 0
	buffer_load_dwordx4 v160, s[16:19], s63 offen lds
	s_mov_b32 m0, s44
	s_nop 0
	buffer_load_dwordx4 v0, s[20:23], s62 offen lds
	s_mov_b32 m0, s36
	s_nop 0
	buffer_load_dwordx4 v159, s[20:23], s62 offen lds
	s_waitcnt vmcnt(8)
	s_waitcnt lgkmcnt(0)
	s_setprio 1
	s_barrier
	v_mfma_f32_16x16x32_bf16 v[62:65], v[130:133], v[168:171], v[62:65]
	v_mfma_f32_16x16x32_bf16 v[58:61], v[138:141], v[168:171], v[58:61]
	v_mfma_f32_16x16x32_bf16 v[46:49], v[130:133], v[176:179], v[46:49]
	v_mfma_f32_16x16x32_bf16 v[42:45], v[138:141], v[176:179], v[42:45]
	v_mfma_f32_16x16x32_bf16 v[30:33], v[130:133], v[184:187], v[30:33]
	v_mfma_f32_16x16x32_bf16 v[26:29], v[138:141], v[184:187], v[26:29]
	v_mfma_f32_16x16x32_bf16 v[14:17], v[130:133], v[192:195], v[14:17]
	v_mfma_f32_16x16x32_bf16 v[10:13], v[138:141], v[192:195], v[10:13]
	v_mfma_f32_16x16x32_bf16 v[62:65], v[134:137], v[172:175], v[62:65]
	v_mfma_f32_16x16x32_bf16 v[58:61], v[142:145], v[172:175], v[58:61]
	v_mfma_f32_16x16x32_bf16 v[46:49], v[134:137], v[180:183], v[46:49]
	v_mfma_f32_16x16x32_bf16 v[42:45], v[142:145], v[180:183], v[42:45]
	v_mfma_f32_16x16x32_bf16 v[30:33], v[134:137], v[188:191], v[30:33]
	v_mfma_f32_16x16x32_bf16 v[26:29], v[142:145], v[188:191], v[26:29]
	v_mfma_f32_16x16x32_bf16 v[14:17], v[134:137], v[200:203], v[14:17]
	v_mfma_f32_16x16x32_bf16 v[10:13], v[142:145], v[200:203], v[10:13]
	v_mfma_f32_16x16x32_bf16 v[54:57], v[146:149], v[168:171], v[54:57]
	v_mfma_f32_16x16x32_bf16 v[50:53], v[154:157], v[168:171], v[50:53]
	v_mfma_f32_16x16x32_bf16 v[38:41], v[146:149], v[176:179], v[38:41]
	v_mfma_f32_16x16x32_bf16 v[34:37], v[154:157], v[176:179], v[34:37]
	v_mfma_f32_16x16x32_bf16 v[22:25], v[146:149], v[184:187], v[22:25]
	v_mfma_f32_16x16x32_bf16 v[18:21], v[154:157], v[184:187], v[18:21]
	v_mfma_f32_16x16x32_bf16 v[6:9], v[146:149], v[192:195], v[6:9]
	v_mfma_f32_16x16x32_bf16 v[2:5], v[154:157], v[192:195], v[2:5]
	v_mfma_f32_16x16x32_bf16 v[54:57], v[150:153], v[172:175], v[54:57]
	v_mfma_f32_16x16x32_bf16 v[50:53], v[164:167], v[172:175], v[50:53]
	v_mfma_f32_16x16x32_bf16 v[38:41], v[150:153], v[180:183], v[38:41]
	v_mfma_f32_16x16x32_bf16 v[34:37], v[164:167], v[180:183], v[34:37]
	v_mfma_f32_16x16x32_bf16 v[22:25], v[150:153], v[188:191], v[22:25]
	v_mfma_f32_16x16x32_bf16 v[18:21], v[164:167], v[188:191], v[18:21]
	v_mfma_f32_16x16x32_bf16 v[6:9], v[150:153], v[200:203], v[6:9]
	v_mfma_f32_16x16x32_bf16 v[2:5], v[164:167], v[200:203], v[2:5]
	s_barrier
; #define PG8_BAR __builtin_amdgcn_s_barrier()
; template <class Epi, bool ALIGN_EPI, bool SP2, class Hook>
; __device__ __forceinline__ void gemm_phase(LAS unsigned char* lds, const Gemm g, const StaticOrder& S, const Epi& E, Acc& acc, const bool fresh, const Hook& H, const int wave_id) {
;     ...
;         if constexpr (ALIGN_EPI) { if (wr == 0) PG8_BAR; }
	s_setprio 0
	v_add_u32_e32 v142, 0x18000, v161
	v_add_u32_e32 v163, 0x1c000, v161
	ds_read_b128 v[130:133], v142
	ds_read_b128 v[134:137], v142 offset:1024
	ds_read_b128 v[138:141], v142 offset:2048
	ds_read_b128 v[142:145], v142 offset:3072
	ds_read_b128 v[146:149], v163
	ds_read_b128 v[150:153], v163 offset:1024
	ds_read_b128 v[154:157], v163 offset:2048
	ds_read_b128 v[164:167], v163 offset:3072
	s_add_i32 s62, s62, 0x40000
	s_mov_b32 m0, s37
	ds_read_b128 v[168:171], v162 offset:32768
	ds_read_b128 v[172:175], v162 offset:33792
	ds_read_b128 v[176:179], v162 offset:34816
	ds_read_b128 v[180:183], v162 offset:35840
	ds_read_b128 v[184:187], v162 offset:36864
	ds_read_b128 v[188:191], v162 offset:37888
	ds_read_b128 v[192:195], v162 offset:38912
	ds_read_b128 v[200:203], v162 offset:39936
	buffer_load_dwordx4 v0, s[20:23], s62 offen lds
	s_mov_b32 m0, s38
	s_nop 0
	buffer_load_dwordx4 v159, s[20:23], s62 offen lds
	s_waitcnt vmcnt(8)
	s_waitcnt lgkmcnt(0)
	s_setprio 1
	s_barrier
	v_mfma_f32_16x16x32_bf16 v[126:129], v[130:133], v[168:171], v[126:129]
	v_mfma_f32_16x16x32_bf16 v[122:125], v[138:141], v[168:171], v[122:125]
	v_mfma_f32_16x16x32_bf16 v[110:113], v[130:133], v[176:179], v[110:113]
	v_mfma_f32_16x16x32_bf16 v[106:109], v[138:141], v[176:179], v[106:109]
	v_mfma_f32_16x16x32_bf16 v[94:97], v[130:133], v[184:187], v[94:97]
	v_mfma_f32_16x16x32_bf16 v[90:93], v[138:141], v[184:187], v[90:93]
	v_mfma_f32_16x16x32_bf16 v[78:81], v[130:133], v[192:195], v[78:81]
	v_mfma_f32_16x16x32_bf16 v[74:77], v[138:141], v[192:195], v[74:77]
	v_mfma_f32_16x16x32_bf16 v[126:129], v[134:137], v[172:175], v[126:129]
	v_mfma_f32_16x16x32_bf16 v[122:125], v[142:145], v[172:175], v[122:125]
	v_mfma_f32_16x16x32_bf16 v[110:113], v[134:137], v[180:183], v[110:113]
	v_mfma_f32_16x16x32_bf16 v[106:109], v[142:145], v[180:183], v[106:109]
	v_mfma_f32_16x16x32_bf16 v[94:97], v[134:137], v[188:191], v[94:97]
	v_mfma_f32_16x16x32_bf16 v[90:93], v[142:145], v[188:191], v[90:93]
	v_mfma_f32_16x16x32_bf16 v[78:81], v[134:137], v[200:203], v[78:81]
	v_mfma_f32_16x16x32_bf16 v[74:77], v[142:145], v[200:203], v[74:77]
	v_mfma_f32_16x16x32_bf16 v[118:121], v[146:149], v[168:171], v[118:121]
	v_mfma_f32_16x16x32_bf16 v[114:117], v[154:157], v[168:171], v[114:117]
	v_mfma_f32_16x16x32_bf16 v[102:105], v[146:149], v[176:179], v[102:105]
	v_mfma_f32_16x16x32_bf16 v[98:101], v[154:157], v[176:179], v[98:101]
	v_mfma_f32_16x16x32_bf16 v[86:89], v[146:149], v[184:187], v[86:89]
	v_mfma_f32_16x16x32_bf16 v[82:85], v[154:157], v[184:187], v[82:85]
	v_mfma_f32_16x16x32_bf16 v[70:73], v[146:149], v[192:195], v[70:73]
	v_mfma_f32_16x16x32_bf16 v[66:69], v[154:157], v[192:195], v[66:69]
	v_mfma_f32_16x16x32_bf16 v[118:121], v[150:153], v[172:175], v[118:121]
	v_mfma_f32_16x16x32_bf16 v[114:117], v[164:167], v[172:175], v[114:117]
	v_mfma_f32_16x16x32_bf16 v[102:105], v[150:153], v[180:183], v[102:105]
	v_mfma_f32_16x16x32_bf16 v[98:101], v[164:167], v[180:183], v[98:101]
	v_mfma_f32_16x16x32_bf16 v[86:89], v[150:153], v[188:191], v[86:89]
	v_mfma_f32_16x16x32_bf16 v[82:85], v[164:167], v[188:191], v[82:85]
	v_mfma_f32_16x16x32_bf16 v[70:73], v[150:153], v[200:203], v[70:73]
	v_mfma_f32_16x16x32_bf16 v[66:69], v[164:167], v[200:203], v[66:69]
	s_barrier
	s_setprio 0
	s_mov_b32 m0, s39
	s_or_b32 s62, s60, 0x80
	ds_read_b128 v[168:171], v162 offset:49152
	ds_read_b128 v[172:175], v162 offset:50176
	ds_read_b128 v[176:179], v162 offset:51200
	ds_read_b128 v[180:183], v162 offset:52224
	ds_read_b128 v[184:187], v162 offset:53248
	ds_read_b128 v[188:191], v162 offset:54272
	ds_read_b128 v[192:195], v162 offset:55296
	ds_read_b128 v[200:203], v162 offset:56320
	buffer_load_dwordx4 v158, s[16:19], s62 offen lds
	s_mov_b32 m0, s40
	s_add_i32 s60, s60, 0x40080
	buffer_load_dwordx4 v160, s[16:19], s62 offen lds
	s_mov_b32 m0, s43
	s_nop 0
	buffer_load_dwordx4 v158, s[16:19], s60 offen lds
	s_mov_b32 m0, s42
	s_nop 0
	buffer_load_dwordx4 v160, s[16:19], s60 offen lds
	s_mov_b32 m0, s41
	s_nop 0
	buffer_load_dwordx4 v0, s[20:23], s61 offen lds
	s_mov_b32 m0, s33
	s_nop 0
	buffer_load_dwordx4 v159, s[20:23], s61 offen lds
	s_waitcnt vmcnt(8)
	s_waitcnt lgkmcnt(0)
	s_setprio 1
	s_barrier
	v_mfma_f32_16x16x32_bf16 v[62:65], v[130:133], v[168:171], v[62:65]
	v_mfma_f32_16x16x32_bf16 v[58:61], v[138:141], v[168:171], v[58:61]
	v_mfma_f32_16x16x32_bf16 v[46:49], v[130:133], v[176:179], v[46:49]
	v_mfma_f32_16x16x32_bf16 v[42:45], v[138:141], v[176:179], v[42:45]
	v_mfma_f32_16x16x32_bf16 v[30:33], v[130:133], v[184:187], v[30:33]
	v_mfma_f32_16x16x32_bf16 v[26:29], v[138:141], v[184:187], v[26:29]
	v_mfma_f32_16x16x32_bf16 v[14:17], v[130:133], v[192:195], v[14:17]
	v_mfma_f32_16x16x32_bf16 v[10:13], v[138:141], v[192:195], v[10:13]
	v_mfma_f32_16x16x32_bf16 v[62:65], v[134:137], v[172:175], v[62:65]
	v_mfma_f32_16x16x32_bf16 v[58:61], v[142:145], v[172:175], v[58:61]
	v_mfma_f32_16x16x32_bf16 v[46:49], v[134:137], v[180:183], v[46:49]
	v_mfma_f32_16x16x32_bf16 v[42:45], v[142:145], v[180:183], v[42:45]
	v_mfma_f32_16x16x32_bf16 v[30:33], v[134:137], v[188:191], v[30:33]
	v_mfma_f32_16x16x32_bf16 v[26:29], v[142:145], v[188:191], v[26:29]
	v_mfma_f32_16x16x32_bf16 v[14:17], v[134:137], v[200:203], v[14:17]
	v_mfma_f32_16x16x32_bf16 v[10:13], v[142:145], v[200:203], v[10:13]
	v_mfma_f32_16x16x32_bf16 v[54:57], v[146:149], v[168:171], v[54:57]
	v_mfma_f32_16x16x32_bf16 v[50:53], v[154:157], v[168:171], v[50:53]
	v_mfma_f32_16x16x32_bf16 v[38:41], v[146:149], v[176:179], v[38:41]
	v_mfma_f32_16x16x32_bf16 v[34:37], v[154:157], v[176:179], v[34:37]
	v_mfma_f32_16x16x32_bf16 v[22:25], v[146:149], v[184:187], v[22:25]
	v_mfma_f32_16x16x32_bf16 v[18:21], v[154:157], v[184:187], v[18:21]
	v_mfma_f32_16x16x32_bf16 v[6:9], v[146:149], v[192:195], v[6:9]
	v_mfma_f32_16x16x32_bf16 v[2:5], v[154:157], v[192:195], v[2:5]
	v_mfma_f32_16x16x32_bf16 v[54:57], v[150:153], v[172:175], v[54:57]
	v_mfma_f32_16x16x32_bf16 v[50:53], v[164:167], v[172:175], v[50:53]
	v_mfma_f32_16x16x32_bf16 v[38:41], v[150:153], v[180:183], v[38:41]
	v_mfma_f32_16x16x32_bf16 v[34:37], v[164:167], v[180:183], v[34:37]
	v_mfma_f32_16x16x32_bf16 v[22:25], v[150:153], v[188:191], v[22:25]
	v_mfma_f32_16x16x32_bf16 v[18:21], v[164:167], v[188:191], v[18:21]
	v_mfma_f32_16x16x32_bf16 v[6:9], v[150:153], v[200:203], v[6:9]
	v_mfma_f32_16x16x32_bf16 v[2:5], v[164:167], v[200:203], v[2:5]
	s_barrier
	s_setprio 0
	s_add_i32 s59, s59, 2
	s_addk_i32 s2, 0x100
	s_addk_i32 s3, 0x100
	s_cmp_gt_u32 s59, 13
	s_cbranch_scc0 .LBB0_1235
	v_readlane_b32 s2, v251, 45
	v_readlane_b32 s3, v251, 46
	s_and_b64 vcc, exec, s[2:3]
	s_cbranch_vccz .LBB0_1238
	s_barrier

; #define PG8_WAIT_V(n) asm volatile("s_waitcnt vmcnt(" #n ")" ::: "memory")
; template <class Epi, bool ALIGN_EPI, bool SP2, class Hook>
; __device__ __forceinline__ void gemm_phase(LAS unsigned char* lds, const Gemm g, const StaticOrder& S, const Epi& E, Acc& acc, const bool fresh, const Hook& H, const int wave_id) {
;     ...
;         if constexpr (SP2 && Epi::NSTORE > 0) {
;             const Src a1 = cA + kstep, a2 = cA + 2 * kstep, b2 = cB + 2 * kstep, a3 = a2 + kstep, b3 = b2 + kstep;
;             if constexpr (Epi::NSTORE == 16) PG8_TRIP_SP2(PG8_WAIT_V(24)); else PG8_TRIP_SP2(PG8_WAIT_V(16));
;             t0 = 2;
;         }
.LBB0_1452:
	ds_read_b128 v[2:5], v138
	ds_read_b128 v[6:9], v138 offset:1024
	ds_read_b128 v[10:13], v138 offset:2048
	ds_read_b128 v[14:17], v138 offset:3072
	ds_read_b128 v[18:21], v139
	ds_read_b128 v[22:25], v139 offset:1024
	ds_read_b128 v[26:29], v139 offset:2048
	ds_read_b128 v[30:33], v139 offset:3072
	s_or_b32 s3, s50, 0x100
	s_or_b32 s2, s50, 0x180
	s_or_b32 s12, s51, 0x100
	s_or_b32 s13, s50, 0x40080
	s_mov_b32 m0, s45
	ds_read_b128 v[34:37], v137
	ds_read_b128 v[38:41], v137 offset:1024
	ds_read_b128 v[42:45], v137 offset:2048
	ds_read_b128 v[46:49], v137 offset:3072
	ds_read_b128 v[50:53], v137 offset:4096
	ds_read_b128 v[54:57], v137 offset:5120
	ds_read_b128 v[58:61], v137 offset:6144
	ds_read_b128 v[62:65], v137 offset:7168
	buffer_load_dwordx4 v132, s[4:7], s13 offen lds
	s_mov_b32 m0, s46
	s_nop 0
	buffer_load_dwordx4 v134, s[4:7], s13 offen lds
	s_waitcnt vmcnt(16)
	s_waitcnt lgkmcnt(0)
	s_setprio 1
	s_barrier
	v_mfma_f32_16x16x32_bf16 v[90:93], v[2:5], v[58:61], 0
	v_mfma_f32_16x16x32_bf16 v[66:69], v[2:5], v[34:37], 0
	v_mfma_f32_16x16x32_bf16 v[70:73], v[10:13], v[34:37], 0
	v_mfma_f32_16x16x32_bf16 v[74:77], v[2:5], v[42:45], 0
	v_mfma_f32_16x16x32_bf16 v[78:81], v[10:13], v[42:45], 0
	v_mfma_f32_16x16x32_bf16 v[82:85], v[2:5], v[50:53], 0
	v_mfma_f32_16x16x32_bf16 v[86:89], v[10:13], v[50:53], 0
	v_mfma_f32_16x16x32_bf16 v[96:99], v[6:9], v[62:65], v[90:93]
	v_mfma_f32_16x16x32_bf16 v[90:93], v[10:13], v[58:61], 0
	v_mfma_f32_16x16x32_bf16 v[66:69], v[6:9], v[38:41], v[66:69]
	v_mfma_f32_16x16x32_bf16 v[70:73], v[14:17], v[38:41], v[70:73]
	v_mfma_f32_16x16x32_bf16 v[74:77], v[6:9], v[46:49], v[74:77]
	v_mfma_f32_16x16x32_bf16 v[78:81], v[14:17], v[46:49], v[78:81]
	v_mfma_f32_16x16x32_bf16 v[82:85], v[6:9], v[54:57], v[82:85]
	v_mfma_f32_16x16x32_bf16 v[86:89], v[14:17], v[54:57], v[86:89]
	v_mfma_f32_16x16x32_bf16 v[104:107], v[14:17], v[62:65], v[90:93]
	v_mfma_f32_16x16x32_bf16 v[90:93], v[18:21], v[34:37], 0
	v_mfma_f32_16x16x32_bf16 v[34:37], v[26:29], v[34:37], 0
	v_mfma_f32_16x16x32_bf16 v[112:115], v[22:25], v[38:41], v[90:93]
	v_mfma_f32_16x16x32_bf16 v[34:37], v[30:33], v[38:41], v[34:37]
	v_mfma_f32_16x16x32_bf16 v[38:41], v[18:21], v[42:45], 0
	v_mfma_f32_16x16x32_bf16 v[42:45], v[26:29], v[42:45], 0
	v_mfma_f32_16x16x32_bf16 v[38:41], v[22:25], v[46:49], v[38:41]
	v_mfma_f32_16x16x32_bf16 v[42:45], v[30:33], v[46:49], v[42:45]
	v_mfma_f32_16x16x32_bf16 v[46:49], v[18:21], v[50:53], 0
	v_mfma_f32_16x16x32_bf16 v[50:53], v[26:29], v[50:53], 0
	v_mfma_f32_16x16x32_bf16 v[46:49], v[22:25], v[54:57], v[46:49]
	v_mfma_f32_16x16x32_bf16 v[50:53], v[30:33], v[54:57], v[50:53]
	v_mfma_f32_16x16x32_bf16 v[54:57], v[18:21], v[58:61], 0
	v_mfma_f32_16x16x32_bf16 v[58:61], v[26:29], v[58:61], 0
	v_mfma_f32_16x16x32_bf16 v[54:57], v[22:25], v[62:65], v[54:57]
	v_mfma_f32_16x16x32_bf16 v[58:61], v[30:33], v[62:65], v[58:61]
	s_barrier
	s_setprio 0
	s_mov_b32 m0, s92
	ds_read_b128 v[62:65], v137 offset:16384
	ds_read_b128 v[90:93], v137 offset:17408
	ds_read_b128 v[100:103], v137 offset:18432
	ds_read_b128 v[108:111], v137 offset:19456
	ds_read_b128 v[116:119], v137 offset:20480
	ds_read_b128 v[120:123], v137 offset:21504
	ds_read_b128 v[124:127], v137 offset:22528
	ds_read_b128 v[128:131], v137 offset:23552
	buffer_load_dwordx4 v133, s[8:11], s12 offen lds
	s_mov_b32 m0, s93
	s_nop 0
	buffer_load_dwordx4 v135, s[8:11], s12 offen lds
	s_or_b32 s12, s51, 0x40100
	s_mov_b32 m0, s94
	s_nop 0
	buffer_load_dwordx4 v133, s[8:11], s12 offen lds
	s_mov_b32 m0, s95
	s_nop 0
	buffer_load_dwordx4 v135, s[8:11], s12 offen lds
	s_mov_b32 m0, s44
	s_nop 0
	buffer_load_dwordx4 v132, s[4:7], s3 offen lds
	s_mov_b32 m0, s36
	s_nop 0
	buffer_load_dwordx4 v134, s[4:7], s3 offen lds
	s_waitcnt vmcnt(16)
	s_waitcnt lgkmcnt(0)
	s_setprio 1
	s_barrier
	v_mfma_f32_16x16x32_bf16 v[142:145], v[2:5], v[62:65], 0
	v_mfma_f32_16x16x32_bf16 v[150:153], v[2:5], v[100:103], 0
	v_mfma_f32_16x16x32_bf16 v[158:161], v[2:5], v[116:119], 0
	v_mfma_f32_16x16x32_bf16 v[2:5], v[2:5], v[124:127], 0
	v_mfma_f32_16x16x32_bf16 v[142:145], v[6:9], v[90:93], v[142:145]
	v_mfma_f32_16x16x32_bf16 v[150:153], v[6:9], v[108:111], v[150:153]
	v_mfma_f32_16x16x32_bf16 v[158:161], v[6:9], v[120:123], v[158:161]
	v_mfma_f32_16x16x32_bf16 v[2:5], v[6:9], v[128:131], v[2:5]
	v_mfma_f32_16x16x32_bf16 v[6:9], v[10:13], v[124:127], 0
	v_mfma_f32_16x16x32_bf16 v[146:149], v[10:13], v[62:65], 0
	v_mfma_f32_16x16x32_bf16 v[154:157], v[10:13], v[100:103], 0
	v_mfma_f32_16x16x32_bf16 v[162:165], v[10:13], v[116:119], 0
	v_mfma_f32_16x16x32_bf16 v[6:9], v[14:17], v[128:131], v[6:9]
	v_mfma_f32_16x16x32_bf16 v[146:149], v[14:17], v[90:93], v[146:149]
	v_mfma_f32_16x16x32_bf16 v[154:157], v[14:17], v[108:111], v[154:157]
	v_mfma_f32_16x16x32_bf16 v[162:165], v[14:17], v[120:123], v[162:165]
	v_mfma_f32_16x16x32_bf16 v[10:13], v[18:21], v[62:65], 0
	v_mfma_f32_16x16x32_bf16 v[166:169], v[22:25], v[90:93], v[10:13]
	v_mfma_f32_16x16x32_bf16 v[10:13], v[26:29], v[62:65], 0
	v_mfma_f32_16x16x32_bf16 v[170:173], v[30:33], v[90:93], v[10:13]
	v_mfma_f32_16x16x32_bf16 v[10:13], v[18:21], v[100:103], 0
	v_mfma_f32_16x16x32_bf16 v[174:177], v[22:25], v[108:111], v[10:13]
	v_mfma_f32_16x16x32_bf16 v[10:13], v[26:29], v[100:103], 0
	v_mfma_f32_16x16x32_bf16 v[178:181], v[30:33], v[108:111], v[10:13]
	v_mfma_f32_16x16x32_bf16 v[10:13], v[18:21], v[116:119], 0
	v_mfma_f32_16x16x32_bf16 v[182:185], v[22:25], v[120:123], v[10:13]
	v_mfma_f32_16x16x32_bf16 v[10:13], v[26:29], v[116:119], 0
	v_mfma_f32_16x16x32_bf16 v[186:189], v[30:33], v[120:123], v[10:13]
	v_mfma_f32_16x16x32_bf16 v[10:13], v[18:21], v[124:127], 0
	v_mfma_f32_16x16x32_bf16 v[16:19], v[22:25], v[128:131], v[10:13]
	v_mfma_f32_16x16x32_bf16 v[10:13], v[26:29], v[124:127], 0
	v_mfma_f32_16x16x32_bf16 v[190:193], v[30:33], v[128:131], v[10:13]
	s_barrier
; #define PG8_WAIT_V(n) asm volatile("s_waitcnt vmcnt(" #n ")" ::: "memory")
; template <class Epi, bool ALIGN_EPI, bool SP2, class Hook>
; __device__ __forceinline__ void gemm_phase(LAS unsigned char* lds, const Gemm g, const StaticOrder& S, const Epi& E, Acc& acc, const bool fresh, const Hook& H, const int wave_id) {
;     ...
;         if constexpr (SP2 && Epi::NSTORE > 0) {
;             const Src a1 = cA + kstep, a2 = cA + 2 * kstep, b2 = cB + 2 * kstep, a3 = a2 + kstep, b3 = b2 + kstep;
;             if constexpr (Epi::NSTORE == 16) PG8_TRIP_SP2(PG8_WAIT_V(24)); else PG8_TRIP_SP2(PG8_WAIT_V(16));
;             t0 = 2;
;         }
	s_setprio 0
	s_nop 4
	ds_read_b128 v[10:13], v140
	ds_read_b128 v[24:27], v140 offset:1024
	ds_read_b128 v[194:197], v140 offset:2048
	ds_read_b128 v[200:203], v140 offset:3072
	ds_read_b128 v[204:207], v141
	ds_read_b128 v[208:211], v141 offset:1024
	ds_read_b128 v[212:215], v141 offset:2048
	ds_read_b128 v[138:141], v141 offset:3072
	s_or_b32 s3, s50, 0x40100
	s_mov_b32 m0, s37
	ds_read_b128 v[20:23], v137 offset:32768
	ds_read_b128 v[28:31], v137 offset:33792
	ds_read_b128 v[216:219], v137 offset:34816
	ds_read_b128 v[220:223], v137 offset:35840
	ds_read_b128 v[228:231], v137 offset:36864
	ds_read_b128 v[232:235], v137 offset:37888
	ds_read_b128 v[236:239], v137 offset:38912
	ds_read_b128 v[240:243], v137 offset:39936
	buffer_load_dwordx4 v132, s[4:7], s3 offen lds
	s_mov_b32 m0, s38
	s_nop 0
	buffer_load_dwordx4 v134, s[4:7], s3 offen lds
	s_waitcnt vmcnt(8)
	s_waitcnt lgkmcnt(0)
	s_setprio 1
	s_barrier
	v_mfma_f32_16x16x32_bf16 v[62:65], v[10:13], v[20:23], v[66:69]
	v_mfma_f32_16x16x32_bf16 v[124:127], v[24:27], v[28:31], v[62:65]
	v_mfma_f32_16x16x32_bf16 v[62:65], v[194:197], v[20:23], v[70:73]
	v_mfma_f32_16x16x32_bf16 v[116:119], v[200:203], v[28:31], v[62:65]
	v_mfma_f32_16x16x32_bf16 v[62:65], v[10:13], v[216:219], v[74:77]
	v_mfma_f32_16x16x32_bf16 v[108:111], v[24:27], v[220:223], v[62:65]
	v_mfma_f32_16x16x32_bf16 v[62:65], v[194:197], v[216:219], v[78:81]
	v_mfma_f32_16x16x32_bf16 v[100:103], v[200:203], v[220:223], v[62:65]
	v_mfma_f32_16x16x32_bf16 v[62:65], v[10:13], v[228:231], v[82:85]
	v_mfma_f32_16x16x32_bf16 v[92:95], v[24:27], v[232:235], v[62:65]
	v_mfma_f32_16x16x32_bf16 v[62:65], v[194:197], v[228:231], v[86:89]
	v_mfma_f32_16x16x32_bf16 v[84:87], v[200:203], v[232:235], v[62:65]
	v_mfma_f32_16x16x32_bf16 v[62:65], v[10:13], v[236:239], v[96:99]
	v_mfma_f32_16x16x32_bf16 v[76:79], v[24:27], v[240:243], v[62:65]
	v_mfma_f32_16x16x32_bf16 v[62:65], v[194:197], v[236:239], v[104:107]
	v_mfma_f32_16x16x32_bf16 v[64:67], v[200:203], v[240:243], v[62:65]
	v_mfma_f32_16x16x32_bf16 v[68:71], v[204:207], v[20:23], v[112:115]
	v_mfma_f32_16x16x32_bf16 v[20:23], v[212:215], v[20:23], v[34:37]
	v_mfma_f32_16x16x32_bf16 v[120:123], v[138:141], v[28:31], v[20:23]
	v_mfma_f32_16x16x32_bf16 v[20:23], v[204:207], v[216:219], v[38:41]
	v_mfma_f32_16x16x32_bf16 v[112:115], v[208:211], v[220:223], v[20:23]
	v_mfma_f32_16x16x32_bf16 v[20:23], v[212:215], v[216:219], v[42:45]
	v_mfma_f32_16x16x32_bf16 v[104:107], v[138:141], v[220:223], v[20:23]
	v_mfma_f32_16x16x32_bf16 v[20:23], v[204:207], v[228:231], v[46:49]
	v_mfma_f32_16x16x32_bf16 v[96:99], v[208:211], v[232:235], v[20:23]
	v_mfma_f32_16x16x32_bf16 v[20:23], v[212:215], v[228:231], v[50:53]
	v_mfma_f32_16x16x32_bf16 v[88:91], v[138:141], v[232:235], v[20:23]
	v_mfma_f32_16x16x32_bf16 v[20:23], v[204:207], v[236:239], v[54:57]
	v_mfma_f32_16x16x32_bf16 v[80:83], v[208:211], v[240:243], v[20:23]
	v_mfma_f32_16x16x32_bf16 v[20:23], v[212:215], v[236:239], v[58:61]
	v_mfma_f32_16x16x32_bf16 v[128:131], v[208:211], v[28:31], v[68:71]
	v_mfma_f32_16x16x32_bf16 v[68:71], v[138:141], v[240:243], v[20:23]
	s_barrier
	s_setprio 0
	s_mov_b32 m0, s39
	s_or_b32 s3, s51, 0x180
	ds_read_b128 v[32:35], v137 offset:49152
	ds_read_b128 v[40:43], v137 offset:50176
	ds_read_b128 v[216:219], v137 offset:51200
	ds_read_b128 v[220:223], v137 offset:52224
	ds_read_b128 v[228:231], v137 offset:53248
	ds_read_b128 v[232:235], v137 offset:54272
	ds_read_b128 v[236:239], v137 offset:55296
	ds_read_b128 v[240:243], v137 offset:56320
	buffer_load_dwordx4 v133, s[8:11], s3 offen lds
	s_mov_b32 m0, s40
	s_nop 0
	buffer_load_dwordx4 v135, s[8:11], s3 offen lds
	s_or_b32 s3, s51, 0x40180
	s_mov_b32 m0, s43
	s_nop 0
	buffer_load_dwordx4 v133, s[8:11], s3 offen lds
	s_mov_b32 m0, s42
	s_nop 0
	buffer_load_dwordx4 v135, s[8:11], s3 offen lds
	s_mov_b32 m0, s41
	s_nop 0
	buffer_load_dwordx4 v132, s[4:7], s2 offen lds
	s_mov_b32 m0, s33
	s_nop 0
	buffer_load_dwordx4 v134, s[4:7], s2 offen lds
	s_waitcnt vmcnt(8)
	s_waitcnt lgkmcnt(0)
	s_setprio 1
	s_barrier
	v_mfma_f32_16x16x32_bf16 v[20:23], v[10:13], v[32:35], v[142:145]
	v_mfma_f32_16x16x32_bf16 v[60:63], v[24:27], v[40:43], v[20:23]
	v_mfma_f32_16x16x32_bf16 v[20:23], v[194:197], v[32:35], v[146:149]
	v_mfma_f32_16x16x32_bf16 v[52:55], v[200:203], v[40:43], v[20:23]
	v_mfma_f32_16x16x32_bf16 v[20:23], v[10:13], v[216:219], v[150:153]
	v_mfma_f32_16x16x32_bf16 v[44:47], v[24:27], v[220:223], v[20:23]
	v_mfma_f32_16x16x32_bf16 v[20:23], v[194:197], v[216:219], v[154:157]
	v_mfma_f32_16x16x32_bf16 v[36:39], v[200:203], v[220:223], v[20:23]
	v_mfma_f32_16x16x32_bf16 v[20:23], v[10:13], v[228:231], v[158:161]
	v_mfma_f32_16x16x32_bf16 v[2:5], v[10:13], v[236:239], v[2:5]
	v_mfma_f32_16x16x32_bf16 v[28:31], v[24:27], v[232:235], v[20:23]
	v_mfma_f32_16x16x32_bf16 v[20:23], v[194:197], v[228:231], v[162:165]
	v_mfma_f32_16x16x32_bf16 v[12:15], v[24:27], v[240:243], v[2:5]
	v_mfma_f32_16x16x32_bf16 v[2:5], v[194:197], v[236:239], v[6:9]
	v_mfma_f32_16x16x32_bf16 v[20:23], v[200:203], v[232:235], v[20:23]
	v_mfma_f32_16x16x32_bf16 v[4:7], v[200:203], v[240:243], v[2:5]
	v_mfma_f32_16x16x32_bf16 v[8:11], v[204:207], v[32:35], v[166:169]
	v_mfma_f32_16x16x32_bf16 v[72:75], v[208:211], v[40:43], v[8:11]
	v_mfma_f32_16x16x32_bf16 v[8:11], v[212:215], v[32:35], v[170:173]
	v_mfma_f32_16x16x32_bf16 v[56:59], v[138:141], v[40:43], v[8:11]
	v_mfma_f32_16x16x32_bf16 v[8:11], v[204:207], v[216:219], v[174:177]
	v_mfma_f32_16x16x32_bf16 v[48:51], v[208:211], v[220:223], v[8:11]
	v_mfma_f32_16x16x32_bf16 v[8:11], v[212:215], v[216:219], v[178:181]
	v_mfma_f32_16x16x32_bf16 v[40:43], v[138:141], v[220:223], v[8:11]
	v_mfma_f32_16x16x32_bf16 v[8:11], v[204:207], v[228:231], v[182:185]
	v_mfma_f32_16x16x32_bf16 v[32:35], v[208:211], v[232:235], v[8:11]
	v_mfma_f32_16x16x32_bf16 v[8:11], v[212:215], v[228:231], v[186:189]
	v_mfma_f32_16x16x32_bf16 v[24:27], v[138:141], v[232:235], v[8:11]
	v_mfma_f32_16x16x32_bf16 v[8:11], v[204:207], v[236:239], v[16:19]
	v_mfma_f32_16x16x32_bf16 v[16:19], v[208:211], v[240:243], v[8:11]
	v_mfma_f32_16x16x32_bf16 v[8:11], v[212:215], v[236:239], v[190:193]
	v_mfma_f32_16x16x32_bf16 v[8:11], v[138:141], v[240:243], v[8:11]
	s_barrier
	s_setprio 0
	s_mov_b64 s[2:3], 0
	v_mov_b64_e32 v[234:235], v[226:227]
	v_mov_b32_e32 v226, v0
	v_mov_b64_e32 v[236:237], v[198:199]
	v_mov_b32_e32 v198, v225

; template <class Epi, bool ALIGN_EPI, bool SP2, class Hook>
; __device__ __forceinline__ void gemm_phase(LAS unsigned char* lds, const Gemm g, const StaticOrder& S, const Epi& E, Acc& acc, const bool fresh, const Hook& H, const int wave_id) {
;     ...
;         for (int t = t0; t < nt; t += 2) {
;             const bool last = (t == nt - 2);
;             const Src a1 = cA + (size_t)(t + 1) * kstep;
;             const Src a2 = last ? nA : cA + (size_t)(t + 2) * kstep, b2 = last ? nB : cB + (size_t)(t + 2) * kstep;
;             const Src a3 = a2 + kstep, b3 = b2 + kstep;
.LBB0_1461:
	v_add_u32_e32 v138, 0x10000, v136
	v_add_u32_e32 v139, 0x14000, v136
	ds_read_b128 v[140:143], v138
	ds_read_b128 v[144:147], v138 offset:1024
	ds_read_b128 v[148:151], v138 offset:2048
	ds_read_b128 v[152:155], v138 offset:3072
	ds_read_b128 v[156:159], v139
	ds_read_b128 v[160:163], v139 offset:1024
	ds_read_b128 v[164:167], v139 offset:2048
	ds_read_b128 v[168:171], v139 offset:3072
	s_add_i32 s16, s55, 0xfffc0080
	s_cmp_eq_u32 s54, 12
	s_cselect_b32 s59, s50, s16
	s_cselect_b32 s17, s9, s77
	s_cselect_b32 s16, s8, s76
	s_cselect_b32 s19, s11, s29
	s_cselect_b32 s18, s10, s28
	s_cselect_b32 s57, s51, s56
	s_cselect_b32 s20, s4, s12
	s_cselect_b32 s21, s5, s13
	s_cselect_b32 s22, s6, s14
	s_cselect_b32 s23, s7, s15
	s_or_b32 s58, s59, 0x80
	s_mov_b32 m0, s45
	ds_read_b128 v[172:175], v137
	ds_read_b128 v[176:179], v137 offset:1024
	ds_read_b128 v[180:183], v137 offset:2048
	ds_read_b128 v[184:187], v137 offset:3072
	ds_read_b128 v[188:191], v137 offset:4096
	ds_read_b128 v[192:195], v137 offset:5120
	ds_read_b128 v[200:203], v137 offset:6144
	ds_read_b128 v[204:207], v137 offset:7168
	buffer_load_dwordx4 v132, s[12:15], s55 offen lds
	s_mov_b32 m0, s46
	s_nop 0
	buffer_load_dwordx4 v134, s[12:15], s55 offen lds
	s_waitcnt vmcnt(8)
	s_waitcnt lgkmcnt(0)
	s_setprio 1
	s_barrier
	v_mfma_f32_16x16x32_bf16 v[124:127], v[140:143], v[172:175], v[124:127]
	v_mfma_f32_16x16x32_bf16 v[116:119], v[148:151], v[172:175], v[116:119]
	v_mfma_f32_16x16x32_bf16 v[108:111], v[140:143], v[180:183], v[108:111]
	v_mfma_f32_16x16x32_bf16 v[100:103], v[148:151], v[180:183], v[100:103]
	v_mfma_f32_16x16x32_bf16 v[92:95], v[140:143], v[188:191], v[92:95]
	v_mfma_f32_16x16x32_bf16 v[84:87], v[148:151], v[188:191], v[84:87]
	v_mfma_f32_16x16x32_bf16 v[76:79], v[140:143], v[200:203], v[76:79]
	v_mfma_f32_16x16x32_bf16 v[64:67], v[148:151], v[200:203], v[64:67]
	v_mfma_f32_16x16x32_bf16 v[124:127], v[144:147], v[176:179], v[124:127]
	v_mfma_f32_16x16x32_bf16 v[116:119], v[152:155], v[176:179], v[116:119]
	v_mfma_f32_16x16x32_bf16 v[108:111], v[144:147], v[184:187], v[108:111]
	v_mfma_f32_16x16x32_bf16 v[100:103], v[152:155], v[184:187], v[100:103]
	v_mfma_f32_16x16x32_bf16 v[92:95], v[144:147], v[192:195], v[92:95]
	v_mfma_f32_16x16x32_bf16 v[84:87], v[152:155], v[192:195], v[84:87]
	v_mfma_f32_16x16x32_bf16 v[76:79], v[144:147], v[204:207], v[76:79]
	v_mfma_f32_16x16x32_bf16 v[64:67], v[152:155], v[204:207], v[64:67]
	v_mfma_f32_16x16x32_bf16 v[128:131], v[156:159], v[172:175], v[128:131]
	v_mfma_f32_16x16x32_bf16 v[120:123], v[164:167], v[172:175], v[120:123]
	v_mfma_f32_16x16x32_bf16 v[112:115], v[156:159], v[180:183], v[112:115]
	v_mfma_f32_16x16x32_bf16 v[104:107], v[164:167], v[180:183], v[104:107]
	v_mfma_f32_16x16x32_bf16 v[96:99], v[156:159], v[188:191], v[96:99]
	v_mfma_f32_16x16x32_bf16 v[88:91], v[164:167], v[188:191], v[88:91]
	v_mfma_f32_16x16x32_bf16 v[80:83], v[156:159], v[200:203], v[80:83]
	v_mfma_f32_16x16x32_bf16 v[68:71], v[164:167], v[200:203], v[68:71]
	v_mfma_f32_16x16x32_bf16 v[128:131], v[160:163], v[176:179], v[128:131]
	v_mfma_f32_16x16x32_bf16 v[120:123], v[168:171], v[176:179], v[120:123]
	v_mfma_f32_16x16x32_bf16 v[112:115], v[160:163], v[184:187], v[112:115]
	v_mfma_f32_16x16x32_bf16 v[104:107], v[168:171], v[184:187], v[104:107]
	v_mfma_f32_16x16x32_bf16 v[96:99], v[160:163], v[192:195], v[96:99]
	v_mfma_f32_16x16x32_bf16 v[88:91], v[168:171], v[192:195], v[88:91]
	v_mfma_f32_16x16x32_bf16 v[80:83], v[160:163], v[204:207], v[80:83]
	v_mfma_f32_16x16x32_bf16 v[68:71], v[168:171], v[204:207], v[68:71]
	s_barrier
	s_setprio 0
	s_mov_b32 m0, s92
	ds_read_b128 v[172:175], v137 offset:16384
	ds_read_b128 v[176:179], v137 offset:17408
	ds_read_b128 v[180:183], v137 offset:18432
	ds_read_b128 v[184:187], v137 offset:19456
	ds_read_b128 v[188:191], v137 offset:20480
	ds_read_b128 v[192:195], v137 offset:21504
	ds_read_b128 v[200:203], v137 offset:22528
	ds_read_b128 v[204:207], v137 offset:23552
	buffer_load_dwordx4 v133, s[16:19], s57 offen lds
	s_mov_b32 m0, s93
	s_add_i32 s60, s57, 0x40000
	buffer_load_dwordx4 v135, s[16:19], s57 offen lds
	s_mov_b32 m0, s94
	s_nop 0
	buffer_load_dwordx4 v133, s[16:19], s60 offen lds
	s_mov_b32 m0, s95
	s_nop 0
	buffer_load_dwordx4 v135, s[16:19], s60 offen lds
	s_mov_b32 m0, s44
	s_nop 0
	buffer_load_dwordx4 v132, s[20:23], s59 offen lds
	s_mov_b32 m0, s36
	s_nop 0
	buffer_load_dwordx4 v134, s[20:23], s59 offen lds
	s_waitcnt vmcnt(8)
	s_waitcnt lgkmcnt(0)
	s_setprio 1
	s_barrier
	v_mfma_f32_16x16x32_bf16 v[60:63], v[140:143], v[172:175], v[60:63]
	v_mfma_f32_16x16x32_bf16 v[52:55], v[148:151], v[172:175], v[52:55]
	v_mfma_f32_16x16x32_bf16 v[44:47], v[140:143], v[180:183], v[44:47]
	v_mfma_f32_16x16x32_bf16 v[36:39], v[148:151], v[180:183], v[36:39]
	v_mfma_f32_16x16x32_bf16 v[28:31], v[140:143], v[188:191], v[28:31]
	v_mfma_f32_16x16x32_bf16 v[20:23], v[148:151], v[188:191], v[20:23]
	v_mfma_f32_16x16x32_bf16 v[12:15], v[140:143], v[200:203], v[12:15]
	v_mfma_f32_16x16x32_bf16 v[2:5], v[148:151], v[200:203], v[4:7]
	v_mfma_f32_16x16x32_bf16 v[60:63], v[144:147], v[176:179], v[60:63]
	v_mfma_f32_16x16x32_bf16 v[52:55], v[152:155], v[176:179], v[52:55]
	v_mfma_f32_16x16x32_bf16 v[44:47], v[144:147], v[184:187], v[44:47]
	v_mfma_f32_16x16x32_bf16 v[36:39], v[152:155], v[184:187], v[36:39]
	v_mfma_f32_16x16x32_bf16 v[28:31], v[144:147], v[192:195], v[28:31]
	v_mfma_f32_16x16x32_bf16 v[20:23], v[152:155], v[192:195], v[20:23]
	v_mfma_f32_16x16x32_bf16 v[12:15], v[144:147], v[204:207], v[12:15]
	v_mfma_f32_16x16x32_bf16 v[2:5], v[152:155], v[204:207], v[2:5]
	v_mfma_f32_16x16x32_bf16 v[72:75], v[156:159], v[172:175], v[72:75]
	v_mfma_f32_16x16x32_bf16 v[56:59], v[164:167], v[172:175], v[56:59]
	v_mfma_f32_16x16x32_bf16 v[48:51], v[156:159], v[180:183], v[48:51]
	v_mfma_f32_16x16x32_bf16 v[40:43], v[164:167], v[180:183], v[40:43]
	v_mfma_f32_16x16x32_bf16 v[32:35], v[156:159], v[188:191], v[32:35]
	v_mfma_f32_16x16x32_bf16 v[24:27], v[164:167], v[188:191], v[24:27]
	v_mfma_f32_16x16x32_bf16 v[16:19], v[156:159], v[200:203], v[16:19]
	v_mfma_f32_16x16x32_bf16 v[6:9], v[164:167], v[200:203], v[8:11]
	v_mfma_f32_16x16x32_bf16 v[72:75], v[160:163], v[176:179], v[72:75]
	v_mfma_f32_16x16x32_bf16 v[56:59], v[168:171], v[176:179], v[56:59]
	v_mfma_f32_16x16x32_bf16 v[48:51], v[160:163], v[184:187], v[48:51]
	v_mfma_f32_16x16x32_bf16 v[40:43], v[168:171], v[184:187], v[40:43]
	v_mfma_f32_16x16x32_bf16 v[32:35], v[160:163], v[192:195], v[32:35]
	v_mfma_f32_16x16x32_bf16 v[24:27], v[168:171], v[192:195], v[24:27]
	v_mfma_f32_16x16x32_bf16 v[16:19], v[160:163], v[204:207], v[16:19]
	v_mfma_f32_16x16x32_bf16 v[8:11], v[168:171], v[204:207], v[6:9]
	s_barrier
; #define PG8_BAR __builtin_amdgcn_s_barrier()
; template <class Epi, bool ALIGN_EPI, bool SP2, class Hook>
; __device__ __forceinline__ void gemm_phase(LAS unsigned char* lds, const Gemm g, const StaticOrder& S, const Epi& E, Acc& acc, const bool fresh, const Hook& H, const int wave_id) {
;     ...
;         if constexpr (ALIGN_EPI) { if (wr == 0) PG8_BAR; }
	s_setprio 0
	v_add_u32_e32 v140, 0x18000, v136
	v_add_u32_e32 v141, 0x1c000, v136
	ds_read_b128 v[142:145], v140
	ds_read_b128 v[146:149], v140 offset:1024
	ds_read_b128 v[150:153], v140 offset:2048
	ds_read_b128 v[154:157], v140 offset:3072
	ds_read_b128 v[158:161], v141
	ds_read_b128 v[162:165], v141 offset:1024
	ds_read_b128 v[166:169], v141 offset:2048
	ds_read_b128 v[170:173], v141 offset:3072
	s_add_i32 s59, s59, 0x40000
	s_mov_b32 m0, s37
	ds_read_b128 v[174:177], v137 offset:32768
	ds_read_b128 v[178:181], v137 offset:33792
	ds_read_b128 v[182:185], v137 offset:34816
	ds_read_b128 v[186:189], v137 offset:35840
	ds_read_b128 v[190:193], v137 offset:36864
	ds_read_b128 v[194:197], v137 offset:37888
	ds_read_b128 v[200:203], v137 offset:38912
	ds_read_b128 v[204:207], v137 offset:39936
	buffer_load_dwordx4 v132, s[20:23], s59 offen lds
	s_mov_b32 m0, s38
	s_nop 0
	buffer_load_dwordx4 v134, s[20:23], s59 offen lds
	s_waitcnt vmcnt(8)
	s_waitcnt lgkmcnt(0)
	s_setprio 1
	s_barrier
	v_mfma_f32_16x16x32_bf16 v[124:127], v[142:145], v[174:177], v[124:127]
	v_mfma_f32_16x16x32_bf16 v[116:119], v[150:153], v[174:177], v[116:119]
	v_mfma_f32_16x16x32_bf16 v[108:111], v[142:145], v[182:185], v[108:111]
	v_mfma_f32_16x16x32_bf16 v[100:103], v[150:153], v[182:185], v[100:103]
	v_mfma_f32_16x16x32_bf16 v[92:95], v[142:145], v[190:193], v[92:95]
	v_mfma_f32_16x16x32_bf16 v[84:87], v[150:153], v[190:193], v[84:87]
	v_mfma_f32_16x16x32_bf16 v[76:79], v[142:145], v[200:203], v[76:79]
	v_mfma_f32_16x16x32_bf16 v[64:67], v[150:153], v[200:203], v[64:67]
	v_mfma_f32_16x16x32_bf16 v[124:127], v[146:149], v[178:181], v[124:127]
	v_mfma_f32_16x16x32_bf16 v[116:119], v[154:157], v[178:181], v[116:119]
	v_mfma_f32_16x16x32_bf16 v[108:111], v[146:149], v[186:189], v[108:111]
	v_mfma_f32_16x16x32_bf16 v[100:103], v[154:157], v[186:189], v[100:103]
	v_mfma_f32_16x16x32_bf16 v[92:95], v[146:149], v[194:197], v[92:95]
	v_mfma_f32_16x16x32_bf16 v[84:87], v[154:157], v[194:197], v[84:87]
	v_mfma_f32_16x16x32_bf16 v[76:79], v[146:149], v[204:207], v[76:79]
	v_mfma_f32_16x16x32_bf16 v[64:67], v[154:157], v[204:207], v[64:67]
	v_mfma_f32_16x16x32_bf16 v[128:131], v[158:161], v[174:177], v[128:131]
	v_mfma_f32_16x16x32_bf16 v[120:123], v[166:169], v[174:177], v[120:123]
	v_mfma_f32_16x16x32_bf16 v[112:115], v[158:161], v[182:185], v[112:115]
	v_mfma_f32_16x16x32_bf16 v[104:107], v[166:169], v[182:185], v[104:107]
	v_mfma_f32_16x16x32_bf16 v[96:99], v[158:161], v[190:193], v[96:99]
	v_mfma_f32_16x16x32_bf16 v[88:91], v[166:169], v[190:193], v[88:91]
	v_mfma_f32_16x16x32_bf16 v[80:83], v[158:161], v[200:203], v[80:83]
	v_mfma_f32_16x16x32_bf16 v[68:71], v[166:169], v[200:203], v[68:71]
	v_mfma_f32_16x16x32_bf16 v[128:131], v[162:165], v[178:181], v[128:131]
	v_mfma_f32_16x16x32_bf16 v[120:123], v[170:173], v[178:181], v[120:123]
	v_mfma_f32_16x16x32_bf16 v[112:115], v[162:165], v[186:189], v[112:115]
	v_mfma_f32_16x16x32_bf16 v[104:107], v[170:173], v[186:189], v[104:107]
	v_mfma_f32_16x16x32_bf16 v[96:99], v[162:165], v[194:197], v[96:99]
	v_mfma_f32_16x16x32_bf16 v[88:91], v[170:173], v[194:197], v[88:91]
	v_mfma_f32_16x16x32_bf16 v[80:83], v[162:165], v[204:207], v[80:83]
	v_mfma_f32_16x16x32_bf16 v[68:71], v[170:173], v[204:207], v[68:71]
	s_barrier
	s_setprio 0
	s_mov_b32 m0, s39
	s_or_b32 s59, s57, 0x80
	ds_read_b128 v[174:177], v137 offset:49152
	ds_read_b128 v[178:181], v137 offset:50176
	ds_read_b128 v[182:185], v137 offset:51200
	ds_read_b128 v[186:189], v137 offset:52224
	ds_read_b128 v[190:193], v137 offset:53248
	ds_read_b128 v[194:197], v137 offset:54272
	ds_read_b128 v[200:203], v137 offset:55296
	ds_read_b128 v[204:207], v137 offset:56320
	buffer_load_dwordx4 v133, s[16:19], s59 offen lds
	s_mov_b32 m0, s40
	s_add_i32 s57, s57, 0x40080
	buffer_load_dwordx4 v135, s[16:19], s59 offen lds
	s_mov_b32 m0, s43
	s_nop 0
	buffer_load_dwordx4 v133, s[16:19], s57 offen lds
	s_mov_b32 m0, s42
	s_nop 0
	buffer_load_dwordx4 v135, s[16:19], s57 offen lds
	s_mov_b32 m0, s41
	s_nop 0
	buffer_load_dwordx4 v132, s[20:23], s58 offen lds
	s_mov_b32 m0, s33
	s_nop 0
	buffer_load_dwordx4 v134, s[20:23], s58 offen lds
	s_waitcnt vmcnt(8)
	s_waitcnt lgkmcnt(0)
	s_setprio 1
	s_barrier
	v_mfma_f32_16x16x32_bf16 v[60:63], v[142:145], v[174:177], v[60:63]
	v_mfma_f32_16x16x32_bf16 v[52:55], v[150:153], v[174:177], v[52:55]
	v_mfma_f32_16x16x32_bf16 v[44:47], v[142:145], v[182:185], v[44:47]
	v_mfma_f32_16x16x32_bf16 v[36:39], v[150:153], v[182:185], v[36:39]
	v_mfma_f32_16x16x32_bf16 v[28:31], v[142:145], v[190:193], v[28:31]
	v_mfma_f32_16x16x32_bf16 v[20:23], v[150:153], v[190:193], v[20:23]
	v_mfma_f32_16x16x32_bf16 v[12:15], v[142:145], v[200:203], v[12:15]
	v_mfma_f32_16x16x32_bf16 v[2:5], v[150:153], v[200:203], v[2:5]
	v_mfma_f32_16x16x32_bf16 v[60:63], v[146:149], v[178:181], v[60:63]
	v_mfma_f32_16x16x32_bf16 v[52:55], v[154:157], v[178:181], v[52:55]
	v_mfma_f32_16x16x32_bf16 v[44:47], v[146:149], v[186:189], v[44:47]
	v_mfma_f32_16x16x32_bf16 v[36:39], v[154:157], v[186:189], v[36:39]
	v_mfma_f32_16x16x32_bf16 v[28:31], v[146:149], v[194:197], v[28:31]
	v_mfma_f32_16x16x32_bf16 v[20:23], v[154:157], v[194:197], v[20:23]
	v_mfma_f32_16x16x32_bf16 v[12:15], v[146:149], v[204:207], v[12:15]
	v_mfma_f32_16x16x32_bf16 v[4:7], v[154:157], v[204:207], v[2:5]
	v_mfma_f32_16x16x32_bf16 v[72:75], v[158:161], v[174:177], v[72:75]
	v_mfma_f32_16x16x32_bf16 v[56:59], v[166:169], v[174:177], v[56:59]
	v_mfma_f32_16x16x32_bf16 v[48:51], v[158:161], v[182:185], v[48:51]
	v_mfma_f32_16x16x32_bf16 v[40:43], v[166:169], v[182:185], v[40:43]
	v_mfma_f32_16x16x32_bf16 v[32:35], v[158:161], v[190:193], v[32:35]
	v_mfma_f32_16x16x32_bf16 v[24:27], v[166:169], v[190:193], v[24:27]
	v_mfma_f32_16x16x32_bf16 v[16:19], v[158:161], v[200:203], v[16:19]
	v_mfma_f32_16x16x32_bf16 v[8:11], v[166:169], v[200:203], v[8:11]
	v_mfma_f32_16x16x32_bf16 v[72:75], v[162:165], v[178:181], v[72:75]
	v_mfma_f32_16x16x32_bf16 v[56:59], v[170:173], v[178:181], v[56:59]
	v_mfma_f32_16x16x32_bf16 v[48:51], v[162:165], v[186:189], v[48:51]
	v_mfma_f32_16x16x32_bf16 v[40:43], v[170:173], v[186:189], v[40:43]
	v_mfma_f32_16x16x32_bf16 v[32:35], v[162:165], v[194:197], v[32:35]
	v_mfma_f32_16x16x32_bf16 v[24:27], v[170:173], v[194:197], v[24:27]
	v_mfma_f32_16x16x32_bf16 v[16:19], v[162:165], v[204:207], v[16:19]
	v_mfma_f32_16x16x32_bf16 v[8:11], v[170:173], v[204:207], v[8:11]
	s_barrier
	s_setprio 0
	s_add_i32 s54, s54, 2
	s_addk_i32 s55, 0x100
	s_addk_i32 s56, 0x100
	s_cmp_gt_u32 s54, 13
	s_cbranch_scc0 .LBB0_1461
	v_readlane_b32 s12, v251, 45
	v_readlane_b32 s13, v251, 46
	s_and_b64 vcc, exec, s[12:13]
	s_cbranch_vccz .LBB0_1464
	s_barrier

; template <class Epi, bool ALIGN_EPI, bool SP2, class Hook>
; __device__ __forceinline__ void gemm_phase(LAS unsigned char* lds, const Gemm g, const StaticOrder& S, const Epi& E, Acc& acc, const bool fresh, const Hook& H, const int wave_id) {
;     ...
;         for (int t = t0; t < nt; t += 2) {
;             const bool last = (t == nt - 2);
;             const Src a1 = cA + (size_t)(t + 1) * kstep;
;             const Src a2 = last ? nA : cA + (size_t)(t + 2) * kstep, b2 = last ? nB : cB + (size_t)(t + 2) * kstep;
;             const Src a3 = a2 + kstep, b3 = b2 + kstep;
.LBB0_1572:
	v_add_u32_e32 v142, 0x10000, v161
	v_add_u32_e32 v163, 0x14000, v161
	ds_read_b128 v[130:133], v142
	ds_read_b128 v[134:137], v142 offset:1024
	ds_read_b128 v[138:141], v142 offset:2048
	ds_read_b128 v[142:145], v142 offset:3072
	ds_read_b128 v[146:149], v163
	ds_read_b128 v[150:153], v163 offset:1024
	ds_read_b128 v[154:157], v163 offset:2048
	ds_read_b128 v[164:167], v163 offset:3072
	s_add_i32 s16, s2, 0xfff40080
	s_cmp_eq_u32 s61, 40
	s_cselect_b32 s64, s57, s16
	s_cselect_b32 s17, s35, s9
	s_cselect_b32 s16, s34, s8
	s_cselect_b32 s19, s51, s53
	s_cselect_b32 s18, s50, s52
	s_cselect_b32 s62, s58, s3
	s_cselect_b32 s20, s10, s12
	s_cselect_b32 s21, s11, s13
	s_cselect_b32 s22, s30, s14
	s_cselect_b32 s23, s31, s15
	s_or_b32 s63, s64, 0x80
	s_mov_b32 m0, s45
	ds_read_b128 v[168:171], v162
	ds_read_b128 v[172:175], v162 offset:1024
	ds_read_b128 v[176:179], v162 offset:2048
	ds_read_b128 v[180:183], v162 offset:3072
	ds_read_b128 v[184:187], v162 offset:4096
	ds_read_b128 v[188:191], v162 offset:5120
	ds_read_b128 v[192:195], v162 offset:6144
	ds_read_b128 v[200:203], v162 offset:7168
	buffer_load_dwordx4 v0, s[12:15], s2 offen lds
	s_mov_b32 m0, s46
	s_nop 0
	buffer_load_dwordx4 v159, s[12:15], s2 offen lds
	s_waitcnt vmcnt(8)
	s_waitcnt lgkmcnt(0)
	s_setprio 1
	s_barrier
	v_mfma_f32_16x16x32_bf16 v[126:129], v[130:133], v[168:171], v[126:129]
	v_mfma_f32_16x16x32_bf16 v[122:125], v[138:141], v[168:171], v[122:125]
	v_mfma_f32_16x16x32_bf16 v[110:113], v[130:133], v[176:179], v[110:113]
	v_mfma_f32_16x16x32_bf16 v[106:109], v[138:141], v[176:179], v[106:109]
	v_mfma_f32_16x16x32_bf16 v[94:97], v[130:133], v[184:187], v[94:97]
	v_mfma_f32_16x16x32_bf16 v[90:93], v[138:141], v[184:187], v[90:93]
	v_mfma_f32_16x16x32_bf16 v[78:81], v[130:133], v[192:195], v[78:81]
	v_mfma_f32_16x16x32_bf16 v[74:77], v[138:141], v[192:195], v[74:77]
	v_mfma_f32_16x16x32_bf16 v[126:129], v[134:137], v[172:175], v[126:129]
	v_mfma_f32_16x16x32_bf16 v[122:125], v[142:145], v[172:175], v[122:125]
	v_mfma_f32_16x16x32_bf16 v[110:113], v[134:137], v[180:183], v[110:113]
	v_mfma_f32_16x16x32_bf16 v[106:109], v[142:145], v[180:183], v[106:109]
	v_mfma_f32_16x16x32_bf16 v[94:97], v[134:137], v[188:191], v[94:97]
	v_mfma_f32_16x16x32_bf16 v[90:93], v[142:145], v[188:191], v[90:93]
	v_mfma_f32_16x16x32_bf16 v[78:81], v[134:137], v[200:203], v[78:81]
	v_mfma_f32_16x16x32_bf16 v[74:77], v[142:145], v[200:203], v[74:77]
	v_mfma_f32_16x16x32_bf16 v[118:121], v[146:149], v[168:171], v[118:121]
	v_mfma_f32_16x16x32_bf16 v[114:117], v[154:157], v[168:171], v[114:117]
	v_mfma_f32_16x16x32_bf16 v[102:105], v[146:149], v[176:179], v[102:105]
	v_mfma_f32_16x16x32_bf16 v[98:101], v[154:157], v[176:179], v[98:101]
	v_mfma_f32_16x16x32_bf16 v[86:89], v[146:149], v[184:187], v[86:89]
	v_mfma_f32_16x16x32_bf16 v[82:85], v[154:157], v[184:187], v[82:85]
	v_mfma_f32_16x16x32_bf16 v[70:73], v[146:149], v[192:195], v[70:73]
	v_mfma_f32_16x16x32_bf16 v[66:69], v[154:157], v[192:195], v[66:69]
	v_mfma_f32_16x16x32_bf16 v[118:121], v[150:153], v[172:175], v[118:121]
	v_mfma_f32_16x16x32_bf16 v[114:117], v[164:167], v[172:175], v[114:117]
	v_mfma_f32_16x16x32_bf16 v[102:105], v[150:153], v[180:183], v[102:105]
	v_mfma_f32_16x16x32_bf16 v[98:101], v[164:167], v[180:183], v[98:101]
	v_mfma_f32_16x16x32_bf16 v[86:89], v[150:153], v[188:191], v[86:89]
	v_mfma_f32_16x16x32_bf16 v[82:85], v[164:167], v[188:191], v[82:85]
	v_mfma_f32_16x16x32_bf16 v[70:73], v[150:153], v[200:203], v[70:73]
	v_mfma_f32_16x16x32_bf16 v[66:69], v[164:167], v[200:203], v[66:69]
	s_barrier
	s_setprio 0
	s_mov_b32 m0, s92
	ds_read_b128 v[168:171], v162 offset:16384
	ds_read_b128 v[172:175], v162 offset:17408
	ds_read_b128 v[176:179], v162 offset:18432
	ds_read_b128 v[180:183], v162 offset:19456
	ds_read_b128 v[184:187], v162 offset:20480
	ds_read_b128 v[188:191], v162 offset:21504
	ds_read_b128 v[192:195], v162 offset:22528
	ds_read_b128 v[200:203], v162 offset:23552
	buffer_load_dwordx4 v158, s[16:19], s62 offen lds
	s_mov_b32 m0, s93
	s_add_i32 s65, s62, 0xb0000
	buffer_load_dwordx4 v160, s[16:19], s62 offen lds
	s_mov_b32 m0, s94
	s_nop 0
	buffer_load_dwordx4 v158, s[16:19], s65 offen lds
	s_mov_b32 m0, s95
	s_nop 0
	buffer_load_dwordx4 v160, s[16:19], s65 offen lds
	s_mov_b32 m0, s44
	s_nop 0
	buffer_load_dwordx4 v0, s[20:23], s64 offen lds
	s_mov_b32 m0, s36
	s_nop 0
	buffer_load_dwordx4 v159, s[20:23], s64 offen lds
	s_waitcnt vmcnt(8)
	s_waitcnt lgkmcnt(0)
	s_setprio 1
	s_barrier
	v_mfma_f32_16x16x32_bf16 v[62:65], v[130:133], v[168:171], v[62:65]
	v_mfma_f32_16x16x32_bf16 v[58:61], v[138:141], v[168:171], v[58:61]
	v_mfma_f32_16x16x32_bf16 v[46:49], v[130:133], v[176:179], v[46:49]
	v_mfma_f32_16x16x32_bf16 v[42:45], v[138:141], v[176:179], v[42:45]
	v_mfma_f32_16x16x32_bf16 v[30:33], v[130:133], v[184:187], v[30:33]
	v_mfma_f32_16x16x32_bf16 v[26:29], v[138:141], v[184:187], v[26:29]
	v_mfma_f32_16x16x32_bf16 v[14:17], v[130:133], v[192:195], v[14:17]
	v_mfma_f32_16x16x32_bf16 v[10:13], v[138:141], v[192:195], v[10:13]
	v_mfma_f32_16x16x32_bf16 v[62:65], v[134:137], v[172:175], v[62:65]
	v_mfma_f32_16x16x32_bf16 v[58:61], v[142:145], v[172:175], v[58:61]
	v_mfma_f32_16x16x32_bf16 v[46:49], v[134:137], v[180:183], v[46:49]
	v_mfma_f32_16x16x32_bf16 v[42:45], v[142:145], v[180:183], v[42:45]
	v_mfma_f32_16x16x32_bf16 v[30:33], v[134:137], v[188:191], v[30:33]
	v_mfma_f32_16x16x32_bf16 v[26:29], v[142:145], v[188:191], v[26:29]
	v_mfma_f32_16x16x32_bf16 v[14:17], v[134:137], v[200:203], v[14:17]
	v_mfma_f32_16x16x32_bf16 v[10:13], v[142:145], v[200:203], v[10:13]
	v_mfma_f32_16x16x32_bf16 v[54:57], v[146:149], v[168:171], v[54:57]
	v_mfma_f32_16x16x32_bf16 v[50:53], v[154:157], v[168:171], v[50:53]
	v_mfma_f32_16x16x32_bf16 v[38:41], v[146:149], v[176:179], v[38:41]
	v_mfma_f32_16x16x32_bf16 v[34:37], v[154:157], v[176:179], v[34:37]
	v_mfma_f32_16x16x32_bf16 v[22:25], v[146:149], v[184:187], v[22:25]
	v_mfma_f32_16x16x32_bf16 v[18:21], v[154:157], v[184:187], v[18:21]
	v_mfma_f32_16x16x32_bf16 v[6:9], v[146:149], v[192:195], v[6:9]
	v_mfma_f32_16x16x32_bf16 v[2:5], v[154:157], v[192:195], v[2:5]
	v_mfma_f32_16x16x32_bf16 v[54:57], v[150:153], v[172:175], v[54:57]
	v_mfma_f32_16x16x32_bf16 v[50:53], v[164:167], v[172:175], v[50:53]
	v_mfma_f32_16x16x32_bf16 v[38:41], v[150:153], v[180:183], v[38:41]
	v_mfma_f32_16x16x32_bf16 v[34:37], v[164:167], v[180:183], v[34:37]
	v_mfma_f32_16x16x32_bf16 v[22:25], v[150:153], v[188:191], v[22:25]
	v_mfma_f32_16x16x32_bf16 v[18:21], v[164:167], v[188:191], v[18:21]
	v_mfma_f32_16x16x32_bf16 v[6:9], v[150:153], v[200:203], v[6:9]
	v_mfma_f32_16x16x32_bf16 v[2:5], v[164:167], v[200:203], v[2:5]
	s_barrier
; #define PG8_BAR __builtin_amdgcn_s_barrier()
; template <class Epi, bool ALIGN_EPI, bool SP2, class Hook>
; __device__ __forceinline__ void gemm_phase(LAS unsigned char* lds, const Gemm g, const StaticOrder& S, const Epi& E, Acc& acc, const bool fresh, const Hook& H, const int wave_id) {
;     ...
;         if constexpr (ALIGN_EPI) { if (wr == 0) PG8_BAR; }
	s_setprio 0
	v_add_u32_e32 v142, 0x18000, v161
	v_add_u32_e32 v163, 0x1c000, v161
	ds_read_b128 v[130:133], v142
	ds_read_b128 v[134:137], v142 offset:1024
	ds_read_b128 v[138:141], v142 offset:2048
	ds_read_b128 v[142:145], v142 offset:3072
	ds_read_b128 v[146:149], v163
	ds_read_b128 v[150:153], v163 offset:1024
	ds_read_b128 v[154:157], v163 offset:2048
	ds_read_b128 v[164:167], v163 offset:3072
	s_add_i32 s64, s64, 0xc0000
	s_mov_b32 m0, s37
	ds_read_b128 v[168:171], v162 offset:32768
	ds_read_b128 v[172:175], v162 offset:33792
	ds_read_b128 v[176:179], v162 offset:34816
	ds_read_b128 v[180:183], v162 offset:35840
	ds_read_b128 v[184:187], v162 offset:36864
	ds_read_b128 v[188:191], v162 offset:37888
	ds_read_b128 v[192:195], v162 offset:38912
	ds_read_b128 v[200:203], v162 offset:39936
	buffer_load_dwordx4 v0, s[20:23], s64 offen lds
	s_mov_b32 m0, s38
	s_nop 0
	buffer_load_dwordx4 v159, s[20:23], s64 offen lds
	s_waitcnt vmcnt(8)
	s_waitcnt lgkmcnt(0)
	s_setprio 1
	s_barrier
	v_mfma_f32_16x16x32_bf16 v[126:129], v[130:133], v[168:171], v[126:129]
	v_mfma_f32_16x16x32_bf16 v[122:125], v[138:141], v[168:171], v[122:125]
	v_mfma_f32_16x16x32_bf16 v[110:113], v[130:133], v[176:179], v[110:113]
	v_mfma_f32_16x16x32_bf16 v[106:109], v[138:141], v[176:179], v[106:109]
	v_mfma_f32_16x16x32_bf16 v[94:97], v[130:133], v[184:187], v[94:97]
	v_mfma_f32_16x16x32_bf16 v[90:93], v[138:141], v[184:187], v[90:93]
	v_mfma_f32_16x16x32_bf16 v[78:81], v[130:133], v[192:195], v[78:81]
	v_mfma_f32_16x16x32_bf16 v[74:77], v[138:141], v[192:195], v[74:77]
	v_mfma_f32_16x16x32_bf16 v[126:129], v[134:137], v[172:175], v[126:129]
	v_mfma_f32_16x16x32_bf16 v[122:125], v[142:145], v[172:175], v[122:125]
	v_mfma_f32_16x16x32_bf16 v[110:113], v[134:137], v[180:183], v[110:113]
	v_mfma_f32_16x16x32_bf16 v[106:109], v[142:145], v[180:183], v[106:109]
	v_mfma_f32_16x16x32_bf16 v[94:97], v[134:137], v[188:191], v[94:97]
	v_mfma_f32_16x16x32_bf16 v[90:93], v[142:145], v[188:191], v[90:93]
	v_mfma_f32_16x16x32_bf16 v[78:81], v[134:137], v[200:203], v[78:81]
	v_mfma_f32_16x16x32_bf16 v[74:77], v[142:145], v[200:203], v[74:77]
	v_mfma_f32_16x16x32_bf16 v[118:121], v[146:149], v[168:171], v[118:121]
	v_mfma_f32_16x16x32_bf16 v[114:117], v[154:157], v[168:171], v[114:117]
	v_mfma_f32_16x16x32_bf16 v[102:105], v[146:149], v[176:179], v[102:105]
	v_mfma_f32_16x16x32_bf16 v[98:101], v[154:157], v[176:179], v[98:101]
	v_mfma_f32_16x16x32_bf16 v[86:89], v[146:149], v[184:187], v[86:89]
	v_mfma_f32_16x16x32_bf16 v[82:85], v[154:157], v[184:187], v[82:85]
	v_mfma_f32_16x16x32_bf16 v[70:73], v[146:149], v[192:195], v[70:73]
	v_mfma_f32_16x16x32_bf16 v[66:69], v[154:157], v[192:195], v[66:69]
	v_mfma_f32_16x16x32_bf16 v[118:121], v[150:153], v[172:175], v[118:121]
	v_mfma_f32_16x16x32_bf16 v[114:117], v[164:167], v[172:175], v[114:117]
	v_mfma_f32_16x16x32_bf16 v[102:105], v[150:153], v[180:183], v[102:105]
	v_mfma_f32_16x16x32_bf16 v[98:101], v[164:167], v[180:183], v[98:101]
	v_mfma_f32_16x16x32_bf16 v[86:89], v[150:153], v[188:191], v[86:89]
	v_mfma_f32_16x16x32_bf16 v[82:85], v[164:167], v[188:191], v[82:85]
	v_mfma_f32_16x16x32_bf16 v[70:73], v[150:153], v[200:203], v[70:73]
	v_mfma_f32_16x16x32_bf16 v[66:69], v[164:167], v[200:203], v[66:69]
	s_barrier
	s_setprio 0
	s_mov_b32 m0, s39
	s_or_b32 s64, s62, 0x80
	ds_read_b128 v[168:171], v162 offset:49152
	ds_read_b128 v[172:175], v162 offset:50176
	ds_read_b128 v[176:179], v162 offset:51200
	ds_read_b128 v[180:183], v162 offset:52224
	ds_read_b128 v[184:187], v162 offset:53248
	ds_read_b128 v[188:191], v162 offset:54272
	ds_read_b128 v[192:195], v162 offset:55296
	ds_read_b128 v[200:203], v162 offset:56320
	buffer_load_dwordx4 v158, s[16:19], s64 offen lds
	s_mov_b32 m0, s40
	s_add_i32 s62, s62, 0xb0080
	buffer_load_dwordx4 v160, s[16:19], s64 offen lds
	s_mov_b32 m0, s43
	s_nop 0
	buffer_load_dwordx4 v158, s[16:19], s62 offen lds
	s_mov_b32 m0, s42
	s_nop 0
	buffer_load_dwordx4 v160, s[16:19], s62 offen lds
	s_mov_b32 m0, s41
	s_nop 0
	buffer_load_dwordx4 v0, s[20:23], s63 offen lds
	s_mov_b32 m0, s33
	s_nop 0
	buffer_load_dwordx4 v159, s[20:23], s63 offen lds
	s_waitcnt vmcnt(8)
	s_waitcnt lgkmcnt(0)
	s_setprio 1
	s_barrier
	v_mfma_f32_16x16x32_bf16 v[62:65], v[130:133], v[168:171], v[62:65]
	v_mfma_f32_16x16x32_bf16 v[58:61], v[138:141], v[168:171], v[58:61]
	v_mfma_f32_16x16x32_bf16 v[46:49], v[130:133], v[176:179], v[46:49]
	v_mfma_f32_16x16x32_bf16 v[42:45], v[138:141], v[176:179], v[42:45]
	v_mfma_f32_16x16x32_bf16 v[30:33], v[130:133], v[184:187], v[30:33]
	v_mfma_f32_16x16x32_bf16 v[26:29], v[138:141], v[184:187], v[26:29]
	v_mfma_f32_16x16x32_bf16 v[14:17], v[130:133], v[192:195], v[14:17]
	v_mfma_f32_16x16x32_bf16 v[10:13], v[138:141], v[192:195], v[10:13]
	v_mfma_f32_16x16x32_bf16 v[62:65], v[134:137], v[172:175], v[62:65]
	v_mfma_f32_16x16x32_bf16 v[58:61], v[142:145], v[172:175], v[58:61]
	v_mfma_f32_16x16x32_bf16 v[46:49], v[134:137], v[180:183], v[46:49]
	v_mfma_f32_16x16x32_bf16 v[42:45], v[142:145], v[180:183], v[42:45]
	v_mfma_f32_16x16x32_bf16 v[30:33], v[134:137], v[188:191], v[30:33]
	v_mfma_f32_16x16x32_bf16 v[26:29], v[142:145], v[188:191], v[26:29]
	v_mfma_f32_16x16x32_bf16 v[14:17], v[134:137], v[200:203], v[14:17]
	v_mfma_f32_16x16x32_bf16 v[10:13], v[142:145], v[200:203], v[10:13]
	v_mfma_f32_16x16x32_bf16 v[54:57], v[146:149], v[168:171], v[54:57]
	v_mfma_f32_16x16x32_bf16 v[50:53], v[154:157], v[168:171], v[50:53]
	v_mfma_f32_16x16x32_bf16 v[38:41], v[146:149], v[176:179], v[38:41]
	v_mfma_f32_16x16x32_bf16 v[34:37], v[154:157], v[176:179], v[34:37]
	v_mfma_f32_16x16x32_bf16 v[22:25], v[146:149], v[184:187], v[22:25]
	v_mfma_f32_16x16x32_bf16 v[18:21], v[154:157], v[184:187], v[18:21]
	v_mfma_f32_16x16x32_bf16 v[6:9], v[146:149], v[192:195], v[6:9]
	v_mfma_f32_16x16x32_bf16 v[2:5], v[154:157], v[192:195], v[2:5]
	v_mfma_f32_16x16x32_bf16 v[54:57], v[150:153], v[172:175], v[54:57]
	v_mfma_f32_16x16x32_bf16 v[50:53], v[164:167], v[172:175], v[50:53]
	v_mfma_f32_16x16x32_bf16 v[38:41], v[150:153], v[180:183], v[38:41]
	v_mfma_f32_16x16x32_bf16 v[34:37], v[164:167], v[180:183], v[34:37]
	v_mfma_f32_16x16x32_bf16 v[22:25], v[150:153], v[188:191], v[22:25]
	v_mfma_f32_16x16x32_bf16 v[18:21], v[164:167], v[188:191], v[18:21]
	v_mfma_f32_16x16x32_bf16 v[6:9], v[150:153], v[200:203], v[6:9]
	v_mfma_f32_16x16x32_bf16 v[2:5], v[164:167], v[200:203], v[2:5]
	s_barrier
	s_setprio 0
	s_add_i32 s61, s61, 2
	s_addk_i32 s2, 0x100
	s_addk_i32 s3, 0x100
	s_cmp_gt_u32 s61, 41
	s_cbranch_scc0 .LBB0_1572
	v_readlane_b32 s2, v251, 45
	v_readlane_b32 s3, v251, 46
	s_and_b64 vcc, exec, s[2:3]
	s_cbranch_vccz .LBB0_1575
	s_barrier

; template <class Epi, bool ALIGN_EPI, bool SP2, class Hook>
; __device__ __forceinline__ void gemm_phase(LAS unsigned char* lds, const Gemm g, const StaticOrder& S, const Epi& E, Acc& acc, const bool fresh, const Hook& H, const int wave_id) {
;     ...
;         for (int t = t0; t < nt; t += 2) {
;             const bool last = (t == nt - 2);
;             const Src a1 = cA + (size_t)(t + 1) * kstep;
;             const Src a2 = last ? nA : cA + (size_t)(t + 2) * kstep, b2 = last ? nB : cB + (size_t)(t + 2) * kstep;
;             const Src a3 = a2 + kstep, b3 = b2 + kstep;
.LBB0_1614:
	v_add_u32_e32 v0, 0x10000, v172
	ds_read_b128 v[130:133], v0
	ds_read_b128 v[134:137], v0 offset:1024
	ds_read_b128 v[138:141], v0 offset:2048
	ds_read_b128 v[142:145], v0 offset:3072
	v_add_u32_e32 v0, 0x14000, v172
	ds_read_b128 v[146:149], v0
	ds_read_b128 v[150:153], v0 offset:1024
	ds_read_b128 v[154:157], v0 offset:2048
	ds_read_b128 v[158:161], v0 offset:3072
	s_add_i32 s12, s2, 0xfff40080
	s_cmp_eq_u32 s59, 40
	s_cselect_b32 s62, s55, s12
	s_cselect_b32 s13, s31, s77
	s_cselect_b32 s12, s30, s76
	s_cselect_b32 s15, s35, s51
	s_cselect_b32 s14, s34, s50
	s_cselect_b32 s60, s56, s3
	s_cselect_b32 s16, s20, s8
	s_cselect_b32 s17, s21, s9
	s_cselect_b32 s18, s22, s10
	s_cselect_b32 s19, s23, s11
	s_or_b32 s61, s62, 0x80
	s_mov_b32 m0, s45
	ds_read_b128 v[162:165], v173
	ds_read_b128 v[174:177], v173 offset:1024
	ds_read_b128 v[178:181], v173 offset:2048
	ds_read_b128 v[182:185], v173 offset:3072
	ds_read_b128 v[186:189], v173 offset:4096
	ds_read_b128 v[190:193], v173 offset:5120
	ds_read_b128 v[194:197], v173 offset:6144
	ds_read_b128 v[200:203], v173 offset:7168
	buffer_load_dwordx4 v168, s[8:11], s2 offen lds
	s_mov_b32 m0, s46
	s_nop 0
	buffer_load_dwordx4 v170, s[8:11], s2 offen lds
	s_waitcnt vmcnt(8)
	s_waitcnt lgkmcnt(0)
	s_setprio 1
	s_barrier
	v_mfma_f32_16x16x32_bf16 v[126:129], v[130:133], v[162:165], v[126:129]
	v_mfma_f32_16x16x32_bf16 v[122:125], v[138:141], v[162:165], v[122:125]
	v_mfma_f32_16x16x32_bf16 v[110:113], v[130:133], v[178:181], v[110:113]
	v_mfma_f32_16x16x32_bf16 v[106:109], v[138:141], v[178:181], v[106:109]
	v_mfma_f32_16x16x32_bf16 v[94:97], v[130:133], v[186:189], v[94:97]
	v_mfma_f32_16x16x32_bf16 v[90:93], v[138:141], v[186:189], v[90:93]
	v_mfma_f32_16x16x32_bf16 v[78:81], v[130:133], v[194:197], v[78:81]
	v_mfma_f32_16x16x32_bf16 v[74:77], v[138:141], v[194:197], v[74:77]
	v_mfma_f32_16x16x32_bf16 v[126:129], v[134:137], v[174:177], v[126:129]
	v_mfma_f32_16x16x32_bf16 v[122:125], v[142:145], v[174:177], v[122:125]
	v_mfma_f32_16x16x32_bf16 v[110:113], v[134:137], v[182:185], v[110:113]
	v_mfma_f32_16x16x32_bf16 v[106:109], v[142:145], v[182:185], v[106:109]
	v_mfma_f32_16x16x32_bf16 v[94:97], v[134:137], v[190:193], v[94:97]
	v_mfma_f32_16x16x32_bf16 v[90:93], v[142:145], v[190:193], v[90:93]
	v_mfma_f32_16x16x32_bf16 v[78:81], v[134:137], v[200:203], v[78:81]
	v_mfma_f32_16x16x32_bf16 v[74:77], v[142:145], v[200:203], v[74:77]
	v_mfma_f32_16x16x32_bf16 v[118:121], v[146:149], v[162:165], v[118:121]
	v_mfma_f32_16x16x32_bf16 v[114:117], v[154:157], v[162:165], v[114:117]
	v_mfma_f32_16x16x32_bf16 v[102:105], v[146:149], v[178:181], v[102:105]
	v_mfma_f32_16x16x32_bf16 v[98:101], v[154:157], v[178:181], v[98:101]
	v_mfma_f32_16x16x32_bf16 v[86:89], v[146:149], v[186:189], v[86:89]
	v_mfma_f32_16x16x32_bf16 v[82:85], v[154:157], v[186:189], v[82:85]
	v_mfma_f32_16x16x32_bf16 v[70:73], v[146:149], v[194:197], v[70:73]
	v_mfma_f32_16x16x32_bf16 v[66:69], v[154:157], v[194:197], v[66:69]
	v_mfma_f32_16x16x32_bf16 v[118:121], v[150:153], v[174:177], v[118:121]
	v_mfma_f32_16x16x32_bf16 v[114:117], v[158:161], v[174:177], v[114:117]
	v_mfma_f32_16x16x32_bf16 v[102:105], v[150:153], v[182:185], v[102:105]
	v_mfma_f32_16x16x32_bf16 v[98:101], v[158:161], v[182:185], v[98:101]
	v_mfma_f32_16x16x32_bf16 v[86:89], v[150:153], v[190:193], v[86:89]
	v_mfma_f32_16x16x32_bf16 v[82:85], v[158:161], v[190:193], v[82:85]
	v_mfma_f32_16x16x32_bf16 v[70:73], v[150:153], v[200:203], v[70:73]
	v_mfma_f32_16x16x32_bf16 v[66:69], v[158:161], v[200:203], v[66:69]
	s_barrier
	s_setprio 0
	s_mov_b32 m0, s92
	ds_read_b128 v[162:165], v173 offset:16384
	ds_read_b128 v[174:177], v173 offset:17408
	ds_read_b128 v[178:181], v173 offset:18432
	ds_read_b128 v[182:185], v173 offset:19456
	ds_read_b128 v[186:189], v173 offset:20480
	ds_read_b128 v[190:193], v173 offset:21504
	ds_read_b128 v[194:197], v173 offset:22528
	ds_read_b128 v[200:203], v173 offset:23552
	buffer_load_dwordx4 v169, s[12:15], s60 offen lds
	s_mov_b32 m0, s93
	s_add_i32 s63, s60, 0xb0000
	buffer_load_dwordx4 v171, s[12:15], s60 offen lds
	s_mov_b32 m0, s94
	s_nop 0
	buffer_load_dwordx4 v169, s[12:15], s63 offen lds
	s_mov_b32 m0, s95
	s_nop 0
	buffer_load_dwordx4 v171, s[12:15], s63 offen lds
	s_mov_b32 m0, s44
	s_nop 0
	buffer_load_dwordx4 v168, s[16:19], s62 offen lds
	s_mov_b32 m0, s36
	s_nop 0
	buffer_load_dwordx4 v170, s[16:19], s62 offen lds
	s_waitcnt vmcnt(8)
	s_waitcnt lgkmcnt(0)
	s_setprio 1
	s_barrier
	v_mfma_f32_16x16x32_bf16 v[62:65], v[130:133], v[162:165], v[62:65]
	v_mfma_f32_16x16x32_bf16 v[58:61], v[138:141], v[162:165], v[58:61]
	v_mfma_f32_16x16x32_bf16 v[46:49], v[130:133], v[178:181], v[46:49]
	v_mfma_f32_16x16x32_bf16 v[42:45], v[138:141], v[178:181], v[42:45]
	v_mfma_f32_16x16x32_bf16 v[30:33], v[130:133], v[186:189], v[30:33]
	v_mfma_f32_16x16x32_bf16 v[26:29], v[138:141], v[186:189], v[26:29]
	v_mfma_f32_16x16x32_bf16 v[14:17], v[130:133], v[194:197], v[14:17]
	v_mfma_f32_16x16x32_bf16 v[10:13], v[138:141], v[194:197], v[10:13]
	v_mfma_f32_16x16x32_bf16 v[62:65], v[134:137], v[174:177], v[62:65]
	v_mfma_f32_16x16x32_bf16 v[58:61], v[142:145], v[174:177], v[58:61]
	v_mfma_f32_16x16x32_bf16 v[46:49], v[134:137], v[182:185], v[46:49]
	v_mfma_f32_16x16x32_bf16 v[42:45], v[142:145], v[182:185], v[42:45]
	v_mfma_f32_16x16x32_bf16 v[30:33], v[134:137], v[190:193], v[30:33]
	v_mfma_f32_16x16x32_bf16 v[26:29], v[142:145], v[190:193], v[26:29]
	v_mfma_f32_16x16x32_bf16 v[14:17], v[134:137], v[200:203], v[14:17]
	v_mfma_f32_16x16x32_bf16 v[10:13], v[142:145], v[200:203], v[10:13]
	v_mfma_f32_16x16x32_bf16 v[54:57], v[146:149], v[162:165], v[54:57]
	v_mfma_f32_16x16x32_bf16 v[50:53], v[154:157], v[162:165], v[50:53]
	v_mfma_f32_16x16x32_bf16 v[38:41], v[146:149], v[178:181], v[38:41]
	v_mfma_f32_16x16x32_bf16 v[34:37], v[154:157], v[178:181], v[34:37]
	v_mfma_f32_16x16x32_bf16 v[22:25], v[146:149], v[186:189], v[22:25]
	v_mfma_f32_16x16x32_bf16 v[18:21], v[154:157], v[186:189], v[18:21]
	v_mfma_f32_16x16x32_bf16 v[6:9], v[146:149], v[194:197], v[6:9]
	v_mfma_f32_16x16x32_bf16 v[2:5], v[154:157], v[194:197], v[2:5]
	v_mfma_f32_16x16x32_bf16 v[54:57], v[150:153], v[174:177], v[54:57]
	v_mfma_f32_16x16x32_bf16 v[50:53], v[158:161], v[174:177], v[50:53]
	v_mfma_f32_16x16x32_bf16 v[38:41], v[150:153], v[182:185], v[38:41]
	v_mfma_f32_16x16x32_bf16 v[34:37], v[158:161], v[182:185], v[34:37]
	v_mfma_f32_16x16x32_bf16 v[22:25], v[150:153], v[190:193], v[22:25]
	v_mfma_f32_16x16x32_bf16 v[18:21], v[158:161], v[190:193], v[18:21]
	v_mfma_f32_16x16x32_bf16 v[6:9], v[150:153], v[200:203], v[6:9]
	v_mfma_f32_16x16x32_bf16 v[2:5], v[158:161], v[200:203], v[2:5]
	s_barrier
; #define PG8_BAR __builtin_amdgcn_s_barrier()
; template <class Epi, bool ALIGN_EPI, bool SP2, class Hook>
; __device__ __forceinline__ void gemm_phase(LAS unsigned char* lds, const Gemm g, const StaticOrder& S, const Epi& E, Acc& acc, const bool fresh, const Hook& H, const int wave_id) {
;     ...
;         if constexpr (ALIGN_EPI) { if (wr == 0) PG8_BAR; }
	s_setprio 0
	v_add_u32_e32 v0, 0x18000, v172
	ds_read_b128 v[130:133], v0
	ds_read_b128 v[134:137], v0 offset:1024
	ds_read_b128 v[138:141], v0 offset:2048
	ds_read_b128 v[142:145], v0 offset:3072
	v_add_u32_e32 v0, 0x1c000, v172
	ds_read_b128 v[146:149], v0
	ds_read_b128 v[150:153], v0 offset:1024
	ds_read_b128 v[154:157], v0 offset:2048
	ds_read_b128 v[158:161], v0 offset:3072
	s_add_i32 s62, s62, 0xc0000
	s_mov_b32 m0, s37
	ds_read_b128 v[162:165], v173 offset:32768
	ds_read_b128 v[174:177], v173 offset:33792
	ds_read_b128 v[178:181], v173 offset:34816
	ds_read_b128 v[182:185], v173 offset:35840
	ds_read_b128 v[186:189], v173 offset:36864
	ds_read_b128 v[190:193], v173 offset:37888
	ds_read_b128 v[194:197], v173 offset:38912
	ds_read_b128 v[200:203], v173 offset:39936
	buffer_load_dwordx4 v168, s[16:19], s62 offen lds
	s_mov_b32 m0, s38
	s_nop 0
	buffer_load_dwordx4 v170, s[16:19], s62 offen lds
	s_waitcnt vmcnt(8)
	s_waitcnt lgkmcnt(0)
	s_setprio 1
	s_barrier
	v_mfma_f32_16x16x32_bf16 v[126:129], v[130:133], v[162:165], v[126:129]
	v_mfma_f32_16x16x32_bf16 v[122:125], v[138:141], v[162:165], v[122:125]
	v_mfma_f32_16x16x32_bf16 v[110:113], v[130:133], v[178:181], v[110:113]
	v_mfma_f32_16x16x32_bf16 v[106:109], v[138:141], v[178:181], v[106:109]
	v_mfma_f32_16x16x32_bf16 v[94:97], v[130:133], v[186:189], v[94:97]
	v_mfma_f32_16x16x32_bf16 v[90:93], v[138:141], v[186:189], v[90:93]
	v_mfma_f32_16x16x32_bf16 v[78:81], v[130:133], v[194:197], v[78:81]
	v_mfma_f32_16x16x32_bf16 v[74:77], v[138:141], v[194:197], v[74:77]
	v_mfma_f32_16x16x32_bf16 v[126:129], v[134:137], v[174:177], v[126:129]
	v_mfma_f32_16x16x32_bf16 v[122:125], v[142:145], v[174:177], v[122:125]
	v_mfma_f32_16x16x32_bf16 v[110:113], v[134:137], v[182:185], v[110:113]
	v_mfma_f32_16x16x32_bf16 v[106:109], v[142:145], v[182:185], v[106:109]
	v_mfma_f32_16x16x32_bf16 v[94:97], v[134:137], v[190:193], v[94:97]
	v_mfma_f32_16x16x32_bf16 v[90:93], v[142:145], v[190:193], v[90:93]
	v_mfma_f32_16x16x32_bf16 v[78:81], v[134:137], v[200:203], v[78:81]
	v_mfma_f32_16x16x32_bf16 v[74:77], v[142:145], v[200:203], v[74:77]
	v_mfma_f32_16x16x32_bf16 v[118:121], v[146:149], v[162:165], v[118:121]
	v_mfma_f32_16x16x32_bf16 v[114:117], v[154:157], v[162:165], v[114:117]
	v_mfma_f32_16x16x32_bf16 v[102:105], v[146:149], v[178:181], v[102:105]
	v_mfma_f32_16x16x32_bf16 v[98:101], v[154:157], v[178:181], v[98:101]
	v_mfma_f32_16x16x32_bf16 v[86:89], v[146:149], v[186:189], v[86:89]
	v_mfma_f32_16x16x32_bf16 v[82:85], v[154:157], v[186:189], v[82:85]
	v_mfma_f32_16x16x32_bf16 v[70:73], v[146:149], v[194:197], v[70:73]
	v_mfma_f32_16x16x32_bf16 v[66:69], v[154:157], v[194:197], v[66:69]
	v_mfma_f32_16x16x32_bf16 v[118:121], v[150:153], v[174:177], v[118:121]
	v_mfma_f32_16x16x32_bf16 v[114:117], v[158:161], v[174:177], v[114:117]
	v_mfma_f32_16x16x32_bf16 v[102:105], v[150:153], v[182:185], v[102:105]
	v_mfma_f32_16x16x32_bf16 v[98:101], v[158:161], v[182:185], v[98:101]
	v_mfma_f32_16x16x32_bf16 v[86:89], v[150:153], v[190:193], v[86:89]
	v_mfma_f32_16x16x32_bf16 v[82:85], v[158:161], v[190:193], v[82:85]
	v_mfma_f32_16x16x32_bf16 v[70:73], v[150:153], v[200:203], v[70:73]
	v_mfma_f32_16x16x32_bf16 v[66:69], v[158:161], v[200:203], v[66:69]
	s_barrier
	s_setprio 0
	s_mov_b32 m0, s39
	s_or_b32 s62, s60, 0x80
	ds_read_b128 v[162:165], v173 offset:49152
	ds_read_b128 v[174:177], v173 offset:50176
	ds_read_b128 v[178:181], v173 offset:51200
	ds_read_b128 v[182:185], v173 offset:52224
	ds_read_b128 v[186:189], v173 offset:53248
	ds_read_b128 v[190:193], v173 offset:54272
	ds_read_b128 v[194:197], v173 offset:55296
	ds_read_b128 v[200:203], v173 offset:56320
	buffer_load_dwordx4 v169, s[12:15], s62 offen lds
	s_mov_b32 m0, s40
	s_add_i32 s60, s60, 0xb0080
	buffer_load_dwordx4 v171, s[12:15], s62 offen lds
	s_mov_b32 m0, s43
	s_nop 0
	buffer_load_dwordx4 v169, s[12:15], s60 offen lds
	s_mov_b32 m0, s42
	s_nop 0
	buffer_load_dwordx4 v171, s[12:15], s60 offen lds
	s_mov_b32 m0, s41
	s_nop 0
	buffer_load_dwordx4 v168, s[16:19], s61 offen lds
	s_mov_b32 m0, s33
	s_nop 0
	buffer_load_dwordx4 v170, s[16:19], s61 offen lds
	s_waitcnt vmcnt(8)
	s_waitcnt lgkmcnt(0)
	s_setprio 1
	s_barrier
	v_mfma_f32_16x16x32_bf16 v[62:65], v[130:133], v[162:165], v[62:65]
	v_mfma_f32_16x16x32_bf16 v[58:61], v[138:141], v[162:165], v[58:61]
	v_mfma_f32_16x16x32_bf16 v[46:49], v[130:133], v[178:181], v[46:49]
	v_mfma_f32_16x16x32_bf16 v[42:45], v[138:141], v[178:181], v[42:45]
	v_mfma_f32_16x16x32_bf16 v[30:33], v[130:133], v[186:189], v[30:33]
	v_mfma_f32_16x16x32_bf16 v[26:29], v[138:141], v[186:189], v[26:29]
	v_mfma_f32_16x16x32_bf16 v[14:17], v[130:133], v[194:197], v[14:17]
	v_mfma_f32_16x16x32_bf16 v[10:13], v[138:141], v[194:197], v[10:13]
	v_mfma_f32_16x16x32_bf16 v[62:65], v[134:137], v[174:177], v[62:65]
	v_mfma_f32_16x16x32_bf16 v[58:61], v[142:145], v[174:177], v[58:61]
	v_mfma_f32_16x16x32_bf16 v[46:49], v[134:137], v[182:185], v[46:49]
	v_mfma_f32_16x16x32_bf16 v[42:45], v[142:145], v[182:185], v[42:45]
	v_mfma_f32_16x16x32_bf16 v[30:33], v[134:137], v[190:193], v[30:33]
	v_mfma_f32_16x16x32_bf16 v[26:29], v[142:145], v[190:193], v[26:29]
	v_mfma_f32_16x16x32_bf16 v[14:17], v[134:137], v[200:203], v[14:17]
	v_mfma_f32_16x16x32_bf16 v[10:13], v[142:145], v[200:203], v[10:13]
	v_mfma_f32_16x16x32_bf16 v[54:57], v[146:149], v[162:165], v[54:57]
	v_mfma_f32_16x16x32_bf16 v[50:53], v[154:157], v[162:165], v[50:53]
	v_mfma_f32_16x16x32_bf16 v[38:41], v[146:149], v[178:181], v[38:41]
	v_mfma_f32_16x16x32_bf16 v[34:37], v[154:157], v[178:181], v[34:37]
	v_mfma_f32_16x16x32_bf16 v[22:25], v[146:149], v[186:189], v[22:25]
	v_mfma_f32_16x16x32_bf16 v[18:21], v[154:157], v[186:189], v[18:21]
	v_mfma_f32_16x16x32_bf16 v[6:9], v[146:149], v[194:197], v[6:9]
	v_mfma_f32_16x16x32_bf16 v[2:5], v[154:157], v[194:197], v[2:5]
	v_mfma_f32_16x16x32_bf16 v[54:57], v[150:153], v[174:177], v[54:57]
	v_mfma_f32_16x16x32_bf16 v[50:53], v[158:161], v[174:177], v[50:53]
	v_mfma_f32_16x16x32_bf16 v[38:41], v[150:153], v[182:185], v[38:41]
	v_mfma_f32_16x16x32_bf16 v[34:37], v[158:161], v[182:185], v[34:37]
	v_mfma_f32_16x16x32_bf16 v[22:25], v[150:153], v[190:193], v[22:25]
	v_mfma_f32_16x16x32_bf16 v[18:21], v[158:161], v[190:193], v[18:21]
	v_mfma_f32_16x16x32_bf16 v[6:9], v[150:153], v[200:203], v[6:9]
	v_mfma_f32_16x16x32_bf16 v[2:5], v[158:161], v[200:203], v[2:5]
	s_barrier
	s_setprio 0
	s_add_i32 s59, s59, 2
	s_addk_i32 s2, 0x100
	s_addk_i32 s3, 0x100
	s_cmp_gt_u32 s59, 41
	s_cbranch_scc0 .LBB0_1614
	v_readlane_b32 s2, v251, 45
	v_readlane_b32 s3, v251, 46
	s_and_b64 vcc, exec, s[2:3]
	s_cbranch_vccz .LBB0_1617
	s_barrier
